# v11 + hoisted rsq loads in SwiGLU/IN epilogues (one wait per tile) + deeper K-fragment read pipelining in QK (counted lgkmcnt)
# baseline (speedup 1.0000x reference)
; __device__ __forceinline__ unsigned cvt_pk_bf16(float lo, float hi) { unsigned r; asm volatile("v_cvt_pk_bf16_f32 %0, %1, %2" : "=v"(r) : "v"(lo), "v"(hi)); return r; }
; __device__ __forceinline__ float rs_of(const rsq_t* rsq, int row) { return __builtin_amdgcn_rsqf((float)rsq[row] * (1.0f / (1048576.0f * 2048.0f)) + 1e-6f); }
; __device__ __forceinline__ float silu_mul(float g, float u) { const float e = __builtin_amdgcn_exp2f(-1.4426950408889634f * g); return g * __builtin_amdgcn_rcpf(1.0f + e) * u; }
;     __device__ __forceinline__ void operator()(const f32x4 (&acc)[2][2][4][2], const Unit& u, int wr, int wc, int fr, int fq) const {
;         const int row0 = u.pm * BM + wr * 64 + fr; const int col0 = u.pn * HALF + wc * 32 + 8 * fq;
; #pragma unroll
;         for (int ai = 0; ai < 2; ++ai)
; #pragma unroll
;             for (int m = 0; m < 4; ++m) { const int row = row0 + ai * HALF + m * 16; bf16_t* rowp = O + (size_t)row * ldc + col0;
;                 const float rs = rs_of(rsq, row);
;                 const f32x4 g0 = acc[ai][0][m][0] * rs, g1 = acc[ai][0][m][1] * rs, u0 = acc[ai][1][m][0] * rs, u1 = acc[ai][1][m][1] * rs;
;                 u32x4 w;
;                 w.x = cvt_pk_bf16(silu_mul(g0[0], u0[0]), silu_mul(g0[1], u0[1])); w.y = cvt_pk_bf16(silu_mul(g0[2], u0[2]), silu_mul(g0[3], u0[3]));
;                 w.z = cvt_pk_bf16(silu_mul(g1[0], u1[0]), silu_mul(g1[1], u1[1])); w.w = cvt_pk_bf16(silu_mul(g1[2], u1[2]), silu_mul(g1[3], u1[3]));
;                 *(u32x4*)rowp = w; }
.LBB0_475:
	v_lshl_add_u32 v144, s1, 7, v152
	v_lshl_add_u32 v140, s2, 8, v150
	v_ashrrev_i32_e32 v145, 31, v144
	v_mov_b64_e32 v[142:143], s[8:9]
	s_movk_i32 s1, 0x2c00
	v_ashrrev_i32_e32 v141, 31, v140
	v_mad_i64_i32 v[146:147], s[2:3], v140, s1, v[142:143]
	v_lshlrev_b64 v[144:145], 1, v[144:145]
	v_lshl_add_u64 v[148:149], v[146:147], 0, v[144:145]
	v_lshl_add_u64 v[146:147], v[140:141], 3, s[10:11]
	global_load_dwordx2 v[154:155], v[146:147], off
	global_load_dwordx2 v[158:159], v[146:147], off offset:128
	global_load_dwordx2 v[160:161], v[146:147], off offset:256
	global_load_dwordx2 v[162:163], v[146:147], off offset:384
	global_load_dwordx2 v[164:165], v[146:147], off offset:1024
	global_load_dwordx2 v[166:167], v[146:147], off offset:1152
	global_load_dwordx2 v[168:169], v[146:147], off offset:1280
	global_load_dwordx2 v[170:171], v[146:147], off offset:1408
	s_andn2_b64 vcc, exec, s[4:5]
	s_waitcnt vmcnt(0)
	v_ffbh_u32_e32 v141, v155
	v_min_u32_e32 v141, 32, v141
	v_lshlrev_b64 v[154:155], v141, v[154:155]
	v_min_u32_e32 v154, 1, v154
	v_or_b32_e32 v154, v155, v154
	v_cvt_f32_u32_e32 v154, v154
	v_sub_u32_e32 v141, 32, v141
	v_ldexp_f32 v141, v154, v141
	v_fmamk_f32 v141, v141, 0x30000000, v198
	v_rsq_f32_e32 v154, v141
	s_nop 0
	v_pk_mul_f32 v[126:127], v[126:127], v[154:155] op_sel_hi:[1,0]
	v_pk_mul_f32 v[156:157], v[118:119], v[154:155] op_sel_hi:[1,0]
	v_pk_mul_f32 v[118:119], v[116:117], v[154:155] op_sel_hi:[1,0]
	v_pk_mul_f32 v[116:117], v[114:115], v[154:155] op_sel_hi:[1,0]
	v_mul_f32_e32 v114, 0xbfb8aa3b, v126
	v_mul_f32_e32 v115, 0xbfb8aa3b, v127
	v_exp_f32_e32 v114, v114
	v_exp_f32_e32 v115, v115
	v_pk_mul_f32 v[128:129], v[128:129], v[154:155] op_sel_hi:[1,0]
	v_pk_mul_f32 v[120:121], v[120:121], v[154:155] op_sel_hi:[1,0]
	v_add_f32_e32 v114, 1.0, v114
	v_add_f32_e32 v115, 1.0, v115
	v_rcp_f32_e32 v114, v114
	v_rcp_f32_e32 v115, v115
	v_pk_mul_f32 v[122:123], v[122:123], v[154:155] op_sel_hi:[1,0]
	v_pk_mul_f32 v[124:125], v[124:125], v[154:155] op_sel_hi:[1,0]
	v_mul_f32_e32 v114, v126, v114
	v_mul_f32_e32 v115, v127, v115
	v_mul_f32_e32 v114, v156, v114
	v_mul_f32_e32 v115, v157, v115
	v_cvt_pk_bf16_f32 v114, v114, v115
	v_mul_f32_e32 v115, 0xbfb8aa3b, v128
	v_exp_f32_e32 v115, v115
	s_nop 0
	v_add_f32_e32 v115, 1.0, v115
	v_rcp_f32_e32 v115, v115
	s_nop 0
	v_mul_f32_e32 v115, v128, v115
	v_mul_f32_e32 v115, v120, v115
	v_mul_f32_e32 v120, 0xbfb8aa3b, v129
	v_exp_f32_e32 v120, v120
	s_nop 0
	v_add_f32_e32 v120, 1.0, v120
	v_rcp_f32_e32 v120, v120
	s_nop 0
	v_mul_f32_e32 v120, v129, v120
	v_mul_f32_e32 v120, v121, v120
	v_cvt_pk_bf16_f32 v115, v115, v120
	v_mul_f32_e32 v120, 0xbfb8aa3b, v122
	v_exp_f32_e32 v120, v120
	s_nop 0
	v_add_f32_e32 v120, 1.0, v120
	v_rcp_f32_e32 v120, v120
	s_nop 0
	v_mul_f32_e32 v120, v122, v120
	v_mul_f32_e32 v116, v116, v120
	v_mul_f32_e32 v120, 0xbfb8aa3b, v123
	v_exp_f32_e32 v120, v120
	s_nop 0
	v_add_f32_e32 v120, 1.0, v120
	v_rcp_f32_e32 v120, v120
	s_nop 0
	v_mul_f32_e32 v120, v123, v120
	v_mul_f32_e32 v117, v117, v120
	v_cvt_pk_bf16_f32 v116, v116, v117
	v_mul_f32_e32 v117, 0xbfb8aa3b, v124
	v_exp_f32_e32 v117, v117
	s_nop 0
	v_add_f32_e32 v117, 1.0, v117
	v_rcp_f32_e32 v117, v117
	s_nop 0
	v_mul_f32_e32 v117, v124, v117
	v_mul_f32_e32 v117, v118, v117
	v_mul_f32_e32 v118, 0xbfb8aa3b, v125
	v_exp_f32_e32 v118, v118
	s_nop 0
	v_add_f32_e32 v118, 1.0, v118
	v_rcp_f32_e32 v118, v118
	s_nop 0
	v_mul_f32_e32 v118, v125, v118
	v_mul_f32_e32 v118, v119, v118
	v_cvt_pk_bf16_f32 v117, v117, v118
	global_store_dwordx4 v[148:149], v[114:117], off
	s_nop 1
	v_mov_b32_e32 v116, v158
	v_mov_b32_e32 v117, v159
	v_ffbh_u32_e32 v118, v117
	v_min_u32_e32 v118, 32, v118
	v_lshlrev_b64 v[116:117], v118, v[116:117]
	v_min_u32_e32 v116, 1, v116
	v_or_b32_e32 v116, v117, v116
	v_cvt_f32_u32_e32 v116, v116
	v_sub_u32_e32 v117, 32, v118
	v_or_b32_e32 v114, 16, v140
	v_mad_i64_i32 v[114:115], s[2:3], v114, s1, v[142:143]
	v_ldexp_f32 v116, v116, v117
	v_fmamk_f32 v116, v116, 0x30000000, v198
	v_rsq_f32_e32 v116, v116
	v_lshl_add_u64 v[114:115], v[114:115], 0, v[144:145]
	v_pk_mul_f32 v[110:111], v[110:111], v[116:117] op_sel_hi:[1,0]
	v_pk_mul_f32 v[118:119], v[102:103], v[116:117] op_sel_hi:[1,0]
	v_pk_mul_f32 v[102:103], v[100:101], v[116:117] op_sel_hi:[1,0]
	v_pk_mul_f32 v[100:101], v[98:99], v[116:117] op_sel_hi:[1,0]
	v_mul_f32_e32 v98, 0xbfb8aa3b, v110
	v_mul_f32_e32 v99, 0xbfb8aa3b, v111
	v_exp_f32_e32 v98, v98
	v_exp_f32_e32 v99, v99
	v_pk_mul_f32 v[112:113], v[112:113], v[116:117] op_sel_hi:[1,0]
	v_pk_mul_f32 v[104:105], v[104:105], v[116:117] op_sel_hi:[1,0]
	v_add_f32_e32 v98, 1.0, v98
	v_add_f32_e32 v99, 1.0, v99
	v_rcp_f32_e32 v98, v98
	v_rcp_f32_e32 v99, v99
	v_pk_mul_f32 v[106:107], v[106:107], v[116:117] op_sel_hi:[1,0]
	v_pk_mul_f32 v[108:109], v[108:109], v[116:117] op_sel_hi:[1,0]
	v_mul_f32_e32 v98, v110, v98
	v_mul_f32_e32 v99, v111, v99
	v_mul_f32_e32 v98, v118, v98
	v_mul_f32_e32 v99, v119, v99
	v_cvt_pk_bf16_f32 v98, v98, v99
	v_mul_f32_e32 v99, 0xbfb8aa3b, v112
	v_exp_f32_e32 v99, v99
	s_nop 0
	v_add_f32_e32 v99, 1.0, v99
	v_rcp_f32_e32 v99, v99
	s_nop 0
	v_mul_f32_e32 v99, v112, v99
	v_mul_f32_e32 v99, v104, v99
	v_mul_f32_e32 v104, 0xbfb8aa3b, v113
	v_exp_f32_e32 v104, v104
	s_nop 0
	v_add_f32_e32 v104, 1.0, v104
	v_rcp_f32_e32 v104, v104
	s_nop 0
	v_mul_f32_e32 v104, v113, v104
	v_mul_f32_e32 v104, v105, v104
	v_cvt_pk_bf16_f32 v99, v99, v104
	v_mul_f32_e32 v104, 0xbfb8aa3b, v106
	v_exp_f32_e32 v104, v104
	s_nop 0
	v_add_f32_e32 v104, 1.0, v104
	v_rcp_f32_e32 v104, v104
	s_nop 0
	v_mul_f32_e32 v104, v106, v104
	v_mul_f32_e32 v100, v100, v104
	v_mul_f32_e32 v104, 0xbfb8aa3b, v107
; __device__ __forceinline__ unsigned cvt_pk_bf16(float lo, float hi) { unsigned r; asm volatile("v_cvt_pk_bf16_f32 %0, %1, %2" : "=v"(r) : "v"(lo), "v"(hi)); return r; }
; __device__ __forceinline__ float silu_mul(float g, float u) { const float e = __builtin_amdgcn_exp2f(-1.4426950408889634f * g); return g * __builtin_amdgcn_rcpf(1.0f + e) * u; }
; __device__ __forceinline__ float rs_of(const rsq_t* rsq, int row) { return __builtin_amdgcn_rsqf((float)rsq[row] * (1.0f / (1048576.0f * 2048.0f)) + 1e-6f); }
;     __device__ __forceinline__ void operator()(const f32x4 (&acc)[2][2][4][2], const Unit& u, int wr, int wc, int fr, int fq) const {
;     ...
;             for (int m = 0; m < 4; ++m) { const int row = row0 + ai * HALF + m * 16; bf16_t* rowp = O + (size_t)row * ldc + col0;
;                 const float rs = rs_of(rsq, row);
;                 const f32x4 g0 = acc[ai][0][m][0] * rs, g1 = acc[ai][0][m][1] * rs, u0 = acc[ai][1][m][0] * rs, u1 = acc[ai][1][m][1] * rs;
;                 u32x4 w;
;                 w.x = cvt_pk_bf16(silu_mul(g0[0], u0[0]), silu_mul(g0[1], u0[1])); w.y = cvt_pk_bf16(silu_mul(g0[2], u0[2]), silu_mul(g0[3], u0[3]));
;                 w.z = cvt_pk_bf16(silu_mul(g1[0], u1[0]), silu_mul(g1[1], u1[1])); w.w = cvt_pk_bf16(silu_mul(g1[2], u1[2]), silu_mul(g1[3], u1[3]));
;                 *(u32x4*)rowp = w; }
	v_exp_f32_e32 v104, v104
	s_nop 0
	v_add_f32_e32 v104, 1.0, v104
	v_rcp_f32_e32 v104, v104
	s_nop 0
	v_mul_f32_e32 v104, v107, v104
	v_mul_f32_e32 v101, v101, v104
	v_cvt_pk_bf16_f32 v100, v100, v101
	v_mul_f32_e32 v101, 0xbfb8aa3b, v108
	v_exp_f32_e32 v101, v101
	s_nop 0
	v_add_f32_e32 v101, 1.0, v101
	v_rcp_f32_e32 v101, v101
	s_nop 0
	v_mul_f32_e32 v101, v108, v101
	v_mul_f32_e32 v101, v102, v101
	v_mul_f32_e32 v102, 0xbfb8aa3b, v109
	v_exp_f32_e32 v102, v102
	s_nop 0
	v_add_f32_e32 v102, 1.0, v102
	v_rcp_f32_e32 v102, v102
	s_nop 0
	v_mul_f32_e32 v102, v109, v102
	v_mul_f32_e32 v102, v103, v102
	v_cvt_pk_bf16_f32 v101, v101, v102
	global_store_dwordx4 v[114:115], v[98:101], off
	s_nop 1
	v_mov_b32_e32 v100, v160
	v_mov_b32_e32 v101, v161
	v_ffbh_u32_e32 v102, v101
	v_min_u32_e32 v102, 32, v102
	v_lshlrev_b64 v[100:101], v102, v[100:101]
	v_min_u32_e32 v100, 1, v100
	v_or_b32_e32 v100, v101, v100
	v_cvt_f32_u32_e32 v100, v100
	v_sub_u32_e32 v101, 32, v102
	v_or_b32_e32 v98, 32, v140
	v_mad_i64_i32 v[98:99], s[2:3], v98, s1, v[142:143]
	v_ldexp_f32 v100, v100, v101
	v_fmamk_f32 v100, v100, 0x30000000, v198
	v_rsq_f32_e32 v100, v100
	v_lshl_add_u64 v[98:99], v[98:99], 0, v[144:145]
	v_pk_mul_f32 v[94:95], v[94:95], v[100:101] op_sel_hi:[1,0]
	v_pk_mul_f32 v[102:103], v[86:87], v[100:101] op_sel_hi:[1,0]
	v_pk_mul_f32 v[86:87], v[84:85], v[100:101] op_sel_hi:[1,0]
	v_pk_mul_f32 v[84:85], v[82:83], v[100:101] op_sel_hi:[1,0]
	v_mul_f32_e32 v82, 0xbfb8aa3b, v94
	v_mul_f32_e32 v83, 0xbfb8aa3b, v95
	v_exp_f32_e32 v82, v82
	v_exp_f32_e32 v83, v83
	v_pk_mul_f32 v[96:97], v[96:97], v[100:101] op_sel_hi:[1,0]
	v_pk_mul_f32 v[88:89], v[88:89], v[100:101] op_sel_hi:[1,0]
	v_add_f32_e32 v82, 1.0, v82
	v_add_f32_e32 v83, 1.0, v83
	v_rcp_f32_e32 v82, v82
	v_rcp_f32_e32 v83, v83
	v_pk_mul_f32 v[90:91], v[90:91], v[100:101] op_sel_hi:[1,0]
	v_pk_mul_f32 v[92:93], v[92:93], v[100:101] op_sel_hi:[1,0]
	v_mul_f32_e32 v82, v94, v82
	v_mul_f32_e32 v83, v95, v83
	v_mul_f32_e32 v82, v102, v82
	v_mul_f32_e32 v83, v103, v83
	v_cvt_pk_bf16_f32 v82, v82, v83
	v_mul_f32_e32 v83, 0xbfb8aa3b, v96
	v_exp_f32_e32 v83, v83
	s_nop 0
	v_add_f32_e32 v83, 1.0, v83
	v_rcp_f32_e32 v83, v83
	s_nop 0
	v_mul_f32_e32 v83, v96, v83
	v_mul_f32_e32 v83, v88, v83
	v_mul_f32_e32 v88, 0xbfb8aa3b, v97
	v_exp_f32_e32 v88, v88
	s_nop 0
	v_add_f32_e32 v88, 1.0, v88
	v_rcp_f32_e32 v88, v88
	s_nop 0
	v_mul_f32_e32 v88, v97, v88
	v_mul_f32_e32 v88, v89, v88
	v_cvt_pk_bf16_f32 v83, v83, v88
	v_mul_f32_e32 v88, 0xbfb8aa3b, v90
	v_exp_f32_e32 v88, v88
	s_nop 0
	v_add_f32_e32 v88, 1.0, v88
	v_rcp_f32_e32 v88, v88
	s_nop 0
	v_mul_f32_e32 v88, v90, v88
	v_mul_f32_e32 v84, v84, v88
	v_mul_f32_e32 v88, 0xbfb8aa3b, v91
	v_exp_f32_e32 v88, v88
	s_nop 0
	v_add_f32_e32 v88, 1.0, v88
	v_rcp_f32_e32 v88, v88
	s_nop 0
	v_mul_f32_e32 v88, v91, v88
	v_mul_f32_e32 v85, v85, v88
	v_cvt_pk_bf16_f32 v84, v84, v85
	v_mul_f32_e32 v85, 0xbfb8aa3b, v92
	v_exp_f32_e32 v85, v85
	s_nop 0
	v_add_f32_e32 v85, 1.0, v85
	v_rcp_f32_e32 v85, v85
	s_nop 0
	v_mul_f32_e32 v85, v92, v85
	v_mul_f32_e32 v85, v86, v85
	v_mul_f32_e32 v86, 0xbfb8aa3b, v93
	v_exp_f32_e32 v86, v86
	s_nop 0
	v_add_f32_e32 v86, 1.0, v86
	v_rcp_f32_e32 v86, v86
	s_nop 0
	v_mul_f32_e32 v86, v93, v86
	v_mul_f32_e32 v86, v87, v86
	v_cvt_pk_bf16_f32 v85, v85, v86
	global_store_dwordx4 v[98:99], v[82:85], off
	s_nop 1
	v_mov_b32_e32 v84, v162
	v_mov_b32_e32 v85, v163
	v_ffbh_u32_e32 v86, v85
	v_min_u32_e32 v86, 32, v86
	v_lshlrev_b64 v[84:85], v86, v[84:85]
	v_min_u32_e32 v84, 1, v84
	v_or_b32_e32 v84, v85, v84
	v_cvt_f32_u32_e32 v84, v84
	v_sub_u32_e32 v85, 32, v86
	v_or_b32_e32 v82, 48, v140
	v_mad_i64_i32 v[82:83], s[2:3], v82, s1, v[142:143]
	v_ldexp_f32 v84, v84, v85
	v_fmamk_f32 v84, v84, 0x30000000, v198
	v_rsq_f32_e32 v84, v84
	v_lshl_add_u64 v[82:83], v[82:83], 0, v[144:145]
	v_pk_mul_f32 v[78:79], v[78:79], v[84:85] op_sel_hi:[1,0]
	v_pk_mul_f32 v[86:87], v[70:71], v[84:85] op_sel_hi:[1,0]
	v_pk_mul_f32 v[70:71], v[68:69], v[84:85] op_sel_hi:[1,0]
	v_pk_mul_f32 v[68:69], v[66:67], v[84:85] op_sel_hi:[1,0]
	v_mul_f32_e32 v66, 0xbfb8aa3b, v78
	v_mul_f32_e32 v67, 0xbfb8aa3b, v79
	v_exp_f32_e32 v66, v66
	v_exp_f32_e32 v67, v67
	v_pk_mul_f32 v[80:81], v[80:81], v[84:85] op_sel_hi:[1,0]
	v_pk_mul_f32 v[72:73], v[72:73], v[84:85] op_sel_hi:[1,0]
	v_add_f32_e32 v66, 1.0, v66
	v_add_f32_e32 v67, 1.0, v67
	v_rcp_f32_e32 v66, v66
	v_rcp_f32_e32 v67, v67
	v_pk_mul_f32 v[74:75], v[74:75], v[84:85] op_sel_hi:[1,0]
	v_pk_mul_f32 v[76:77], v[76:77], v[84:85] op_sel_hi:[1,0]
	v_mul_f32_e32 v66, v78, v66
	v_mul_f32_e32 v67, v79, v67
	v_mul_f32_e32 v66, v86, v66
	v_mul_f32_e32 v67, v87, v67
	v_cvt_pk_bf16_f32 v66, v66, v67
	v_mul_f32_e32 v67, 0xbfb8aa3b, v80
	v_exp_f32_e32 v67, v67
	s_nop 0
	v_add_f32_e32 v67, 1.0, v67
	v_rcp_f32_e32 v67, v67
	s_nop 0
	v_mul_f32_e32 v67, v80, v67
	v_mul_f32_e32 v67, v72, v67
	v_mul_f32_e32 v72, 0xbfb8aa3b, v81
	v_exp_f32_e32 v72, v72
	s_nop 0
	v_add_f32_e32 v72, 1.0, v72
	v_rcp_f32_e32 v72, v72
	s_nop 0
	v_mul_f32_e32 v72, v81, v72
	v_mul_f32_e32 v72, v73, v72
	v_cvt_pk_bf16_f32 v67, v67, v72
	v_mul_f32_e32 v72, 0xbfb8aa3b, v74
	v_exp_f32_e32 v72, v72
	s_nop 0
	v_add_f32_e32 v72, 1.0, v72
	v_rcp_f32_e32 v72, v72
	s_nop 0
	v_mul_f32_e32 v72, v74, v72
	v_mul_f32_e32 v68, v68, v72
	v_mul_f32_e32 v72, 0xbfb8aa3b, v75
	v_exp_f32_e32 v72, v72
	s_nop 0
	v_add_f32_e32 v72, 1.0, v72
	v_rcp_f32_e32 v72, v72
	s_nop 0
	v_mul_f32_e32 v72, v75, v72
	v_mul_f32_e32 v69, v69, v72
	v_cvt_pk_bf16_f32 v68, v68, v69
	v_mul_f32_e32 v69, 0xbfb8aa3b, v76
	v_exp_f32_e32 v69, v69
	s_nop 0
	v_add_f32_e32 v69, 1.0, v69
	v_rcp_f32_e32 v69, v69
	s_nop 0
; __device__ __forceinline__ unsigned cvt_pk_bf16(float lo, float hi) { unsigned r; asm volatile("v_cvt_pk_bf16_f32 %0, %1, %2" : "=v"(r) : "v"(lo), "v"(hi)); return r; }
; __device__ __forceinline__ float silu_mul(float g, float u) { const float e = __builtin_amdgcn_exp2f(-1.4426950408889634f * g); return g * __builtin_amdgcn_rcpf(1.0f + e) * u; }
; __device__ __forceinline__ float rs_of(const rsq_t* rsq, int row) { return __builtin_amdgcn_rsqf((float)rsq[row] * (1.0f / (1048576.0f * 2048.0f)) + 1e-6f); }
;     __device__ __forceinline__ void operator()(const f32x4 (&acc)[2][2][4][2], const Unit& u, int wr, int wc, int fr, int fq) const {
;     ...
;             for (int m = 0; m < 4; ++m) { const int row = row0 + ai * HALF + m * 16; bf16_t* rowp = O + (size_t)row * ldc + col0;
;                 const float rs = rs_of(rsq, row);
;                 const f32x4 g0 = acc[ai][0][m][0] * rs, g1 = acc[ai][0][m][1] * rs, u0 = acc[ai][1][m][0] * rs, u1 = acc[ai][1][m][1] * rs;
;                 u32x4 w;
;                 w.x = cvt_pk_bf16(silu_mul(g0[0], u0[0]), silu_mul(g0[1], u0[1])); w.y = cvt_pk_bf16(silu_mul(g0[2], u0[2]), silu_mul(g0[3], u0[3]));
;                 w.z = cvt_pk_bf16(silu_mul(g1[0], u1[0]), silu_mul(g1[1], u1[1])); w.w = cvt_pk_bf16(silu_mul(g1[2], u1[2]), silu_mul(g1[3], u1[3]));
;                 *(u32x4*)rowp = w; }
	v_mul_f32_e32 v69, v76, v69
	v_mul_f32_e32 v69, v70, v69
	v_mul_f32_e32 v70, 0xbfb8aa3b, v77
	v_exp_f32_e32 v70, v70
	s_nop 0
	v_add_f32_e32 v70, 1.0, v70
	v_rcp_f32_e32 v70, v70
	s_nop 0
	v_mul_f32_e32 v70, v77, v70
	v_mul_f32_e32 v70, v71, v70
	v_cvt_pk_bf16_f32 v69, v69, v70
	global_store_dwordx4 v[82:83], v[66:69], off
	s_nop 1
	v_mov_b32_e32 v68, v164
	v_mov_b32_e32 v69, v165
	v_ffbh_u32_e32 v70, v69
	v_min_u32_e32 v70, 32, v70
	v_lshlrev_b64 v[68:69], v70, v[68:69]
	v_min_u32_e32 v68, 1, v68
	v_or_b32_e32 v68, v69, v68
	v_cvt_f32_u32_e32 v68, v68
	v_sub_u32_e32 v69, 32, v70
	v_add_u32_e32 v66, 0x80, v140
	v_mad_i64_i32 v[66:67], s[2:3], v66, s1, v[142:143]
	v_ldexp_f32 v68, v68, v69
	v_fmamk_f32 v68, v68, 0x30000000, v198
	v_rsq_f32_e32 v68, v68
	v_lshl_add_u64 v[66:67], v[66:67], 0, v[144:145]
	v_pk_mul_f32 v[62:63], v[62:63], v[68:69] op_sel_hi:[1,0]
	v_pk_mul_f32 v[70:71], v[54:55], v[68:69] op_sel_hi:[1,0]
	v_pk_mul_f32 v[54:55], v[52:53], v[68:69] op_sel_hi:[1,0]
	v_pk_mul_f32 v[52:53], v[50:51], v[68:69] op_sel_hi:[1,0]
	v_mul_f32_e32 v50, 0xbfb8aa3b, v62
	v_mul_f32_e32 v51, 0xbfb8aa3b, v63
	v_exp_f32_e32 v50, v50
	v_exp_f32_e32 v51, v51
	v_pk_mul_f32 v[64:65], v[64:65], v[68:69] op_sel_hi:[1,0]
	v_pk_mul_f32 v[56:57], v[56:57], v[68:69] op_sel_hi:[1,0]
	v_add_f32_e32 v50, 1.0, v50
	v_add_f32_e32 v51, 1.0, v51
	v_rcp_f32_e32 v50, v50
	v_rcp_f32_e32 v51, v51
	v_pk_mul_f32 v[58:59], v[58:59], v[68:69] op_sel_hi:[1,0]
	v_pk_mul_f32 v[60:61], v[60:61], v[68:69] op_sel_hi:[1,0]
	v_mul_f32_e32 v50, v62, v50
	v_mul_f32_e32 v51, v63, v51
	v_mul_f32_e32 v50, v70, v50
	v_mul_f32_e32 v51, v71, v51
	v_cvt_pk_bf16_f32 v50, v50, v51
	v_mul_f32_e32 v51, 0xbfb8aa3b, v64
	v_exp_f32_e32 v51, v51
	s_nop 0
	v_add_f32_e32 v51, 1.0, v51
	v_rcp_f32_e32 v51, v51
	s_nop 0
	v_mul_f32_e32 v51, v64, v51
	v_mul_f32_e32 v51, v56, v51
	v_mul_f32_e32 v56, 0xbfb8aa3b, v65
	v_exp_f32_e32 v56, v56
	s_nop 0
	v_add_f32_e32 v56, 1.0, v56
	v_rcp_f32_e32 v56, v56
	s_nop 0
	v_mul_f32_e32 v56, v65, v56
	v_mul_f32_e32 v56, v57, v56
	v_cvt_pk_bf16_f32 v51, v51, v56
	v_mul_f32_e32 v56, 0xbfb8aa3b, v58
	v_exp_f32_e32 v56, v56
	s_nop 0
	v_add_f32_e32 v56, 1.0, v56
	v_rcp_f32_e32 v56, v56
	s_nop 0
	v_mul_f32_e32 v56, v58, v56
	v_mul_f32_e32 v52, v52, v56
	v_mul_f32_e32 v56, 0xbfb8aa3b, v59
	v_exp_f32_e32 v56, v56
	s_nop 0
	v_add_f32_e32 v56, 1.0, v56
	v_rcp_f32_e32 v56, v56
	s_nop 0
	v_mul_f32_e32 v56, v59, v56
	v_mul_f32_e32 v53, v53, v56
	v_cvt_pk_bf16_f32 v52, v52, v53
	v_mul_f32_e32 v53, 0xbfb8aa3b, v60
	v_exp_f32_e32 v53, v53
	s_nop 0
	v_add_f32_e32 v53, 1.0, v53
	v_rcp_f32_e32 v53, v53
	s_nop 0
	v_mul_f32_e32 v53, v60, v53
	v_mul_f32_e32 v53, v54, v53
	v_mul_f32_e32 v54, 0xbfb8aa3b, v61
	v_exp_f32_e32 v54, v54
	s_nop 0
	v_add_f32_e32 v54, 1.0, v54
	v_rcp_f32_e32 v54, v54
	s_nop 0
	v_mul_f32_e32 v54, v61, v54
	v_mul_f32_e32 v54, v55, v54
	v_cvt_pk_bf16_f32 v53, v53, v54
	global_store_dwordx4 v[66:67], v[50:53], off
	s_nop 1
	v_mov_b32_e32 v52, v166
	v_mov_b32_e32 v53, v167
	v_ffbh_u32_e32 v54, v53
	v_min_u32_e32 v54, 32, v54
	v_lshlrev_b64 v[52:53], v54, v[52:53]
	v_min_u32_e32 v52, 1, v52
	v_or_b32_e32 v52, v53, v52
	v_cvt_f32_u32_e32 v52, v52
	v_sub_u32_e32 v53, 32, v54
	v_add_u32_e32 v50, 0x90, v140
	v_mad_i64_i32 v[50:51], s[2:3], v50, s1, v[142:143]
	v_ldexp_f32 v52, v52, v53
	v_fmamk_f32 v52, v52, 0x30000000, v198
	v_rsq_f32_e32 v52, v52
	v_lshl_add_u64 v[50:51], v[50:51], 0, v[144:145]
	v_pk_mul_f32 v[46:47], v[46:47], v[52:53] op_sel_hi:[1,0]
	v_pk_mul_f32 v[54:55], v[38:39], v[52:53] op_sel_hi:[1,0]
	v_pk_mul_f32 v[38:39], v[36:37], v[52:53] op_sel_hi:[1,0]
	v_pk_mul_f32 v[36:37], v[34:35], v[52:53] op_sel_hi:[1,0]
	v_mul_f32_e32 v34, 0xbfb8aa3b, v46
	v_mul_f32_e32 v35, 0xbfb8aa3b, v47
	v_exp_f32_e32 v34, v34
	v_exp_f32_e32 v35, v35
	v_pk_mul_f32 v[48:49], v[48:49], v[52:53] op_sel_hi:[1,0]
	v_pk_mul_f32 v[40:41], v[40:41], v[52:53] op_sel_hi:[1,0]
	v_add_f32_e32 v34, 1.0, v34
	v_add_f32_e32 v35, 1.0, v35
	v_rcp_f32_e32 v34, v34
	v_rcp_f32_e32 v35, v35
	v_pk_mul_f32 v[42:43], v[42:43], v[52:53] op_sel_hi:[1,0]
	v_pk_mul_f32 v[44:45], v[44:45], v[52:53] op_sel_hi:[1,0]
	v_mul_f32_e32 v34, v46, v34
	v_mul_f32_e32 v35, v47, v35
	v_mul_f32_e32 v34, v54, v34
	v_mul_f32_e32 v35, v55, v35
	v_cvt_pk_bf16_f32 v34, v34, v35
	v_mul_f32_e32 v35, 0xbfb8aa3b, v48
	v_exp_f32_e32 v35, v35
	s_nop 0
	v_add_f32_e32 v35, 1.0, v35
	v_rcp_f32_e32 v35, v35
	s_nop 0
	v_mul_f32_e32 v35, v48, v35
	v_mul_f32_e32 v35, v40, v35
	v_mul_f32_e32 v40, 0xbfb8aa3b, v49
	v_exp_f32_e32 v40, v40
	s_nop 0
	v_add_f32_e32 v40, 1.0, v40
	v_rcp_f32_e32 v40, v40
	s_nop 0
	v_mul_f32_e32 v40, v49, v40
	v_mul_f32_e32 v40, v41, v40
	v_cvt_pk_bf16_f32 v35, v35, v40
	v_mul_f32_e32 v40, 0xbfb8aa3b, v42
	v_exp_f32_e32 v40, v40
	s_nop 0
	v_add_f32_e32 v40, 1.0, v40
	v_rcp_f32_e32 v40, v40
	s_nop 0
	v_mul_f32_e32 v40, v42, v40
	v_mul_f32_e32 v36, v36, v40
	v_mul_f32_e32 v40, 0xbfb8aa3b, v43
	v_exp_f32_e32 v40, v40
	s_nop 0
	v_add_f32_e32 v40, 1.0, v40
	v_rcp_f32_e32 v40, v40
	s_nop 0
	v_mul_f32_e32 v40, v43, v40
	v_mul_f32_e32 v37, v37, v40
	v_cvt_pk_bf16_f32 v36, v36, v37
	v_mul_f32_e32 v37, 0xbfb8aa3b, v44
	v_exp_f32_e32 v37, v37
	s_nop 0
	v_add_f32_e32 v37, 1.0, v37
	v_rcp_f32_e32 v37, v37
	s_nop 0
	v_mul_f32_e32 v37, v44, v37
	v_mul_f32_e32 v37, v38, v37
	v_mul_f32_e32 v38, 0xbfb8aa3b, v45
	v_exp_f32_e32 v38, v38
	s_nop 0
; __device__ __forceinline__ unsigned cvt_pk_bf16(float lo, float hi) { unsigned r; asm volatile("v_cvt_pk_bf16_f32 %0, %1, %2" : "=v"(r) : "v"(lo), "v"(hi)); return r; }
; __device__ __forceinline__ float silu_mul(float g, float u) { const float e = __builtin_amdgcn_exp2f(-1.4426950408889634f * g); return g * __builtin_amdgcn_rcpf(1.0f + e) * u; }
; __device__ __forceinline__ float rs_of(const rsq_t* rsq, int row) { return __builtin_amdgcn_rsqf((float)rsq[row] * (1.0f / (1048576.0f * 2048.0f)) + 1e-6f); }
;     __device__ __forceinline__ void operator()(const f32x4 (&acc)[2][2][4][2], const Unit& u, int wr, int wc, int fr, int fq) const {
;     ...
;             for (int m = 0; m < 4; ++m) { const int row = row0 + ai * HALF + m * 16; bf16_t* rowp = O + (size_t)row * ldc + col0;
;                 const float rs = rs_of(rsq, row);
;                 const f32x4 g0 = acc[ai][0][m][0] * rs, g1 = acc[ai][0][m][1] * rs, u0 = acc[ai][1][m][0] * rs, u1 = acc[ai][1][m][1] * rs;
;                 u32x4 w;
;                 w.x = cvt_pk_bf16(silu_mul(g0[0], u0[0]), silu_mul(g0[1], u0[1])); w.y = cvt_pk_bf16(silu_mul(g0[2], u0[2]), silu_mul(g0[3], u0[3]));
;                 w.z = cvt_pk_bf16(silu_mul(g1[0], u1[0]), silu_mul(g1[1], u1[1])); w.w = cvt_pk_bf16(silu_mul(g1[2], u1[2]), silu_mul(g1[3], u1[3]));
;                 *(u32x4*)rowp = w; }
	v_add_f32_e32 v38, 1.0, v38
	v_rcp_f32_e32 v38, v38
	s_nop 0
	v_mul_f32_e32 v38, v45, v38
	v_mul_f32_e32 v38, v39, v38
	v_cvt_pk_bf16_f32 v37, v37, v38
	global_store_dwordx4 v[50:51], v[34:37], off
	s_nop 1
	v_mov_b32_e32 v36, v168
	v_mov_b32_e32 v37, v169
	v_ffbh_u32_e32 v38, v37
	v_min_u32_e32 v38, 32, v38
	v_lshlrev_b64 v[36:37], v38, v[36:37]
	v_min_u32_e32 v36, 1, v36
	v_or_b32_e32 v36, v37, v36
	v_cvt_f32_u32_e32 v36, v36
	v_sub_u32_e32 v37, 32, v38
	v_add_u32_e32 v34, 0xa0, v140
	v_mad_i64_i32 v[34:35], s[2:3], v34, s1, v[142:143]
	v_ldexp_f32 v36, v36, v37
	v_fmamk_f32 v36, v36, 0x30000000, v198
	v_rsq_f32_e32 v36, v36
	v_lshl_add_u64 v[34:35], v[34:35], 0, v[144:145]
	v_pk_mul_f32 v[30:31], v[30:31], v[36:37] op_sel_hi:[1,0]
	v_pk_mul_f32 v[38:39], v[22:23], v[36:37] op_sel_hi:[1,0]
	v_pk_mul_f32 v[22:23], v[20:21], v[36:37] op_sel_hi:[1,0]
	v_pk_mul_f32 v[20:21], v[18:19], v[36:37] op_sel_hi:[1,0]
	v_mul_f32_e32 v18, 0xbfb8aa3b, v30
	v_mul_f32_e32 v19, 0xbfb8aa3b, v31
	v_exp_f32_e32 v18, v18
	v_exp_f32_e32 v19, v19
	v_pk_mul_f32 v[32:33], v[32:33], v[36:37] op_sel_hi:[1,0]
	v_pk_mul_f32 v[24:25], v[24:25], v[36:37] op_sel_hi:[1,0]
	v_add_f32_e32 v18, 1.0, v18
	v_add_f32_e32 v19, 1.0, v19
	v_rcp_f32_e32 v18, v18
	v_rcp_f32_e32 v19, v19
	v_pk_mul_f32 v[26:27], v[26:27], v[36:37] op_sel_hi:[1,0]
	v_pk_mul_f32 v[28:29], v[28:29], v[36:37] op_sel_hi:[1,0]
	v_mul_f32_e32 v18, v30, v18
	v_mul_f32_e32 v19, v31, v19
	v_mul_f32_e32 v18, v38, v18
	v_mul_f32_e32 v19, v39, v19
	v_cvt_pk_bf16_f32 v18, v18, v19
	v_mul_f32_e32 v19, 0xbfb8aa3b, v32
	v_exp_f32_e32 v19, v19
	s_nop 0
	v_add_f32_e32 v19, 1.0, v19
	v_rcp_f32_e32 v19, v19
	s_nop 0
	v_mul_f32_e32 v19, v32, v19
	v_mul_f32_e32 v19, v24, v19
	v_mul_f32_e32 v24, 0xbfb8aa3b, v33
	v_exp_f32_e32 v24, v24
	s_nop 0
	v_add_f32_e32 v24, 1.0, v24
	v_rcp_f32_e32 v24, v24
	s_nop 0
	v_mul_f32_e32 v24, v33, v24
	v_mul_f32_e32 v24, v25, v24
	v_cvt_pk_bf16_f32 v19, v19, v24
	v_mul_f32_e32 v24, 0xbfb8aa3b, v26
	v_exp_f32_e32 v24, v24
	s_nop 0
	v_add_f32_e32 v24, 1.0, v24
	v_rcp_f32_e32 v24, v24
	s_nop 0
	v_mul_f32_e32 v24, v26, v24
	v_mul_f32_e32 v20, v20, v24
	v_mul_f32_e32 v24, 0xbfb8aa3b, v27
	v_exp_f32_e32 v24, v24
	s_nop 0
	v_add_f32_e32 v24, 1.0, v24
	v_rcp_f32_e32 v24, v24
	s_nop 0
	v_mul_f32_e32 v24, v27, v24
	v_mul_f32_e32 v21, v21, v24
	v_cvt_pk_bf16_f32 v20, v20, v21
	v_mul_f32_e32 v21, 0xbfb8aa3b, v28
	v_exp_f32_e32 v21, v21
	s_nop 0
	v_add_f32_e32 v21, 1.0, v21
	v_rcp_f32_e32 v21, v21
	s_nop 0
	v_mul_f32_e32 v21, v28, v21
	v_mul_f32_e32 v21, v22, v21
	v_mul_f32_e32 v22, 0xbfb8aa3b, v29
	v_exp_f32_e32 v22, v22
	s_nop 0
	v_add_f32_e32 v22, 1.0, v22
	v_rcp_f32_e32 v22, v22
	s_nop 0
	v_mul_f32_e32 v22, v29, v22
	v_mul_f32_e32 v22, v23, v22
	v_cvt_pk_bf16_f32 v21, v21, v22
	global_store_dwordx4 v[34:35], v[18:21], off
	s_nop 1
	v_mov_b32_e32 v20, v170
	v_mov_b32_e32 v21, v171
	v_ffbh_u32_e32 v22, v21
	v_min_u32_e32 v22, 32, v22
	v_lshlrev_b64 v[20:21], v22, v[20:21]
	v_min_u32_e32 v20, 1, v20
	v_or_b32_e32 v20, v21, v20
	v_cvt_f32_u32_e32 v20, v20
	v_sub_u32_e32 v21, 32, v22
	v_add_u32_e32 v18, 0xb0, v140
	v_mad_i64_i32 v[18:19], s[2:3], v18, s1, v[142:143]
	v_ldexp_f32 v20, v20, v21
	v_fmamk_f32 v20, v20, 0x30000000, v198
	v_rsq_f32_e32 v20, v20
	v_lshl_add_u64 v[18:19], v[18:19], 0, v[144:145]
	s_mov_b64 s[2:3], -1
	v_pk_mul_f32 v[14:15], v[14:15], v[20:21] op_sel_hi:[1,0]
	v_pk_mul_f32 v[22:23], v[4:5], v[20:21] op_sel_hi:[1,0]
	v_pk_mul_f32 v[4:5], v[2:3], v[20:21] op_sel_hi:[1,0]
	v_mul_f32_e32 v2, 0xbfb8aa3b, v14
	v_mul_f32_e32 v3, 0xbfb8aa3b, v15
	v_exp_f32_e32 v2, v2
	v_exp_f32_e32 v3, v3
	v_pk_mul_f32 v[6:7], v[6:7], v[20:21] op_sel_hi:[1,0]
	v_pk_mul_f32 v[16:17], v[16:17], v[20:21] op_sel_hi:[1,0]
	v_add_f32_e32 v2, 1.0, v2
	v_add_f32_e32 v3, 1.0, v3
	v_rcp_f32_e32 v2, v2
	v_rcp_f32_e32 v3, v3
	v_pk_mul_f32 v[8:9], v[8:9], v[20:21] op_sel_hi:[1,0]
	v_pk_mul_f32 v[10:11], v[10:11], v[20:21] op_sel_hi:[1,0]
	v_mul_f32_e32 v2, v14, v2
	v_mul_f32_e32 v3, v15, v3
	v_mul_f32_e32 v2, v6, v2
	v_mul_f32_e32 v3, v7, v3
	v_cvt_pk_bf16_f32 v2, v2, v3
	v_mul_f32_e32 v3, 0xbfb8aa3b, v16
	v_mul_f32_e32 v6, 0xbfb8aa3b, v17
	v_exp_f32_e32 v3, v3
	v_exp_f32_e32 v6, v6
	v_pk_mul_f32 v[12:13], v[12:13], v[20:21] op_sel_hi:[1,0]
	v_add_f32_e32 v3, 1.0, v3
	v_add_f32_e32 v6, 1.0, v6
	v_rcp_f32_e32 v3, v3
	v_rcp_f32_e32 v6, v6
	v_mul_f32_e32 v3, v16, v3
	v_mul_f32_e32 v6, v17, v6
	v_mul_f32_e32 v3, v8, v3
	v_mul_f32_e32 v6, v9, v6
	v_cvt_pk_bf16_f32 v3, v3, v6
	v_mul_f32_e32 v6, 0xbfb8aa3b, v10
	v_exp_f32_e32 v6, v6
	s_nop 0
	v_add_f32_e32 v6, 1.0, v6
	v_rcp_f32_e32 v6, v6
	s_nop 0
	v_mul_f32_e32 v6, v10, v6
	v_mul_f32_e32 v4, v4, v6
	v_mul_f32_e32 v6, 0xbfb8aa3b, v11
	v_exp_f32_e32 v6, v6
	s_nop 0
	v_add_f32_e32 v6, 1.0, v6
	v_rcp_f32_e32 v6, v6
	s_nop 0
	v_mul_f32_e32 v6, v11, v6
	v_mul_f32_e32 v5, v5, v6
	v_cvt_pk_bf16_f32 v4, v4, v5
	v_mul_f32_e32 v5, 0xbfb8aa3b, v12
	v_exp_f32_e32 v5, v5
	v_mul_f32_e32 v6, 0xbfb8aa3b, v13
	v_exp_f32_e32 v6, v6
	v_add_f32_e32 v5, 1.0, v5
	v_rcp_f32_e32 v5, v5
	v_add_f32_e32 v6, 1.0, v6
	v_rcp_f32_e32 v6, v6
	v_mul_f32_e32 v5, v12, v5
	v_mul_f32_e32 v5, v22, v5
	v_mul_f32_e32 v6, v13, v6
	v_mul_f32_e32 v6, v23, v6
	v_cvt_pk_bf16_f32 v5, v5, v6
	global_store_dwordx4 v[18:19], v[2:5], off
	s_cbranch_vccnz .LBB0_468
	s_andn2_b64 vcc, exec, s[6:7]
	s_cbranch_vccnz .LBB0_467
	s_barrier
	s_branch .LBB0_467

; __device__ __forceinline__ unsigned cvt_pk_bf16(float lo, float hi) { unsigned r; asm volatile("v_cvt_pk_bf16_f32 %0, %1, %2" : "=v"(r) : "v"(lo), "v"(hi)); return r; }
; __device__ __forceinline__ float rs_of(const rsq_t* rsq, int row) { return __builtin_amdgcn_rsqf((float)rsq[row] * (1.0f / (1048576.0f * 2048.0f)) + 1e-6f); }
;     __device__ __forceinline__ void operator()(const f32x4 (&acc)[2][2][4][2], const Unit& u, int wr, int wc, int fr, int fq) const {
;         const int row0 = u.pm * BM + wr * 64 + fr; const int col0 = u.pn * BM + wc * 32 + 8 * fq;
; #pragma unroll
;         for (int ai = 0; ai < 2; ++ai)
; #pragma unroll
;             for (int m = 0; m < 4; ++m) { const int row = row0 + ai * HALF + m * 16; bf16_t* rowp = O + (size_t)row * ldc + col0;
;                 const float rs = rsq ? rs_of(rsq, row) : 1.0f;
; #pragma unroll
;                 for (int bj = 0; bj < 2; ++bj) { const f32x4 v0 = acc[ai][bj][m][0] * rs, v1 = acc[ai][bj][m][1] * rs;
;                     u32x4 w; w.x = cvt_pk_bf16(v0[0], v0[1]); w.y = cvt_pk_bf16(v0[2], v0[3]); w.z = cvt_pk_bf16(v1[0], v1[1]); w.w = cvt_pk_bf16(v1[2], v1[3]);
;                     *(u32x4*)(rowp + bj * HALF) = w; } }
;     }
.LBB0_738:
	v_lshl_add_u32 v140, s2, 8, v148
	v_ashrrev_i32_e32 v141, 31, v140
	v_lshl_add_u64 v[146:147], v[140:141], 3, s[18:19]
	global_load_dwordx2 v[142:143], v[146:147], off
	global_load_dwordx2 v[158:159], v[146:147], off offset:128
	global_load_dwordx2 v[160:161], v[146:147], off offset:256
	global_load_dwordx2 v[162:163], v[146:147], off offset:384
	global_load_dwordx2 v[164:165], v[146:147], off offset:1024
	global_load_dwordx2 v[166:167], v[146:147], off offset:1152
	global_load_dwordx2 v[168:169], v[146:147], off offset:1280
	global_load_dwordx2 v[170:171], v[146:147], off offset:1408
	v_lshl_add_u32 v144, s3, 8, v150
	v_ashrrev_i32_e32 v145, 31, v144
	v_lshlrev_b64 v[144:145], 1, v[144:145]
	s_andn2_b64 vcc, exec, s[8:9]
	s_waitcnt vmcnt(0)
	v_ffbh_u32_e32 v141, v143
	v_min_u32_e32 v141, 32, v141
	v_lshlrev_b64 v[142:143], v141, v[142:143]
	v_min_u32_e32 v142, 1, v142
	v_or_b32_e32 v142, v143, v142
	v_cvt_f32_u32_e32 v152, v142
	v_sub_u32_e32 v141, 32, v141
	v_mov_b64_e32 v[142:143], s[12:13]
	v_mad_i64_i32 v[154:155], s[2:3], v140, s79, v[142:143]
	v_ldexp_f32 v141, v152, v141
	v_fmamk_f32 v141, v141, 0x30000000, v198
	v_rsq_f32_e32 v152, v141
	v_lshl_add_u64 v[154:155], v[154:155], 0, v[144:145]
	v_pk_mul_f32 v[128:129], v[128:129], v[152:153] op_sel_hi:[1,0]
	v_pk_mul_f32 v[126:127], v[126:127], v[152:153] op_sel_hi:[1,0]
	v_pk_mul_f32 v[124:125], v[124:125], v[152:153] op_sel_hi:[1,0]
	v_pk_mul_f32 v[122:123], v[122:123], v[152:153] op_sel_hi:[1,0]
	v_pk_mul_f32 v[120:121], v[120:121], v[152:153] op_sel_hi:[1,0]
	v_pk_mul_f32 v[118:119], v[118:119], v[152:153] op_sel_hi:[1,0]
	v_pk_mul_f32 v[156:157], v[116:117], v[152:153] op_sel_hi:[1,0]
	v_pk_mul_f32 v[152:153], v[114:115], v[152:153] op_sel_hi:[1,0]
	v_cvt_pk_bf16_f32 v114, v126, v127
	v_cvt_pk_bf16_f32 v115, v128, v129
	v_cvt_pk_bf16_f32 v116, v122, v123
	v_cvt_pk_bf16_f32 v117, v124, v125
	global_store_dwordx4 v[154:155], v[114:117], off
	s_nop 1
	v_cvt_pk_bf16_f32 v114, v118, v119
	v_cvt_pk_bf16_f32 v115, v120, v121
	v_cvt_pk_bf16_f32 v116, v152, v153
	v_cvt_pk_bf16_f32 v117, v156, v157
	global_store_dwordx4 v[154:155], v[114:117], off offset:256
	s_nop 1
	v_mov_b32_e32 v114, v158
	v_mov_b32_e32 v115, v159
	v_ffbh_u32_e32 v116, v115
	v_min_u32_e32 v116, 32, v116
	v_lshlrev_b64 v[114:115], v116, v[114:115]
	v_min_u32_e32 v114, 1, v114
	v_or_b32_e32 v114, v115, v114
	v_cvt_f32_u32_e32 v114, v114
	v_sub_u32_e32 v116, 32, v116
	v_or_b32_e32 v115, 16, v140
	v_ldexp_f32 v114, v114, v116
	v_fmamk_f32 v114, v114, 0x30000000, v198
	v_rsq_f32_e32 v114, v114
	v_mad_i64_i32 v[116:117], s[2:3], v115, s79, v[142:143]
	v_lshl_add_u64 v[116:117], v[116:117], 0, v[144:145]
	v_pk_mul_f32 v[112:113], v[112:113], v[114:115] op_sel_hi:[1,0]
	v_pk_mul_f32 v[110:111], v[110:111], v[114:115] op_sel_hi:[1,0]
	v_pk_mul_f32 v[108:109], v[108:109], v[114:115] op_sel_hi:[1,0]
	v_pk_mul_f32 v[106:107], v[106:107], v[114:115] op_sel_hi:[1,0]
	v_pk_mul_f32 v[104:105], v[104:105], v[114:115] op_sel_hi:[1,0]
	v_pk_mul_f32 v[102:103], v[102:103], v[114:115] op_sel_hi:[1,0]
	v_pk_mul_f32 v[118:119], v[100:101], v[114:115] op_sel_hi:[1,0]
	v_pk_mul_f32 v[114:115], v[98:99], v[114:115] op_sel_hi:[1,0]
	v_cvt_pk_bf16_f32 v98, v110, v111
	v_cvt_pk_bf16_f32 v99, v112, v113
	v_cvt_pk_bf16_f32 v100, v106, v107
	v_cvt_pk_bf16_f32 v101, v108, v109
	global_store_dwordx4 v[116:117], v[98:101], off
	s_nop 1
	v_cvt_pk_bf16_f32 v98, v102, v103
	v_cvt_pk_bf16_f32 v99, v104, v105
	v_cvt_pk_bf16_f32 v100, v114, v115
	v_cvt_pk_bf16_f32 v101, v118, v119
	global_store_dwordx4 v[116:117], v[98:101], off offset:256
	s_nop 1
	v_mov_b32_e32 v98, v160
	v_mov_b32_e32 v99, v161
	v_ffbh_u32_e32 v100, v99
	v_min_u32_e32 v100, 32, v100
	v_lshlrev_b64 v[98:99], v100, v[98:99]
	v_min_u32_e32 v98, 1, v98
	v_or_b32_e32 v98, v99, v98
	v_cvt_f32_u32_e32 v98, v98
	v_sub_u32_e32 v100, 32, v100
	v_or_b32_e32 v99, 32, v140
	v_ldexp_f32 v98, v98, v100
	v_fmamk_f32 v98, v98, 0x30000000, v198
	v_rsq_f32_e32 v98, v98
	v_mad_i64_i32 v[100:101], s[2:3], v99, s79, v[142:143]
	v_lshl_add_u64 v[100:101], v[100:101], 0, v[144:145]
	v_pk_mul_f32 v[96:97], v[96:97], v[98:99] op_sel_hi:[1,0]
	v_pk_mul_f32 v[94:95], v[94:95], v[98:99] op_sel_hi:[1,0]
	v_pk_mul_f32 v[92:93], v[92:93], v[98:99] op_sel_hi:[1,0]
	v_pk_mul_f32 v[90:91], v[90:91], v[98:99] op_sel_hi:[1,0]
	v_pk_mul_f32 v[88:89], v[88:89], v[98:99] op_sel_hi:[1,0]
	v_pk_mul_f32 v[86:87], v[86:87], v[98:99] op_sel_hi:[1,0]
	v_pk_mul_f32 v[102:103], v[84:85], v[98:99] op_sel_hi:[1,0]
	v_pk_mul_f32 v[98:99], v[82:83], v[98:99] op_sel_hi:[1,0]
	v_cvt_pk_bf16_f32 v82, v94, v95
	v_cvt_pk_bf16_f32 v83, v96, v97
	v_cvt_pk_bf16_f32 v84, v90, v91
	v_cvt_pk_bf16_f32 v85, v92, v93
	global_store_dwordx4 v[100:101], v[82:85], off
	s_nop 1
	v_cvt_pk_bf16_f32 v82, v86, v87
	v_cvt_pk_bf16_f32 v83, v88, v89
	v_cvt_pk_bf16_f32 v84, v98, v99
	v_cvt_pk_bf16_f32 v85, v102, v103
	global_store_dwordx4 v[100:101], v[82:85], off offset:256
	s_nop 1
	v_mov_b32_e32 v82, v162
	v_mov_b32_e32 v83, v163
	v_ffbh_u32_e32 v84, v83
	v_min_u32_e32 v84, 32, v84
	v_lshlrev_b64 v[82:83], v84, v[82:83]
	v_min_u32_e32 v82, 1, v82
	v_or_b32_e32 v82, v83, v82
	v_cvt_f32_u32_e32 v82, v82
	v_sub_u32_e32 v84, 32, v84
	v_or_b32_e32 v83, 48, v140
	v_ldexp_f32 v82, v82, v84
	v_fmamk_f32 v82, v82, 0x30000000, v198
	v_rsq_f32_e32 v82, v82
	v_mad_i64_i32 v[84:85], s[2:3], v83, s79, v[142:143]
	v_lshl_add_u64 v[84:85], v[84:85], 0, v[144:145]
	v_pk_mul_f32 v[80:81], v[80:81], v[82:83] op_sel_hi:[1,0]
	v_pk_mul_f32 v[78:79], v[78:79], v[82:83] op_sel_hi:[1,0]
	v_pk_mul_f32 v[76:77], v[76:77], v[82:83] op_sel_hi:[1,0]
; __device__ __forceinline__ unsigned cvt_pk_bf16(float lo, float hi) { unsigned r; asm volatile("v_cvt_pk_bf16_f32 %0, %1, %2" : "=v"(r) : "v"(lo), "v"(hi)); return r; }
; __device__ __forceinline__ float rs_of(const rsq_t* rsq, int row) { return __builtin_amdgcn_rsqf((float)rsq[row] * (1.0f / (1048576.0f * 2048.0f)) + 1e-6f); }
;     __device__ __forceinline__ void operator()(const f32x4 (&acc)[2][2][4][2], const Unit& u, int wr, int wc, int fr, int fq) const {
;         const int row0 = u.pm * BM + wr * 64 + fr; const int col0 = u.pn * BM + wc * 32 + 8 * fq;
; #pragma unroll
;         for (int ai = 0; ai < 2; ++ai)
; #pragma unroll
;             for (int m = 0; m < 4; ++m) { const int row = row0 + ai * HALF + m * 16; bf16_t* rowp = O + (size_t)row * ldc + col0;
;                 const float rs = rsq ? rs_of(rsq, row) : 1.0f;
; #pragma unroll
;                 for (int bj = 0; bj < 2; ++bj) { const f32x4 v0 = acc[ai][bj][m][0] * rs, v1 = acc[ai][bj][m][1] * rs;
;                     u32x4 w; w.x = cvt_pk_bf16(v0[0], v0[1]); w.y = cvt_pk_bf16(v0[2], v0[3]); w.z = cvt_pk_bf16(v1[0], v1[1]); w.w = cvt_pk_bf16(v1[2], v1[3]);
;                     *(u32x4*)(rowp + bj * HALF) = w; } }
;     }
	v_pk_mul_f32 v[74:75], v[74:75], v[82:83] op_sel_hi:[1,0]
	v_pk_mul_f32 v[72:73], v[72:73], v[82:83] op_sel_hi:[1,0]
	v_pk_mul_f32 v[70:71], v[70:71], v[82:83] op_sel_hi:[1,0]
	v_pk_mul_f32 v[86:87], v[68:69], v[82:83] op_sel_hi:[1,0]
	v_pk_mul_f32 v[82:83], v[66:67], v[82:83] op_sel_hi:[1,0]
	v_cvt_pk_bf16_f32 v66, v78, v79
	v_cvt_pk_bf16_f32 v67, v80, v81
	v_cvt_pk_bf16_f32 v68, v74, v75
	v_cvt_pk_bf16_f32 v69, v76, v77
	global_store_dwordx4 v[84:85], v[66:69], off
	s_nop 1
	v_cvt_pk_bf16_f32 v66, v70, v71
	v_cvt_pk_bf16_f32 v67, v72, v73
	v_cvt_pk_bf16_f32 v68, v82, v83
	v_cvt_pk_bf16_f32 v69, v86, v87
	global_store_dwordx4 v[84:85], v[66:69], off offset:256
	s_nop 1
	v_mov_b32_e32 v66, v164
	v_mov_b32_e32 v67, v165
	v_ffbh_u32_e32 v68, v67
	v_min_u32_e32 v68, 32, v68
	v_lshlrev_b64 v[66:67], v68, v[66:67]
	v_min_u32_e32 v66, 1, v66
	v_or_b32_e32 v66, v67, v66
	v_cvt_f32_u32_e32 v66, v66
	v_sub_u32_e32 v68, 32, v68
	v_add_u32_e32 v67, 0x80, v140
	v_ldexp_f32 v66, v66, v68
	v_fmamk_f32 v66, v66, 0x30000000, v198
	v_rsq_f32_e32 v66, v66
	v_mad_i64_i32 v[68:69], s[2:3], v67, s79, v[142:143]
	v_lshl_add_u64 v[68:69], v[68:69], 0, v[144:145]
	v_pk_mul_f32 v[64:65], v[64:65], v[66:67] op_sel_hi:[1,0]
	v_pk_mul_f32 v[62:63], v[62:63], v[66:67] op_sel_hi:[1,0]
	v_pk_mul_f32 v[60:61], v[60:61], v[66:67] op_sel_hi:[1,0]
	v_pk_mul_f32 v[58:59], v[58:59], v[66:67] op_sel_hi:[1,0]
	v_pk_mul_f32 v[56:57], v[56:57], v[66:67] op_sel_hi:[1,0]
	v_pk_mul_f32 v[54:55], v[54:55], v[66:67] op_sel_hi:[1,0]
	v_pk_mul_f32 v[70:71], v[52:53], v[66:67] op_sel_hi:[1,0]
	v_pk_mul_f32 v[66:67], v[50:51], v[66:67] op_sel_hi:[1,0]
	v_cvt_pk_bf16_f32 v50, v62, v63
	v_cvt_pk_bf16_f32 v51, v64, v65
	v_cvt_pk_bf16_f32 v52, v58, v59
	v_cvt_pk_bf16_f32 v53, v60, v61
	global_store_dwordx4 v[68:69], v[50:53], off
	s_nop 1
	v_cvt_pk_bf16_f32 v50, v54, v55
	v_cvt_pk_bf16_f32 v51, v56, v57
	v_cvt_pk_bf16_f32 v52, v66, v67
	v_cvt_pk_bf16_f32 v53, v70, v71
	global_store_dwordx4 v[68:69], v[50:53], off offset:256
	s_nop 1
	v_mov_b32_e32 v50, v166
	v_mov_b32_e32 v51, v167
	v_ffbh_u32_e32 v52, v51
	v_min_u32_e32 v52, 32, v52
	v_lshlrev_b64 v[50:51], v52, v[50:51]
	v_min_u32_e32 v50, 1, v50
	v_or_b32_e32 v50, v51, v50
	v_cvt_f32_u32_e32 v50, v50
	v_sub_u32_e32 v52, 32, v52
	v_add_u32_e32 v51, 0x90, v140
	v_ldexp_f32 v50, v50, v52
	v_fmamk_f32 v50, v50, 0x30000000, v198
	v_rsq_f32_e32 v50, v50
	v_mad_i64_i32 v[52:53], s[2:3], v51, s79, v[142:143]
	v_lshl_add_u64 v[52:53], v[52:53], 0, v[144:145]
	v_pk_mul_f32 v[48:49], v[48:49], v[50:51] op_sel_hi:[1,0]
	v_pk_mul_f32 v[46:47], v[46:47], v[50:51] op_sel_hi:[1,0]
	v_pk_mul_f32 v[44:45], v[44:45], v[50:51] op_sel_hi:[1,0]
	v_pk_mul_f32 v[42:43], v[42:43], v[50:51] op_sel_hi:[1,0]
	v_pk_mul_f32 v[40:41], v[40:41], v[50:51] op_sel_hi:[1,0]
	v_pk_mul_f32 v[38:39], v[38:39], v[50:51] op_sel_hi:[1,0]
	v_pk_mul_f32 v[54:55], v[36:37], v[50:51] op_sel_hi:[1,0]
	v_pk_mul_f32 v[50:51], v[34:35], v[50:51] op_sel_hi:[1,0]
	v_cvt_pk_bf16_f32 v34, v46, v47
	v_cvt_pk_bf16_f32 v35, v48, v49
	v_cvt_pk_bf16_f32 v36, v42, v43
	v_cvt_pk_bf16_f32 v37, v44, v45
	global_store_dwordx4 v[52:53], v[34:37], off
	s_nop 1
	v_cvt_pk_bf16_f32 v34, v38, v39
	v_cvt_pk_bf16_f32 v35, v40, v41
	v_cvt_pk_bf16_f32 v36, v50, v51
	v_cvt_pk_bf16_f32 v37, v54, v55
	global_store_dwordx4 v[52:53], v[34:37], off offset:256
	s_nop 1
	v_mov_b32_e32 v34, v168
	v_mov_b32_e32 v35, v169
	v_ffbh_u32_e32 v36, v35
	v_min_u32_e32 v36, 32, v36
	v_lshlrev_b64 v[34:35], v36, v[34:35]
	v_min_u32_e32 v34, 1, v34
	v_or_b32_e32 v34, v35, v34
	v_cvt_f32_u32_e32 v34, v34
	v_sub_u32_e32 v36, 32, v36
	v_add_u32_e32 v35, 0xa0, v140
	v_ldexp_f32 v34, v34, v36
	v_fmamk_f32 v34, v34, 0x30000000, v198
	v_rsq_f32_e32 v34, v34
	v_mad_i64_i32 v[36:37], s[2:3], v35, s79, v[142:143]
	v_lshl_add_u64 v[36:37], v[36:37], 0, v[144:145]
	v_pk_mul_f32 v[32:33], v[32:33], v[34:35] op_sel_hi:[1,0]
	v_pk_mul_f32 v[30:31], v[30:31], v[34:35] op_sel_hi:[1,0]
	v_pk_mul_f32 v[28:29], v[28:29], v[34:35] op_sel_hi:[1,0]
	v_pk_mul_f32 v[26:27], v[26:27], v[34:35] op_sel_hi:[1,0]
	v_pk_mul_f32 v[24:25], v[24:25], v[34:35] op_sel_hi:[1,0]
	v_pk_mul_f32 v[22:23], v[22:23], v[34:35] op_sel_hi:[1,0]
	v_pk_mul_f32 v[38:39], v[20:21], v[34:35] op_sel_hi:[1,0]
	v_pk_mul_f32 v[34:35], v[18:19], v[34:35] op_sel_hi:[1,0]
	v_cvt_pk_bf16_f32 v18, v30, v31
	v_cvt_pk_bf16_f32 v19, v32, v33
	v_cvt_pk_bf16_f32 v20, v26, v27
	v_cvt_pk_bf16_f32 v21, v28, v29
	global_store_dwordx4 v[36:37], v[18:21], off
	s_nop 1
	v_cvt_pk_bf16_f32 v18, v22, v23
	v_cvt_pk_bf16_f32 v19, v24, v25
	v_cvt_pk_bf16_f32 v20, v34, v35
	v_cvt_pk_bf16_f32 v21, v38, v39
	global_store_dwordx4 v[36:37], v[18:21], off offset:256
	s_nop 1
	v_mov_b32_e32 v18, v170
	v_mov_b32_e32 v19, v171
	v_ffbh_u32_e32 v20, v19
	v_min_u32_e32 v20, 32, v20
	v_lshlrev_b64 v[18:19], v20, v[18:19]
	v_min_u32_e32 v18, 1, v18
	v_or_b32_e32 v18, v19, v18
	v_cvt_f32_u32_e32 v18, v18
	v_sub_u32_e32 v20, 32, v20
	v_add_u32_e32 v19, 0xb0, v140
	v_ldexp_f32 v18, v18, v20
	v_fmamk_f32 v18, v18, 0x30000000, v198
	v_rsq_f32_e32 v18, v18
	v_mad_i64_i32 v[20:21], s[2:3], v19, s79, v[142:143]
	v_lshl_add_u64 v[20:21], v[20:21], 0, v[144:145]
	v_pk_mul_f32 v[16:17], v[16:17], v[18:19] op_sel_hi:[1,0]
	v_pk_mul_f32 v[14:15], v[14:15], v[18:19] op_sel_hi:[1,0]
	v_pk_mul_f32 v[12:13], v[12:13], v[18:19] op_sel_hi:[1,0]
	v_pk_mul_f32 v[10:11], v[10:11], v[18:19] op_sel_hi:[1,0]
	v_pk_mul_f32 v[8:9], v[8:9], v[18:19] op_sel_hi:[1,0]
	v_pk_mul_f32 v[6:7], v[6:7], v[18:19] op_sel_hi:[1,0]
	v_pk_mul_f32 v[22:23], v[4:5], v[18:19] op_sel_hi:[1,0]
	v_pk_mul_f32 v[18:19], v[2:3], v[18:19] op_sel_hi:[1,0]
	v_cvt_pk_bf16_f32 v2, v14, v15
	v_cvt_pk_bf16_f32 v3, v16, v17
	v_cvt_pk_bf16_f32 v4, v10, v11
	v_cvt_pk_bf16_f32 v5, v12, v13
	s_mov_b64 s[2:3], -1
	global_store_dwordx4 v[20:21], v[2:5], off
	s_nop 1
	v_cvt_pk_bf16_f32 v2, v6, v7
	v_cvt_pk_bf16_f32 v3, v8, v9
	v_cvt_pk_bf16_f32 v4, v18, v19
	v_cvt_pk_bf16_f32 v5, v22, v23
	global_store_dwordx4 v[20:21], v[2:5], off offset:256
	s_cbranch_vccnz .LBB0_731
	s_andn2_b64 vcc, exec, s[10:11]
	s_cbranch_vccnz .LBB0_730
	s_barrier
	s_branch .LBB0_730

; __device__ __forceinline__ void finishSM(f32x16& p0, f32x16& p1, float alpha, float& l_reg, bf16x8& pa0, bf16x8& pa1, bf16x8& pa2, bf16x8& pa3) {
; #pragma unroll
;   for (int r = 0; r < 16; ++r) p1[r] = __builtin_amdgcn_exp2f(p1[r]);
;   float ps = 0;
; #pragma unroll
;   for (int r = 0; r < 16; ++r) ps += p0[r];
; #pragma unroll
;   for (int r = 0; r < 16; ++r) ps += p1[r];
;   { auto rr = __builtin_amdgcn_permlane32_swap(__float_as_uint(ps), __float_as_uint(ps), false, false);
;     ps = __uint_as_float(rr[0]) + __uint_as_float(rr[1]); }
;   l_reg = l_reg * alpha + ps;
;   PK4(p0, 0, pa0); PK4(p0, 8, pa1); PK4(p1, 0, pa2); PK4(p1, 8, pa3);
; }
;   p0 = f32x16{}; p1 = f32x16{};
; #pragma unroll
;   for (int d0 = DLO; d0 < DHI; ++d0) { int cb = (d0 * 16 + hi * 8) * 2;
;     bf16x8 b0 = *reinterpret_cast<const bf16x8*>((const char*)Ks + KSWZ(r32, cb));
;     bf16x8 b1 = *reinterpret_cast<const bf16x8*>((const char*)Ks + KSWZ(32 + r32, cb));
;     p0 = __builtin_amdgcn_mfma_f32_32x32x16_bf16(b0, qr[d0], p0, 0, 0, 0);
;     p1 = __builtin_amdgcn_mfma_f32_32x32x16_bf16(b1, qr[d0], p1, 0, 0, 0); }
; }
; __device__ __forceinline__ int v_st(int k, int c) { const int kk = (k & ~0xC) | ((k & 4) << 1) | ((k & 8) >> 1); return ((kk >> 3) * 4 + (c >> 5)) * 512 + ((kk & 7) * 32 + (c & 31)) * 2; }
; __device__ __forceinline__ int v_rd_base(int lane) { return ((lane & 3) << 3) | (((lane >> 2) & 3) << 6) | (((lane >> 4) & 1) << 5) | (((lane >> 5) & 1) << 8); }
; template <int OFF> __device__ __forceinline__ s16x4 tr_read(int vb) {
;   s16x4 r; asm volatile("ds_read_b64_tr_b16 %0, %1 offset:%2" : "=&v"(r) : "v"(vb), "i"(OFF) : "memory"); return r;
; }
; template <int D0> __device__ __forceinline__ void pv_one(f32x16& od, int vb, bf16x8 pa0, bf16x8 pa1, bf16x8 pa2, bf16x8 pa3) {
;   const s16x4 l0 = tr_read<v_rd_off(D0, 0, 0)>(vb), h0 = tr_read<v_rd_off(D0, 0, 1)>(vb), l1 = tr_read<v_rd_off(D0, 1, 0)>(vb), h1 = tr_read<v_rd_off(D0, 1, 1)>(vb);
;   const s16x4 l2 = tr_read<v_rd_off(D0, 2, 0)>(vb), h2 = tr_read<v_rd_off(D0, 2, 1)>(vb), l3 = tr_read<v_rd_off(D0, 3, 0)>(vb), h3 = tr_read<v_rd_off(D0, 3, 1)>(vb);
;   asm volatile("s_waitcnt lgkmcnt(0)" ::: "memory"); SBAR();
;     ...
;   od = __builtin_amdgcn_mfma_f32_32x32x16_bf16(pa0, PK(l0, h0), od, 0, 0, 0);
;   od = __builtin_amdgcn_mfma_f32_32x32x16_bf16(pa1, PK(l1, h1), od, 0, 0, 0);
.LBB0_1002:
	ds_read_b128 v[66:69], v190 offset:49152
	ds_read_b128 v[70:73], v190 offset:57344
	ds_read_b128 v[186:189], v194 offset:49152
	ds_read_b128 v[208:211], v194 offset:57344
	ds_read_b128 v[232:235], v195 offset:49152
	ds_read_b128 v[236:239], v195 offset:57344
	ds_read_b128 v[240:243], v196 offset:49152
	ds_read_b128 v[244:247], v196 offset:57344
	v_add_f32_e32 v146, 0, v161
	v_add_f32_e32 v146, v167, v146
	v_add_f32_e32 v146, v147, v146
	s_waitcnt lgkmcnt(7)
	v_mfma_f32_32x32x16_bf16 v[82:97], v[66:69], v[102:105], 0
	v_add_f32_e32 v146, v166, v146
	v_add_f32_e32 v146, v148, v146
	v_add_f32_e32 v146, v160, v146
	v_add_f32_e32 v146, v149, v146
	v_add_f32_e32 v146, v159, v146
	v_add_f32_e32 v146, v156, v146
	s_waitcnt lgkmcnt(6)
	v_mfma_f32_32x32x16_bf16 v[66:81], v[70:73], v[102:105], 0
	v_add_f32_e32 v146, v158, v146
	v_add_f32_e32 v146, v154, v146
	v_add_f32_e32 v146, v157, v146
	v_exp_f32_e32 v142, v142
	v_add_f32_e32 v146, v152, v146
	v_exp_f32_e32 v143, v143
	v_add_f32_e32 v146, v155, v146
	s_waitcnt lgkmcnt(5)
	v_mfma_f32_32x32x16_bf16 v[82:97], v[186:189], v[98:101], v[82:97]
	v_exp_f32_e32 v140, v140
	v_add_f32_e32 v146, v151, v146
	v_exp_f32_e32 v141, v141
	v_add_f32_e32 v146, v153, v146
	v_exp_f32_e32 v134, v134
	v_add_f32_e32 v146, v142, v146
	v_exp_f32_e32 v135, v135
	s_waitcnt lgkmcnt(4)
	v_mfma_f32_32x32x16_bf16 v[66:81], v[208:211], v[98:101], v[66:81]
	v_add_f32_e32 v146, v143, v146
	v_exp_f32_e32 v132, v132
	v_add_f32_e32 v146, v140, v146
	v_exp_f32_e32 v133, v133
	v_add_f32_e32 v146, v141, v146
	v_exp_f32_e32 v130, v130
	s_waitcnt lgkmcnt(3)
	v_mfma_f32_32x32x16_bf16 v[82:97], v[232:235], v[106:109], v[82:97]
	v_add_f32_e32 v146, v134, v146
	v_exp_f32_e32 v131, v131
	v_add_f32_e32 v146, v135, v146
	v_exp_f32_e32 v144, v144
	v_add_f32_e32 v146, v132, v146
	v_exp_f32_e32 v145, v145
	v_add_f32_e32 v146, v133, v146
	s_waitcnt lgkmcnt(2)
	v_mfma_f32_32x32x16_bf16 v[66:81], v[236:239], v[106:109], v[66:81]
	v_exp_f32_e32 v138, v138
	v_add_f32_e32 v146, v130, v146
	v_exp_f32_e32 v139, v139
	v_add_f32_e32 v146, v131, v146
	v_exp_f32_e32 v136, v136
	v_add_f32_e32 v146, v144, v146
	s_waitcnt lgkmcnt(1)
	v_mfma_f32_32x32x16_bf16 v[82:97], v[240:243], v[110:113], v[82:97]
	v_exp_f32_e32 v137, v137
	v_add_f32_e32 v146, v145, v146
	v_add_f32_e32 v146, v138, v146
	v_add_f32_e32 v146, v139, v146
	v_add_f32_e32 v146, v136, v146
	v_add_f32_e32 v207, v137, v146
	v_cvt_pk_bf16_f32 v146, v161, v167
	s_waitcnt lgkmcnt(0)
	v_mfma_f32_32x32x16_bf16 v[66:81], v[244:247], v[110:113], v[66:81]
	v_mov_b32_e32 v208, v207
	v_cvt_pk_bf16_f32 v147, v147, v166
	v_cvt_pk_bf16_f32 v148, v148, v160
	s_nop 1
	v_permlane32_swap_b32_e32 v207, v208
	v_cvt_pk_bf16_f32 v149, v149, v159
	v_permlane32_swap_b32_e32 v146, v148
	v_cvt_pk_bf16_f32 v156, v156, v158
	v_cvt_pk_bf16_f32 v157, v154, v157
	v_cvt_pk_bf16_f32 v158, v152, v155
	v_cvt_pk_bf16_f32 v159, v151, v153
	v_cvt_pk_bf16_f32 v152, v142, v143
	v_cvt_pk_bf16_f32 v153, v140, v141
	v_cvt_pk_bf16_f32 v154, v134, v135
	v_cvt_pk_bf16_f32 v155, v132, v133
	v_cvt_pk_bf16_f32 v186, v130, v131
	v_cvt_pk_bf16_f32 v187, v144, v145
	v_cvt_pk_bf16_f32 v188, v138, v139
	v_cvt_pk_bf16_f32 v189, v136, v137
	v_permlane32_swap_b32_e32 v147, v149
	v_permlane32_swap_b32_e32 v156, v158
	v_permlane32_swap_b32_e32 v157, v159
	v_permlane32_swap_b32_e32 v152, v154
	v_permlane32_swap_b32_e32 v153, v155
	v_permlane32_swap_b32_e32 v186, v188
	v_permlane32_swap_b32_e32 v187, v189
	s_waitcnt vmcnt(0)
	ds_write_b128 v192, v[114:117]
	ds_write_b128 v193, v[118:121]
	ds_write_b128 v177, v[122:125] offset:32768
	ds_write_b128 v191, v[126:129] offset:32768
	v_lshl_add_u64 v[168:169], v[164:165], 0, v[0:1]
	s_mov_b32 s1, 0x18fb0000
	v_add_co_u32_e32 v130, vcc, s1, v168
	s_mov_b32 s1, 0x18ff8000
	s_nop 0
	v_addc_co_u32_e32 v131, vcc, 0, v169, vcc
	v_add_co_u32_e32 v134, vcc, s1, v168
	v_lshl_add_u64 v[166:167], v[162:163], 0, v[0:1]
	s_nop 0
	v_addc_co_u32_e32 v135, vcc, 0, v169, vcc
	s_mov_b32 s1, 0x1f648000
	v_add_co_u32_e32 v138, vcc, s1, v166
	s_mov_b32 s1, 0x1f654000
	s_nop 0
	v_addc_co_u32_e32 v139, vcc, 0, v167, vcc
	v_add_co_u32_e32 v142, vcc, s1, v166
	global_load_dwordx4 v[130:133], v[130:131], off
	s_nop 0
	global_load_dwordx4 v[134:137], v[134:135], off
	v_addc_co_u32_e32 v143, vcc, 0, v167, vcc
	global_load_dwordx4 v[138:141], v[138:139], off
	s_nop 0
	global_load_dwordx4 v[142:145], v[142:143], off
	ds_read_b64_tr_b16 v[210:211], v176 offset:0
	ds_read_b64_tr_b16 v[212:213], v176 offset:0x800
	ds_read_b64_tr_b16 v[214:215], v176 offset:0x1000
	ds_read_b64_tr_b16 v[216:217], v176 offset:0x1800
	ds_read_b64_tr_b16 v[218:219], v176 offset:0x2000
	ds_read_b64_tr_b16 v[220:221], v176 offset:0x2800
	ds_read_b64_tr_b16 v[222:223], v176 offset:0x3000
	ds_read_b64_tr_b16 v[224:225], v176 offset:0x3800
	s_waitcnt lgkmcnt(4)
	s_nop 0
	v_mfma_f32_32x32x16_bf16 v[2:17], v[146:149], v[210:213], v[2:17]
	ds_read_b64_tr_b16 v[210:211], v176 offset:0x200
	ds_read_b64_tr_b16 v[212:213], v176 offset:0xa00
	v_mfma_f32_32x32x16_bf16 v[2:17], v[156:159], v[214:217], v[2:17]
	ds_read_b64_tr_b16 v[214:215], v176 offset:0x1200
	ds_read_b64_tr_b16 v[216:217], v176 offset:0x1a00
	s_waitcnt lgkmcnt(4)
	v_mfma_f32_32x32x16_bf16 v[2:17], v[152:155], v[218:221], v[2:17]
	ds_read_b64_tr_b16 v[218:219], v176 offset:0x2200
	ds_read_b64_tr_b16 v[220:221], v176 offset:0x2a00
	v_mfma_f32_32x32x16_bf16 v[2:17], v[186:189], v[222:225], v[2:17]
	ds_read_b64_tr_b16 v[222:223], v176 offset:0x3200
	ds_read_b64_tr_b16 v[224:225], v176 offset:0x3a00
	s_waitcnt lgkmcnt(4)
; __device__ __forceinline__ void partialSM(f32x16& p0, f32x16& p1, float& m_reg, float& mn, float& alpha) {
;   constexpr float C = SCALE * 1.4426950408889634f;
;   float pmax = p0[0];
; #pragma unroll
;   for (int r = 1; r < 16; ++r) pmax = fmaxf(pmax, p0[r]);
; #pragma unroll
;   for (int r = 0; r < 16; ++r) pmax = fmaxf(pmax, p1[r]);
;   { auto rr = __builtin_amdgcn_permlane32_swap(__float_as_uint(pmax), __float_as_uint(pmax), false, false);
;     pmax = fmaxf(__uint_as_float(rr[0]), __uint_as_float(rr[1])); }
;   if (__builtin_expect(__all(pmax - m_reg <= THR / SCALE), 1)) { mn = m_reg; alpha = 1.f; }
;   else { mn = fmaxf(m_reg, pmax); alpha = __builtin_amdgcn_exp2f((m_reg - mn) * C); m_reg = mn; }
	v_mfma_f32_32x32x16_bf16 v[50:65], v[146:149], v[210:213], v[50:65]
	ds_read_b64_tr_b16 v[210:211], v176 offset:0x400
	ds_read_b64_tr_b16 v[212:213], v176 offset:0xc00
	v_mfma_f32_32x32x16_bf16 v[50:65], v[156:159], v[214:217], v[50:65]
	ds_read_b64_tr_b16 v[214:215], v176 offset:0x1400
	ds_read_b64_tr_b16 v[216:217], v176 offset:0x1c00
	s_waitcnt lgkmcnt(4)
	v_mfma_f32_32x32x16_bf16 v[50:65], v[152:155], v[218:221], v[50:65]
	ds_read_b64_tr_b16 v[218:219], v176 offset:0x2400
	ds_read_b64_tr_b16 v[220:221], v176 offset:0x2c00
	v_mfma_f32_32x32x16_bf16 v[50:65], v[186:189], v[222:225], v[50:65]
	ds_read_b64_tr_b16 v[222:223], v176 offset:0x3400
	ds_read_b64_tr_b16 v[224:225], v176 offset:0x3c00
	s_waitcnt lgkmcnt(4)
	v_mfma_f32_32x32x16_bf16 v[34:49], v[146:149], v[210:213], v[34:49]
	ds_read_b64_tr_b16 v[210:211], v176 offset:0x600
	ds_read_b64_tr_b16 v[212:213], v176 offset:0xe00
	v_mfma_f32_32x32x16_bf16 v[34:49], v[156:159], v[214:217], v[34:49]
	ds_read_b64_tr_b16 v[214:215], v176 offset:0x1600
	ds_read_b64_tr_b16 v[216:217], v176 offset:0x1e00
	s_waitcnt lgkmcnt(4)
	v_mfma_f32_32x32x16_bf16 v[34:49], v[152:155], v[218:221], v[34:49]
	ds_read_b64_tr_b16 v[218:219], v176 offset:0x2600
	ds_read_b64_tr_b16 v[220:221], v176 offset:0x2e00
	v_mfma_f32_32x32x16_bf16 v[34:49], v[186:189], v[222:225], v[34:49]
	ds_read_b64_tr_b16 v[222:223], v176 offset:0x3600
	ds_read_b64_tr_b16 v[224:225], v176 offset:0x3e00
	s_waitcnt lgkmcnt(4)
	v_mfma_f32_32x32x16_bf16 v[18:33], v[146:149], v[210:213], v[18:33]
	v_max_f32_e32 v146, v83, v83
	v_max_f32_e32 v147, v82, v82
	v_max_f32_e32 v146, v147, v146
	v_max3_f32 v146, v146, v84, v85
	v_max3_f32 v146, v146, v86, v87
	v_max3_f32 v146, v146, v88, v89
	v_max3_f32 v146, v146, v90, v91
	v_max3_f32 v146, v146, v92, v93
	v_max3_f32 v146, v146, v94, v95
	v_mfma_f32_32x32x16_bf16 v[18:33], v[156:159], v[214:217], v[18:33]
	v_max3_f32 v146, v146, v96, v97
	v_max3_f32 v146, v146, v66, v67
	v_max3_f32 v146, v146, v68, v69
	v_max3_f32 v146, v146, v70, v71
	v_max3_f32 v146, v146, v72, v73
	v_max3_f32 v146, v146, v74, v75
	v_max3_f32 v146, v146, v76, v77
	v_max3_f32 v146, v146, v78, v79
	s_waitcnt lgkmcnt(0)
	v_mfma_f32_32x32x16_bf16 v[18:33], v[152:155], v[218:221], v[18:33]
	v_max3_f32 v146, v146, v80, v81
	v_mov_b32_e32 v147, v146
	s_nop 1
	v_permlane32_swap_b32_e32 v146, v147
	v_max_f32_e32 v147, v147, v147
	v_max_f32_e32 v146, v146, v146
	v_max_f32_e32 v146, v146, v147
	v_sub_f32_e32 v147, v146, v150
	v_cmp_ge_f32_e32 vcc, s63, v147
	v_max_f32_e32 v147, v150, v150
	v_max_f32_e32 v146, v147, v146
	v_mfma_f32_32x32x16_bf16 v[18:33], v[186:189], v[222:225], v[18:33]
	v_sub_f32_e32 v147, v150, v146
	v_mul_f32_e32 v147, 0x3e0293ee, v147
	v_exp_f32_e32 v147, v147
	s_cmp_eq_u64 vcc, exec
	s_cselect_b64 s[8:9], -1, 0
	s_waitcnt vmcnt(4)
	v_cndmask_b32_e64 v209, v147, 1.0, s[8:9]
	v_cmp_gt_f32_e32 vcc, 1.0, v209
	s_cbranch_vccz .LBB0_1006
	s_and_saveexec_b64 s[2:3], s[6:7]
	ds_write_b32 v173, v209 offset:128
	s_or_b64 exec, exec, s[2:3]
	s_waitcnt lgkmcnt(0)
	v_add_u32_e32 v147, s15, v172
	ds_read_b128 v[152:155], v147 offset:224
	ds_read_b128 v[156:159], v147 offset:192
	ds_read_b128 v[186:189], v147 offset:160
	ds_read_b128 v[210:213], v147 offset:128
	s_waitcnt lgkmcnt(3)
	v_pk_mul_f32 v[14:15], v[14:15], v[152:153]
	s_waitcnt lgkmcnt(2)
	v_pk_mul_f32 v[10:11], v[10:11], v[156:157]
	s_waitcnt lgkmcnt(1)
	v_pk_mul_f32 v[6:7], v[6:7], v[186:187]
	v_pk_mul_f32 v[16:17], v[16:17], v[154:155]
	v_pk_mul_f32 v[12:13], v[12:13], v[158:159]
	v_pk_mul_f32 v[8:9], v[8:9], v[188:189]
	s_waitcnt lgkmcnt(0)
	v_pk_mul_f32 v[4:5], v[4:5], v[212:213]
	v_pk_mul_f32 v[2:3], v[2:3], v[210:211]
	v_pk_mul_f32 v[62:63], v[62:63], v[152:153]
	v_pk_mul_f32 v[58:59], v[58:59], v[156:157]
	v_pk_mul_f32 v[54:55], v[54:55], v[186:187]
	v_pk_mul_f32 v[64:65], v[64:65], v[154:155]
	v_pk_mul_f32 v[60:61], v[60:61], v[158:159]
	v_pk_mul_f32 v[56:57], v[56:57], v[188:189]
	v_pk_mul_f32 v[52:53], v[52:53], v[212:213]
	v_pk_mul_f32 v[50:51], v[50:51], v[210:211]
	v_pk_mul_f32 v[46:47], v[46:47], v[152:153]
	v_pk_mul_f32 v[42:43], v[42:43], v[156:157]
	v_pk_mul_f32 v[38:39], v[38:39], v[186:187]
	v_pk_mul_f32 v[48:49], v[48:49], v[154:155]
	v_pk_mul_f32 v[44:45], v[44:45], v[158:159]
	v_pk_mul_f32 v[40:41], v[40:41], v[188:189]
	v_pk_mul_f32 v[36:37], v[36:37], v[212:213]
	v_pk_mul_f32 v[34:35], v[34:35], v[210:211]
	v_pk_mul_f32 v[30:31], v[30:31], v[152:153]
	v_pk_mul_f32 v[26:27], v[26:27], v[156:157]
	v_pk_mul_f32 v[22:23], v[22:23], v[186:187]
	v_pk_mul_f32 v[32:33], v[32:33], v[154:155]
	v_pk_mul_f32 v[28:29], v[28:29], v[158:159]
	v_pk_mul_f32 v[24:25], v[24:25], v[188:189]
	v_pk_mul_f32 v[20:21], v[20:21], v[212:213]
	v_pk_mul_f32 v[18:19], v[18:19], v[210:211]
; __device__ __forceinline__ void partialSM(f32x16& p0, f32x16& p1, float& m_reg, float& mn, float& alpha) {
;     ...
;   float mnC = -mn * C;
; #pragma unroll
;   for (int r = 0; r < 16; ++r) p0[r] = fmaf(p0[r], C, mnC);
; #pragma unroll
;   for (int r = 0; r < 16; ++r) p1[r] = fmaf(p1[r], C, mnC);
; #pragma unroll
;   for (int r = 0; r < 16; ++r) p0[r] = __builtin_amdgcn_exp2f(p0[r]);
; }
; __device__ __forceinline__ void finishSM(f32x16& p0, f32x16& p1, float alpha, float& l_reg, bf16x8& pa0, bf16x8& pa1, bf16x8& pa2, bf16x8& pa3) {
; #pragma unroll
;   for (int r = 0; r < 16; ++r) p1[r] = __builtin_amdgcn_exp2f(p1[r]);
;   float ps = 0;
; #pragma unroll
;   for (int r = 0; r < 16; ++r) ps += p0[r];
; #pragma unroll
;   for (int r = 0; r < 16; ++r) ps += p1[r];
;   { auto rr = __builtin_amdgcn_permlane32_swap(__float_as_uint(ps), __float_as_uint(ps), false, false);
;     ps = __uint_as_float(rr[0]) + __uint_as_float(rr[1]); }
;   l_reg = l_reg * alpha + ps;
;   PK4(p0, 0, pa0); PK4(p0, 8, pa1); PK4(p1, 0, pa2); PK4(p1, 8, pa3);
; }
;   p0 = f32x16{}; p1 = f32x16{};
; #pragma unroll
;   for (int d0 = DLO; d0 < DHI; ++d0) { int cb = (d0 * 16 + hi * 8) * 2;
;     bf16x8 b0 = *reinterpret_cast<const bf16x8*>((const char*)Ks + KSWZ(r32, cb));
;     bf16x8 b1 = *reinterpret_cast<const bf16x8*>((const char*)Ks + KSWZ(32 + r32, cb));
;     p0 = __builtin_amdgcn_mfma_f32_32x32x16_bf16(b0, qr[d0], p0, 0, 0, 0);
;     p1 = __builtin_amdgcn_mfma_f32_32x32x16_bf16(b1, qr[d0], p1, 0, 0, 0); }
; }
.LBB0_1006:
	v_cndmask_b32_e64 v210, v146, v150, s[8:9]
	v_mul_f32_e32 v211, 0xbe0293ee, v210
	v_fmamk_f32 v82, v82, 0x3e0293ee, v211
	v_fmamk_f32 v83, v83, 0x3e0293ee, v211
	v_fmamk_f32 v84, v84, 0x3e0293ee, v211
	v_fmamk_f32 v85, v85, 0x3e0293ee, v211
	v_fmamk_f32 v86, v86, 0x3e0293ee, v211
	v_fmamk_f32 v87, v87, 0x3e0293ee, v211
	v_fmamk_f32 v88, v88, 0x3e0293ee, v211
	v_fmamk_f32 v89, v89, 0x3e0293ee, v211
	v_fmamk_f32 v90, v90, 0x3e0293ee, v211
	v_fmamk_f32 v91, v91, 0x3e0293ee, v211
	v_fmamk_f32 v92, v92, 0x3e0293ee, v211
	v_fmamk_f32 v93, v93, 0x3e0293ee, v211
	v_fmamk_f32 v94, v94, 0x3e0293ee, v211
	v_fmamk_f32 v95, v95, 0x3e0293ee, v211
	v_fmamk_f32 v96, v96, 0x3e0293ee, v211
	v_fmamk_f32 v97, v97, 0x3e0293ee, v211
	v_exp_f32_e32 v146, v82
	v_exp_f32_e32 v161, v83
	v_exp_f32_e32 v147, v84
	v_exp_f32_e32 v160, v85
	v_exp_f32_e32 v148, v86
	v_exp_f32_e32 v159, v87
	v_exp_f32_e32 v149, v88
	v_exp_f32_e32 v158, v89
	v_exp_f32_e32 v150, v90
	v_exp_f32_e32 v157, v91
	v_exp_f32_e32 v151, v92
	v_exp_f32_e32 v156, v93
	v_exp_f32_e32 v152, v94
	v_exp_f32_e32 v155, v95
	v_exp_f32_e32 v153, v96
	v_exp_f32_e32 v154, v97
	v_fmamk_f32 v220, v66, 0x3e0293ee, v211
	v_fmamk_f32 v221, v67, 0x3e0293ee, v211
	v_fmamk_f32 v222, v68, 0x3e0293ee, v211
	v_fmamk_f32 v223, v69, 0x3e0293ee, v211
	v_fmamk_f32 v224, v70, 0x3e0293ee, v211
	v_fmamk_f32 v213, v71, 0x3e0293ee, v211
	v_fmamk_f32 v214, v72, 0x3e0293ee, v211
	v_fmamk_f32 v215, v73, 0x3e0293ee, v211
	v_fmamk_f32 v216, v74, 0x3e0293ee, v211
	v_fmamk_f32 v217, v75, 0x3e0293ee, v211
	v_fmamk_f32 v218, v76, 0x3e0293ee, v211
	v_fmamk_f32 v219, v77, 0x3e0293ee, v211
	v_fmamk_f32 v212, v78, 0x3e0293ee, v211
	v_fmamk_f32 v225, v79, 0x3e0293ee, v211
	v_fmamk_f32 v226, v80, 0x3e0293ee, v211
	v_fmac_f32_e32 v211, 0x3e0293ee, v81
	s_waitcnt lgkmcnt(0)
	s_barrier
	v_xor_b32_e32 v190, 0x10000, v190
	v_xor_b32_e32 v194, 0x10000, v194
	v_xor_b32_e32 v195, 0x10000, v195
	v_xor_b32_e32 v196, 0x10000, v196
	ds_read_b128 v[66:69], v190 offset:32768
	ds_read_b128 v[70:73], v190 offset:40960
	ds_read_b128 v[232:235], v194 offset:32768
	ds_read_b128 v[236:239], v194 offset:40960
	ds_read_b128 v[240:243], v195 offset:32768
	ds_read_b128 v[244:247], v195 offset:40960
	ds_read_b128 v[248:251], v196 offset:32768
	ds_read_b128 v[114:117], v196 offset:40960
	v_exp_f32_e32 v213, v213
	v_exp_f32_e32 v214, v214
	s_waitcnt lgkmcnt(7)
	v_mfma_f32_32x32x16_bf16 v[82:97], v[66:69], v[102:105], 0
	v_exp_f32_e32 v215, v215
	v_exp_f32_e32 v216, v216
	v_exp_f32_e32 v217, v217
	v_exp_f32_e32 v218, v218
	v_exp_f32_e32 v219, v219
	s_waitcnt lgkmcnt(6)
	v_mfma_f32_32x32x16_bf16 v[66:81], v[70:73], v[102:105], 0
	s_waitcnt lgkmcnt(5)
	v_mfma_f32_32x32x16_bf16 v[82:97], v[232:235], v[98:101], v[82:97]
	s_waitcnt lgkmcnt(4)
	v_mfma_f32_32x32x16_bf16 v[66:81], v[236:239], v[98:101], v[66:81]
	s_waitcnt lgkmcnt(3)
	v_mfma_f32_32x32x16_bf16 v[82:97], v[240:243], v[106:109], v[82:97]
	s_waitcnt lgkmcnt(2)
	v_mfma_f32_32x32x16_bf16 v[66:81], v[244:247], v[106:109], v[66:81]
	s_waitcnt lgkmcnt(1)
	v_mfma_f32_32x32x16_bf16 v[82:97], v[248:251], v[110:113], v[82:97]
	v_exp_f32_e32 v186, v220
	v_exp_f32_e32 v220, v224
	v_exp_f32_e32 v224, v211
	v_add_f32_e32 v211, 0, v146
	v_add_f32_e32 v211, v161, v211
	v_add_f32_e32 v211, v147, v211
	v_add_f32_e32 v211, v160, v211
	v_add_f32_e32 v211, v148, v211
	v_add_f32_e32 v211, v159, v211
	v_add_f32_e32 v211, v149, v211
	v_add_f32_e32 v211, v158, v211
	v_add_f32_e32 v211, v150, v211
	v_add_f32_e32 v211, v157, v211
	v_add_f32_e32 v211, v151, v211
	v_add_f32_e32 v211, v156, v211
	v_add_f32_e32 v211, v152, v211
	v_exp_f32_e32 v187, v221
	v_add_f32_e32 v211, v155, v211
	v_exp_f32_e32 v188, v222
	v_add_f32_e32 v211, v153, v211
	v_exp_f32_e32 v189, v223
	v_add_f32_e32 v211, v154, v211
	v_add_f32_e32 v211, v186, v211
	v_add_f32_e32 v211, v187, v211
	v_add_f32_e32 v211, v188, v211
	v_add_f32_e32 v211, v189, v211
	v_add_f32_e32 v211, v220, v211
	v_add_f32_e32 v211, v213, v211
	v_add_f32_e32 v211, v214, v211
	v_add_f32_e32 v211, v215, v211
	v_exp_f32_e32 v221, v212
	v_add_f32_e32 v211, v216, v211
	v_exp_f32_e32 v222, v225
	v_add_f32_e32 v211, v217, v211
	s_waitcnt lgkmcnt(0)
	v_mfma_f32_32x32x16_bf16 v[66:81], v[114:117], v[110:113], v[66:81]
	v_exp_f32_e32 v223, v226
	v_add_f32_e32 v211, v218, v211
	v_add_f32_e32 v211, v219, v211
	v_add_f32_e32 v211, v221, v211
	v_add_f32_e32 v211, v222, v211
	v_add_f32_e32 v211, v223, v211
	v_add_f32_e32 v211, v224, v211
	v_mov_b32_e32 v212, v211
	v_cvt_pk_bf16_f32 v146, v146, v161
	v_cvt_pk_bf16_f32 v147, v147, v160
	v_cvt_pk_bf16_f32 v148, v148, v159
	v_cvt_pk_bf16_f32 v149, v149, v158
	v_cvt_pk_bf16_f32 v150, v150, v157
	v_cvt_pk_bf16_f32 v151, v151, v156
	v_cvt_pk_bf16_f32 v152, v152, v155
	v_cvt_pk_bf16_f32 v153, v153, v154
	v_cvt_pk_bf16_f32 v154, v186, v187
	v_cvt_pk_bf16_f32 v155, v188, v189
	v_cvt_pk_bf16_f32 v156, v220, v213
	v_cvt_pk_bf16_f32 v157, v214, v215
	v_cvt_pk_bf16_f32 v158, v216, v217
	v_cvt_pk_bf16_f32 v159, v218, v219
	v_cvt_pk_bf16_f32 v160, v221, v222
	v_cvt_pk_bf16_f32 v161, v223, v224
	s_nop 1
	v_permlane32_swap_b32_e32 v211, v212
	v_permlane32_swap_b32_e32 v146, v148
	v_permlane32_swap_b32_e32 v147, v149
	v_permlane32_swap_b32_e32 v150, v152
	v_permlane32_swap_b32_e32 v151, v153
	v_permlane32_swap_b32_e32 v154, v156
	v_permlane32_swap_b32_e32 v155, v157
	v_permlane32_swap_b32_e32 v158, v160
	v_permlane32_swap_b32_e32 v159, v161
	s_waitcnt vmcnt(0)
	ds_write_b128 v192, v[130:133] offset:16384
	ds_write_b128 v193, v[134:137] offset:16384
	ds_write_b128 v177, v[138:141] offset:49152
	ds_write_b128 v191, v[142:145] offset:49152
	s_cmp_gt_u32 s34, 60
	s_cselect_b64 s[2:3], -1, 0
	s_and_b64 vcc, exec, s[2:3]
	s_cbranch_vccnz .LBB0_1008
	v_add_co_u32_e32 v114, vcc, 0x19040000, v168
	s_nop 1
	v_addc_co_u32_e32 v115, vcc, 0, v169, vcc
	v_add_co_u32_e32 v118, vcc, 0x19088000, v168
	s_nop 1
	v_addc_co_u32_e32 v119, vcc, 0, v169, vcc
	v_add_co_u32_e32 v122, vcc, 0x1f660000, v166
	global_load_dwordx4 v[114:117], v[114:115], off
	s_nop 0
	global_load_dwordx4 v[118:121], v[118:119], off
	v_addc_co_u32_e32 v123, vcc, 0, v167, vcc
	v_add_co_u32_e32 v126, vcc, 0x1f66c000, v166
	s_nop 1
	v_addc_co_u32_e32 v127, vcc, 0, v167, vcc
	global_load_dwordx4 v[122:125], v[122:123], off
	s_nop 0
	global_load_dwordx4 v[126:129], v[126:127], off

; __device__ __forceinline__ void finishSM(f32x16& p0, f32x16& p1, float alpha, float& l_reg, bf16x8& pa0, bf16x8& pa1, bf16x8& pa2, bf16x8& pa3) {
; #pragma unroll
;   for (int r = 0; r < 16; ++r) p1[r] = __builtin_amdgcn_exp2f(p1[r]);
;   float ps = 0;
; #pragma unroll
;   for (int r = 0; r < 16; ++r) ps += p0[r];
; #pragma unroll
;   for (int r = 0; r < 16; ++r) ps += p1[r];
;   { auto rr = __builtin_amdgcn_permlane32_swap(__float_as_uint(ps), __float_as_uint(ps), false, false);
;     ps = __uint_as_float(rr[0]) + __uint_as_float(rr[1]); }
;   l_reg = l_reg * alpha + ps;
;   PK4(p0, 0, pa0); PK4(p0, 8, pa1); PK4(p1, 0, pa2); PK4(p1, 8, pa3);
; }
;   p0 = f32x16{}; p1 = f32x16{};
; #pragma unroll
;   for (int d0 = DLO; d0 < DHI; ++d0) { int cb = (d0 * 16 + hi * 8) * 2;
;     bf16x8 b0 = *reinterpret_cast<const bf16x8*>((const char*)Ks + KSWZ(r32, cb));
;     bf16x8 b1 = *reinterpret_cast<const bf16x8*>((const char*)Ks + KSWZ(32 + r32, cb));
;     p0 = __builtin_amdgcn_mfma_f32_32x32x16_bf16(b0, qr[d0], p0, 0, 0, 0);
;     p1 = __builtin_amdgcn_mfma_f32_32x32x16_bf16(b1, qr[d0], p1, 0, 0, 0); }
; }
; __device__ __forceinline__ int v_st(int k, int c) { const int kk = (k & ~0xC) | ((k & 4) << 1) | ((k & 8) >> 1); return ((kk >> 3) * 4 + (c >> 5)) * 512 + ((kk & 7) * 32 + (c & 31)) * 2; }
; __device__ __forceinline__ int v_rd_base(int lane) { return ((lane & 3) << 3) | (((lane >> 2) & 3) << 6) | (((lane >> 4) & 1) << 5) | (((lane >> 5) & 1) << 8); }
; template <int OFF> __device__ __forceinline__ s16x4 tr_read(int vb) {
;   s16x4 r; asm volatile("ds_read_b64_tr_b16 %0, %1 offset:%2" : "=&v"(r) : "v"(vb), "i"(OFF) : "memory"); return r;
; }
; template <int D0> __device__ __forceinline__ void pv_one(f32x16& od, int vb, bf16x8 pa0, bf16x8 pa1, bf16x8 pa2, bf16x8 pa3) {
;   const s16x4 l0 = tr_read<v_rd_off(D0, 0, 0)>(vb), h0 = tr_read<v_rd_off(D0, 0, 1)>(vb), l1 = tr_read<v_rd_off(D0, 1, 0)>(vb), h1 = tr_read<v_rd_off(D0, 1, 1)>(vb);
;   const s16x4 l2 = tr_read<v_rd_off(D0, 2, 0)>(vb), h2 = tr_read<v_rd_off(D0, 2, 1)>(vb), l3 = tr_read<v_rd_off(D0, 3, 0)>(vb), h3 = tr_read<v_rd_off(D0, 3, 1)>(vb);
;   asm volatile("s_waitcnt lgkmcnt(0)" ::: "memory"); SBAR();
;     ...
;   od = __builtin_amdgcn_mfma_f32_32x32x16_bf16(pa0, PK(l0, h0), od, 0, 0, 0);
;   od = __builtin_amdgcn_mfma_f32_32x32x16_bf16(pa1, PK(l1, h1), od, 0, 0, 0);
.LBB0_1022:
	ds_read_b128 v[66:69], v177 offset:49152
	ds_read_b128 v[70:73], v177 offset:57344
	ds_read_b128 v[186:189], v194 offset:49152
	ds_read_b128 v[208:211], v194 offset:57344
	ds_read_b128 v[232:235], v195 offset:49152
	ds_read_b128 v[236:239], v195 offset:57344
	ds_read_b128 v[240:243], v196 offset:49152
	ds_read_b128 v[244:247], v196 offset:57344
	v_add_f32_e32 v146, 0, v161
	v_add_f32_e32 v146, v167, v146
	v_add_f32_e32 v146, v147, v146
	s_waitcnt lgkmcnt(7)
	v_mfma_f32_32x32x16_bf16 v[82:97], v[66:69], v[102:105], 0
	v_add_f32_e32 v146, v166, v146
	v_add_f32_e32 v146, v148, v146
	v_add_f32_e32 v146, v160, v146
	v_add_f32_e32 v146, v149, v146
	v_add_f32_e32 v146, v159, v146
	v_add_f32_e32 v146, v156, v146
	s_waitcnt lgkmcnt(6)
	v_mfma_f32_32x32x16_bf16 v[66:81], v[70:73], v[102:105], 0
	v_add_f32_e32 v146, v158, v146
	v_add_f32_e32 v146, v154, v146
	v_add_f32_e32 v146, v157, v146
	v_exp_f32_e32 v142, v142
	v_add_f32_e32 v146, v152, v146
	v_exp_f32_e32 v143, v143
	v_add_f32_e32 v146, v155, v146
	s_waitcnt lgkmcnt(5)
	v_mfma_f32_32x32x16_bf16 v[82:97], v[186:189], v[98:101], v[82:97]
	v_exp_f32_e32 v140, v140
	v_add_f32_e32 v146, v151, v146
	v_exp_f32_e32 v141, v141
	v_add_f32_e32 v146, v153, v146
	v_exp_f32_e32 v134, v134
	v_add_f32_e32 v146, v142, v146
	v_exp_f32_e32 v135, v135
	s_waitcnt lgkmcnt(4)
	v_mfma_f32_32x32x16_bf16 v[66:81], v[208:211], v[98:101], v[66:81]
	v_add_f32_e32 v146, v143, v146
	v_exp_f32_e32 v132, v132
	v_add_f32_e32 v146, v140, v146
	v_exp_f32_e32 v133, v133
	v_add_f32_e32 v146, v141, v146
	v_exp_f32_e32 v130, v130
	s_waitcnt lgkmcnt(3)
	v_mfma_f32_32x32x16_bf16 v[82:97], v[232:235], v[106:109], v[82:97]
	v_add_f32_e32 v146, v134, v146
	v_exp_f32_e32 v131, v131
	v_add_f32_e32 v146, v135, v146
	v_exp_f32_e32 v144, v144
	v_add_f32_e32 v146, v132, v146
	v_exp_f32_e32 v145, v145
	v_add_f32_e32 v146, v133, v146
	s_waitcnt lgkmcnt(2)
	v_mfma_f32_32x32x16_bf16 v[66:81], v[236:239], v[106:109], v[66:81]
	v_exp_f32_e32 v138, v138
	v_add_f32_e32 v146, v130, v146
	v_exp_f32_e32 v139, v139
	v_add_f32_e32 v146, v131, v146
	v_exp_f32_e32 v136, v136
	v_add_f32_e32 v146, v144, v146
	s_waitcnt lgkmcnt(1)
	v_mfma_f32_32x32x16_bf16 v[82:97], v[240:243], v[110:113], v[82:97]
	v_exp_f32_e32 v137, v137
	v_add_f32_e32 v146, v145, v146
	v_add_f32_e32 v146, v138, v146
	v_add_f32_e32 v146, v139, v146
	v_add_f32_e32 v146, v136, v146
	v_add_f32_e32 v207, v137, v146
	v_cvt_pk_bf16_f32 v146, v161, v167
	s_waitcnt lgkmcnt(0)
	v_mfma_f32_32x32x16_bf16 v[66:81], v[244:247], v[110:113], v[66:81]
	v_mov_b32_e32 v208, v207
	v_cvt_pk_bf16_f32 v147, v147, v166
	v_cvt_pk_bf16_f32 v148, v148, v160
	s_nop 1
	v_permlane32_swap_b32_e32 v207, v208
	v_cvt_pk_bf16_f32 v149, v149, v159
	v_permlane32_swap_b32_e32 v146, v148
	v_cvt_pk_bf16_f32 v156, v156, v158
	v_cvt_pk_bf16_f32 v157, v154, v157
	v_cvt_pk_bf16_f32 v158, v152, v155
	v_cvt_pk_bf16_f32 v159, v151, v153
	v_cvt_pk_bf16_f32 v152, v142, v143
	v_cvt_pk_bf16_f32 v153, v140, v141
	v_cvt_pk_bf16_f32 v154, v134, v135
	v_cvt_pk_bf16_f32 v155, v132, v133
	v_cvt_pk_bf16_f32 v186, v130, v131
	v_cvt_pk_bf16_f32 v187, v144, v145
	v_cvt_pk_bf16_f32 v188, v138, v139
	v_cvt_pk_bf16_f32 v189, v136, v137
	v_permlane32_swap_b32_e32 v147, v149
	v_permlane32_swap_b32_e32 v156, v158
	v_permlane32_swap_b32_e32 v157, v159
	v_permlane32_swap_b32_e32 v152, v154
	v_permlane32_swap_b32_e32 v153, v155
	v_permlane32_swap_b32_e32 v186, v188
	v_permlane32_swap_b32_e32 v187, v189
	s_waitcnt vmcnt(0)
	ds_write_b128 v192, v[114:117]
	ds_write_b128 v193, v[118:121]
	ds_write_b128 v190, v[122:125] offset:32768
	ds_write_b128 v191, v[126:129] offset:32768
	v_lshl_add_u64 v[168:169], v[164:165], 0, v[0:1]
	s_mov_b32 s1, 0x18fb0000
	v_add_co_u32_e32 v130, vcc, s1, v168
	s_mov_b32 s1, 0x18ff8000
	s_nop 0
	v_addc_co_u32_e32 v131, vcc, 0, v169, vcc
	v_add_co_u32_e32 v134, vcc, s1, v168
	v_lshl_add_u64 v[166:167], v[162:163], 0, v[0:1]
	s_nop 0
	v_addc_co_u32_e32 v135, vcc, 0, v169, vcc
	s_mov_b32 s1, 0x1f648000
	v_add_co_u32_e32 v138, vcc, s1, v166
	s_mov_b32 s1, 0x1f654000
	s_nop 0
	v_addc_co_u32_e32 v139, vcc, 0, v167, vcc
	v_add_co_u32_e32 v142, vcc, s1, v166
	global_load_dwordx4 v[130:133], v[130:131], off
	s_nop 0
	global_load_dwordx4 v[134:137], v[134:135], off
	v_addc_co_u32_e32 v143, vcc, 0, v167, vcc
	global_load_dwordx4 v[138:141], v[138:139], off
	s_nop 0
	global_load_dwordx4 v[142:145], v[142:143], off
	ds_read_b64_tr_b16 v[210:211], v176 offset:0
	ds_read_b64_tr_b16 v[212:213], v176 offset:0x800
	ds_read_b64_tr_b16 v[214:215], v176 offset:0x1000
	ds_read_b64_tr_b16 v[216:217], v176 offset:0x1800
	ds_read_b64_tr_b16 v[218:219], v176 offset:0x2000
	ds_read_b64_tr_b16 v[220:221], v176 offset:0x2800
	ds_read_b64_tr_b16 v[222:223], v176 offset:0x3000
	ds_read_b64_tr_b16 v[224:225], v176 offset:0x3800
	s_waitcnt lgkmcnt(4)
	s_nop 0
	v_mfma_f32_32x32x16_bf16 v[2:17], v[146:149], v[210:213], v[2:17]
	ds_read_b64_tr_b16 v[210:211], v176 offset:0x200
	ds_read_b64_tr_b16 v[212:213], v176 offset:0xa00
	v_mfma_f32_32x32x16_bf16 v[2:17], v[156:159], v[214:217], v[2:17]
	ds_read_b64_tr_b16 v[214:215], v176 offset:0x1200
	ds_read_b64_tr_b16 v[216:217], v176 offset:0x1a00
	s_waitcnt lgkmcnt(4)
	v_mfma_f32_32x32x16_bf16 v[2:17], v[152:155], v[218:221], v[2:17]
	ds_read_b64_tr_b16 v[218:219], v176 offset:0x2200
	ds_read_b64_tr_b16 v[220:221], v176 offset:0x2a00
	v_mfma_f32_32x32x16_bf16 v[2:17], v[186:189], v[222:225], v[2:17]
	ds_read_b64_tr_b16 v[222:223], v176 offset:0x3200
	ds_read_b64_tr_b16 v[224:225], v176 offset:0x3a00
	s_waitcnt lgkmcnt(4)
; __device__ __forceinline__ void partialSM(f32x16& p0, f32x16& p1, float& m_reg, float& mn, float& alpha) {
;   constexpr float C = SCALE * 1.4426950408889634f;
;   float pmax = p0[0];
; #pragma unroll
;   for (int r = 1; r < 16; ++r) pmax = fmaxf(pmax, p0[r]);
; #pragma unroll
;   for (int r = 0; r < 16; ++r) pmax = fmaxf(pmax, p1[r]);
;   { auto rr = __builtin_amdgcn_permlane32_swap(__float_as_uint(pmax), __float_as_uint(pmax), false, false);
;     pmax = fmaxf(__uint_as_float(rr[0]), __uint_as_float(rr[1])); }
;   if (__builtin_expect(__all(pmax - m_reg <= THR / SCALE), 1)) { mn = m_reg; alpha = 1.f; }
;   else { mn = fmaxf(m_reg, pmax); alpha = __builtin_amdgcn_exp2f((m_reg - mn) * C); m_reg = mn; }
	v_mfma_f32_32x32x16_bf16 v[50:65], v[146:149], v[210:213], v[50:65]
	ds_read_b64_tr_b16 v[210:211], v176 offset:0x400
	ds_read_b64_tr_b16 v[212:213], v176 offset:0xc00
	v_mfma_f32_32x32x16_bf16 v[50:65], v[156:159], v[214:217], v[50:65]
	ds_read_b64_tr_b16 v[214:215], v176 offset:0x1400
	ds_read_b64_tr_b16 v[216:217], v176 offset:0x1c00
	s_waitcnt lgkmcnt(4)
	v_mfma_f32_32x32x16_bf16 v[50:65], v[152:155], v[218:221], v[50:65]
	ds_read_b64_tr_b16 v[218:219], v176 offset:0x2400
	ds_read_b64_tr_b16 v[220:221], v176 offset:0x2c00
	v_mfma_f32_32x32x16_bf16 v[50:65], v[186:189], v[222:225], v[50:65]
	ds_read_b64_tr_b16 v[222:223], v176 offset:0x3400
	ds_read_b64_tr_b16 v[224:225], v176 offset:0x3c00
	s_waitcnt lgkmcnt(4)
	v_mfma_f32_32x32x16_bf16 v[34:49], v[146:149], v[210:213], v[34:49]
	ds_read_b64_tr_b16 v[210:211], v176 offset:0x600
	ds_read_b64_tr_b16 v[212:213], v176 offset:0xe00
	v_mfma_f32_32x32x16_bf16 v[34:49], v[156:159], v[214:217], v[34:49]
	ds_read_b64_tr_b16 v[214:215], v176 offset:0x1600
	ds_read_b64_tr_b16 v[216:217], v176 offset:0x1e00
	s_waitcnt lgkmcnt(4)
	v_mfma_f32_32x32x16_bf16 v[34:49], v[152:155], v[218:221], v[34:49]
	ds_read_b64_tr_b16 v[218:219], v176 offset:0x2600
	ds_read_b64_tr_b16 v[220:221], v176 offset:0x2e00
	v_mfma_f32_32x32x16_bf16 v[34:49], v[186:189], v[222:225], v[34:49]
	ds_read_b64_tr_b16 v[222:223], v176 offset:0x3600
	ds_read_b64_tr_b16 v[224:225], v176 offset:0x3e00
	s_waitcnt lgkmcnt(4)
	v_mfma_f32_32x32x16_bf16 v[18:33], v[146:149], v[210:213], v[18:33]
	v_max_f32_e32 v146, v83, v83
	v_max_f32_e32 v147, v82, v82
	v_max_f32_e32 v146, v147, v146
	v_max3_f32 v146, v146, v84, v85
	v_max3_f32 v146, v146, v86, v87
	v_max3_f32 v146, v146, v88, v89
	v_max3_f32 v146, v146, v90, v91
	v_max3_f32 v146, v146, v92, v93
	v_max3_f32 v146, v146, v94, v95
	v_mfma_f32_32x32x16_bf16 v[18:33], v[156:159], v[214:217], v[18:33]
	v_max3_f32 v146, v146, v96, v97
	v_max3_f32 v146, v146, v66, v67
	v_max3_f32 v146, v146, v68, v69
	v_max3_f32 v146, v146, v70, v71
	v_max3_f32 v146, v146, v72, v73
	v_max3_f32 v146, v146, v74, v75
	v_max3_f32 v146, v146, v76, v77
	v_max3_f32 v146, v146, v78, v79
	s_waitcnt lgkmcnt(0)
	v_mfma_f32_32x32x16_bf16 v[18:33], v[152:155], v[218:221], v[18:33]
	v_max3_f32 v146, v146, v80, v81
	v_mov_b32_e32 v147, v146
	s_nop 1
	v_permlane32_swap_b32_e32 v146, v147
	v_max_f32_e32 v147, v147, v147
	v_max_f32_e32 v146, v146, v146
	v_max_f32_e32 v146, v146, v147
	v_sub_f32_e32 v147, v146, v150
	v_cmp_ge_f32_e32 vcc, s63, v147
	v_max_f32_e32 v147, v150, v150
	v_max_f32_e32 v146, v147, v146
	v_mfma_f32_32x32x16_bf16 v[18:33], v[186:189], v[222:225], v[18:33]
	v_sub_f32_e32 v147, v150, v146
	v_mul_f32_e32 v147, 0x3e0293ee, v147
	v_exp_f32_e32 v147, v147
	s_cmp_eq_u64 vcc, exec
	s_cselect_b64 s[8:9], -1, 0
	s_waitcnt vmcnt(4)
	v_cndmask_b32_e64 v209, v147, 1.0, s[8:9]
	v_cmp_gt_f32_e32 vcc, 1.0, v209
	s_cbranch_vccz .LBB0_1026
	s_and_saveexec_b64 s[2:3], s[6:7]
	ds_write_b32 v173, v209 offset:128
	s_or_b64 exec, exec, s[2:3]
	s_waitcnt lgkmcnt(0)
	v_add_u32_e32 v147, s15, v172
	ds_read_b128 v[152:155], v147 offset:224
	ds_read_b128 v[156:159], v147 offset:192
	ds_read_b128 v[186:189], v147 offset:160
	ds_read_b128 v[210:213], v147 offset:128
	s_waitcnt lgkmcnt(3)
	v_pk_mul_f32 v[14:15], v[14:15], v[152:153]
	s_waitcnt lgkmcnt(2)
	v_pk_mul_f32 v[10:11], v[10:11], v[156:157]
	s_waitcnt lgkmcnt(1)
	v_pk_mul_f32 v[6:7], v[6:7], v[186:187]
	v_pk_mul_f32 v[16:17], v[16:17], v[154:155]
	v_pk_mul_f32 v[12:13], v[12:13], v[158:159]
	v_pk_mul_f32 v[8:9], v[8:9], v[188:189]
	s_waitcnt lgkmcnt(0)
	v_pk_mul_f32 v[4:5], v[4:5], v[212:213]
	v_pk_mul_f32 v[2:3], v[2:3], v[210:211]
	v_pk_mul_f32 v[62:63], v[62:63], v[152:153]
	v_pk_mul_f32 v[58:59], v[58:59], v[156:157]
	v_pk_mul_f32 v[54:55], v[54:55], v[186:187]
	v_pk_mul_f32 v[64:65], v[64:65], v[154:155]
	v_pk_mul_f32 v[60:61], v[60:61], v[158:159]
	v_pk_mul_f32 v[56:57], v[56:57], v[188:189]
	v_pk_mul_f32 v[52:53], v[52:53], v[212:213]
	v_pk_mul_f32 v[50:51], v[50:51], v[210:211]
	v_pk_mul_f32 v[46:47], v[46:47], v[152:153]
	v_pk_mul_f32 v[42:43], v[42:43], v[156:157]
	v_pk_mul_f32 v[38:39], v[38:39], v[186:187]
	v_pk_mul_f32 v[48:49], v[48:49], v[154:155]
	v_pk_mul_f32 v[44:45], v[44:45], v[158:159]
	v_pk_mul_f32 v[40:41], v[40:41], v[188:189]
	v_pk_mul_f32 v[36:37], v[36:37], v[212:213]
	v_pk_mul_f32 v[34:35], v[34:35], v[210:211]
	v_pk_mul_f32 v[30:31], v[30:31], v[152:153]
	v_pk_mul_f32 v[26:27], v[26:27], v[156:157]
	v_pk_mul_f32 v[22:23], v[22:23], v[186:187]
	v_pk_mul_f32 v[32:33], v[32:33], v[154:155]
	v_pk_mul_f32 v[28:29], v[28:29], v[158:159]
	v_pk_mul_f32 v[24:25], v[24:25], v[188:189]
	v_pk_mul_f32 v[20:21], v[20:21], v[212:213]
	v_pk_mul_f32 v[18:19], v[18:19], v[210:211]
; __device__ __forceinline__ void partialSM(f32x16& p0, f32x16& p1, float& m_reg, float& mn, float& alpha) {
;     ...
;   float mnC = -mn * C;
; #pragma unroll
;   for (int r = 0; r < 16; ++r) p0[r] = fmaf(p0[r], C, mnC);
; #pragma unroll
;   for (int r = 0; r < 16; ++r) p1[r] = fmaf(p1[r], C, mnC);
; #pragma unroll
;   for (int r = 0; r < 16; ++r) p0[r] = __builtin_amdgcn_exp2f(p0[r]);
; }
; __device__ __forceinline__ void finishSM(f32x16& p0, f32x16& p1, float alpha, float& l_reg, bf16x8& pa0, bf16x8& pa1, bf16x8& pa2, bf16x8& pa3) {
; #pragma unroll
;   for (int r = 0; r < 16; ++r) p1[r] = __builtin_amdgcn_exp2f(p1[r]);
;   float ps = 0;
; #pragma unroll
;   for (int r = 0; r < 16; ++r) ps += p0[r];
; #pragma unroll
;   for (int r = 0; r < 16; ++r) ps += p1[r];
;   { auto rr = __builtin_amdgcn_permlane32_swap(__float_as_uint(ps), __float_as_uint(ps), false, false);
;     ps = __uint_as_float(rr[0]) + __uint_as_float(rr[1]); }
;   l_reg = l_reg * alpha + ps;
;   PK4(p0, 0, pa0); PK4(p0, 8, pa1); PK4(p1, 0, pa2); PK4(p1, 8, pa3);
; }
;   p0 = f32x16{}; p1 = f32x16{};
; #pragma unroll
;   for (int d0 = DLO; d0 < DHI; ++d0) { int cb = (d0 * 16 + hi * 8) * 2;
;     bf16x8 b0 = *reinterpret_cast<const bf16x8*>((const char*)Ks + KSWZ(r32, cb));
;     bf16x8 b1 = *reinterpret_cast<const bf16x8*>((const char*)Ks + KSWZ(32 + r32, cb));
;     p0 = __builtin_amdgcn_mfma_f32_32x32x16_bf16(b0, qr[d0], p0, 0, 0, 0);
;     p1 = __builtin_amdgcn_mfma_f32_32x32x16_bf16(b1, qr[d0], p1, 0, 0, 0); }
; }
.LBB0_1026:
	v_cndmask_b32_e64 v210, v146, v150, s[8:9]
	v_mul_f32_e32 v211, 0xbe0293ee, v210
	v_fmamk_f32 v82, v82, 0x3e0293ee, v211
	v_fmamk_f32 v83, v83, 0x3e0293ee, v211
	v_fmamk_f32 v84, v84, 0x3e0293ee, v211
	v_fmamk_f32 v85, v85, 0x3e0293ee, v211
	v_fmamk_f32 v86, v86, 0x3e0293ee, v211
	v_fmamk_f32 v87, v87, 0x3e0293ee, v211
	v_fmamk_f32 v88, v88, 0x3e0293ee, v211
	v_fmamk_f32 v89, v89, 0x3e0293ee, v211
	v_fmamk_f32 v90, v90, 0x3e0293ee, v211
	v_fmamk_f32 v91, v91, 0x3e0293ee, v211
	v_fmamk_f32 v92, v92, 0x3e0293ee, v211
	v_fmamk_f32 v93, v93, 0x3e0293ee, v211
	v_fmamk_f32 v94, v94, 0x3e0293ee, v211
	v_fmamk_f32 v95, v95, 0x3e0293ee, v211
	v_fmamk_f32 v96, v96, 0x3e0293ee, v211
	v_fmamk_f32 v97, v97, 0x3e0293ee, v211
	v_exp_f32_e32 v146, v82
	v_exp_f32_e32 v161, v83
	v_exp_f32_e32 v147, v84
	v_exp_f32_e32 v160, v85
	v_exp_f32_e32 v148, v86
	v_exp_f32_e32 v159, v87
	v_exp_f32_e32 v149, v88
	v_exp_f32_e32 v158, v89
	v_exp_f32_e32 v150, v90
	v_exp_f32_e32 v157, v91
	v_exp_f32_e32 v151, v92
	v_exp_f32_e32 v156, v93
	v_exp_f32_e32 v152, v94
	v_exp_f32_e32 v155, v95
	v_exp_f32_e32 v153, v96
	v_exp_f32_e32 v154, v97
	v_fmamk_f32 v220, v66, 0x3e0293ee, v211
	v_fmamk_f32 v221, v67, 0x3e0293ee, v211
	v_fmamk_f32 v222, v68, 0x3e0293ee, v211
	v_fmamk_f32 v223, v69, 0x3e0293ee, v211
	v_fmamk_f32 v224, v70, 0x3e0293ee, v211
	v_fmamk_f32 v213, v71, 0x3e0293ee, v211
	v_fmamk_f32 v214, v72, 0x3e0293ee, v211
	v_fmamk_f32 v215, v73, 0x3e0293ee, v211
	v_fmamk_f32 v216, v74, 0x3e0293ee, v211
	v_fmamk_f32 v217, v75, 0x3e0293ee, v211
	v_fmamk_f32 v218, v76, 0x3e0293ee, v211
	v_fmamk_f32 v219, v77, 0x3e0293ee, v211
	v_fmamk_f32 v212, v78, 0x3e0293ee, v211
	v_fmamk_f32 v225, v79, 0x3e0293ee, v211
	v_fmamk_f32 v226, v80, 0x3e0293ee, v211
	v_fmac_f32_e32 v211, 0x3e0293ee, v81
	s_waitcnt lgkmcnt(0)
	s_barrier
	v_xor_b32_e32 v177, 0x10000, v177
	v_xor_b32_e32 v194, 0x10000, v194
	v_xor_b32_e32 v195, 0x10000, v195
	v_xor_b32_e32 v196, 0x10000, v196
	ds_read_b128 v[66:69], v177 offset:32768
	ds_read_b128 v[70:73], v177 offset:40960
	ds_read_b128 v[232:235], v194 offset:32768
	ds_read_b128 v[236:239], v194 offset:40960
	ds_read_b128 v[240:243], v195 offset:32768
	ds_read_b128 v[244:247], v195 offset:40960
	ds_read_b128 v[248:251], v196 offset:32768
	ds_read_b128 v[114:117], v196 offset:40960
	v_exp_f32_e32 v213, v213
	v_exp_f32_e32 v214, v214
	s_waitcnt lgkmcnt(7)
	v_mfma_f32_32x32x16_bf16 v[82:97], v[66:69], v[102:105], 0
	v_exp_f32_e32 v215, v215
	v_exp_f32_e32 v216, v216
	v_exp_f32_e32 v217, v217
	v_exp_f32_e32 v218, v218
	v_exp_f32_e32 v219, v219
	s_waitcnt lgkmcnt(6)
	v_mfma_f32_32x32x16_bf16 v[66:81], v[70:73], v[102:105], 0
	s_waitcnt lgkmcnt(5)
	v_mfma_f32_32x32x16_bf16 v[82:97], v[232:235], v[98:101], v[82:97]
	s_waitcnt lgkmcnt(4)
	v_mfma_f32_32x32x16_bf16 v[66:81], v[236:239], v[98:101], v[66:81]
	s_waitcnt lgkmcnt(3)
	v_mfma_f32_32x32x16_bf16 v[82:97], v[240:243], v[106:109], v[82:97]
	s_waitcnt lgkmcnt(2)
	v_mfma_f32_32x32x16_bf16 v[66:81], v[244:247], v[106:109], v[66:81]
	s_waitcnt lgkmcnt(1)
	v_mfma_f32_32x32x16_bf16 v[82:97], v[248:251], v[110:113], v[82:97]
	v_exp_f32_e32 v186, v220
	v_exp_f32_e32 v220, v224
	v_exp_f32_e32 v224, v211
	v_add_f32_e32 v211, 0, v146
	v_add_f32_e32 v211, v161, v211
	v_add_f32_e32 v211, v147, v211
	v_add_f32_e32 v211, v160, v211
	v_add_f32_e32 v211, v148, v211
	v_add_f32_e32 v211, v159, v211
	v_add_f32_e32 v211, v149, v211
	v_add_f32_e32 v211, v158, v211
	v_add_f32_e32 v211, v150, v211
	v_add_f32_e32 v211, v157, v211
	v_add_f32_e32 v211, v151, v211
	v_add_f32_e32 v211, v156, v211
	v_add_f32_e32 v211, v152, v211
	v_exp_f32_e32 v187, v221
	v_add_f32_e32 v211, v155, v211
	v_exp_f32_e32 v188, v222
	v_add_f32_e32 v211, v153, v211
	v_exp_f32_e32 v189, v223
	v_add_f32_e32 v211, v154, v211
	v_add_f32_e32 v211, v186, v211
	v_add_f32_e32 v211, v187, v211
	v_add_f32_e32 v211, v188, v211
	v_add_f32_e32 v211, v189, v211
	v_add_f32_e32 v211, v220, v211
	v_add_f32_e32 v211, v213, v211
	v_add_f32_e32 v211, v214, v211
	v_add_f32_e32 v211, v215, v211
	v_exp_f32_e32 v221, v212
	v_add_f32_e32 v211, v216, v211
	v_exp_f32_e32 v222, v225
	v_add_f32_e32 v211, v217, v211
	s_waitcnt lgkmcnt(0)
	v_mfma_f32_32x32x16_bf16 v[66:81], v[114:117], v[110:113], v[66:81]
	v_exp_f32_e32 v223, v226
	v_add_f32_e32 v211, v218, v211
	v_add_f32_e32 v211, v219, v211
	v_add_f32_e32 v211, v221, v211
	v_add_f32_e32 v211, v222, v211
	v_add_f32_e32 v211, v223, v211
	v_add_f32_e32 v211, v224, v211
	v_mov_b32_e32 v212, v211
	v_cvt_pk_bf16_f32 v146, v146, v161
	v_cvt_pk_bf16_f32 v147, v147, v160
	v_cvt_pk_bf16_f32 v148, v148, v159
	v_cvt_pk_bf16_f32 v149, v149, v158
	v_cvt_pk_bf16_f32 v150, v150, v157
	v_cvt_pk_bf16_f32 v151, v151, v156
	v_cvt_pk_bf16_f32 v152, v152, v155
	v_cvt_pk_bf16_f32 v153, v153, v154
	v_cvt_pk_bf16_f32 v154, v186, v187
	v_cvt_pk_bf16_f32 v155, v188, v189
	v_cvt_pk_bf16_f32 v156, v220, v213
	v_cvt_pk_bf16_f32 v157, v214, v215
	v_cvt_pk_bf16_f32 v158, v216, v217
	v_cvt_pk_bf16_f32 v159, v218, v219
	v_cvt_pk_bf16_f32 v160, v221, v222
	v_cvt_pk_bf16_f32 v161, v223, v224
	s_nop 1
	v_permlane32_swap_b32_e32 v211, v212
	v_permlane32_swap_b32_e32 v146, v148
	v_permlane32_swap_b32_e32 v147, v149
	v_permlane32_swap_b32_e32 v150, v152
	v_permlane32_swap_b32_e32 v151, v153
	v_permlane32_swap_b32_e32 v154, v156
	v_permlane32_swap_b32_e32 v155, v157
	v_permlane32_swap_b32_e32 v158, v160
	v_permlane32_swap_b32_e32 v159, v161
	s_waitcnt vmcnt(0)
	ds_write_b128 v192, v[130:133] offset:16384
	ds_write_b128 v193, v[134:137] offset:16384
	ds_write_b128 v190, v[138:141] offset:49152
	ds_write_b128 v191, v[142:145] offset:49152
	s_cmp_gt_u32 s34, 60
	s_cselect_b64 s[2:3], -1, 0
	s_and_b64 vcc, exec, s[2:3]
	s_cbranch_vccnz .LBB0_1028
	v_add_co_u32_e32 v114, vcc, 0x19040000, v168
	s_nop 1
	v_addc_co_u32_e32 v115, vcc, 0, v169, vcc
	v_add_co_u32_e32 v118, vcc, 0x19088000, v168
	s_nop 1
	v_addc_co_u32_e32 v119, vcc, 0, v169, vcc
	v_add_co_u32_e32 v122, vcc, 0x1f660000, v166
	global_load_dwordx4 v[114:117], v[114:115], off
	s_nop 0
	global_load_dwordx4 v[118:121], v[118:119], off
	v_addc_co_u32_e32 v123, vcc, 0, v167, vcc
	v_add_co_u32_e32 v126, vcc, 0x1f66c000, v166
	s_nop 1
	v_addc_co_u32_e32 v127, vcc, 0, v167, vcc
	global_load_dwordx4 v[122:125], v[122:123], off
	s_nop 0
	global_load_dwordx4 v[126:129], v[126:127], off

; __device__ __forceinline__ void finishSM(f32x16& p0, f32x16& p1, float alpha, float& l_reg, bf16x8& pa0, bf16x8& pa1, bf16x8& pa2, bf16x8& pa3) {
; #pragma unroll
;   for (int r = 0; r < 16; ++r) p1[r] = __builtin_amdgcn_exp2f(p1[r]);
;   float ps = 0;
; #pragma unroll
;   for (int r = 0; r < 16; ++r) ps += p0[r];
; #pragma unroll
;   for (int r = 0; r < 16; ++r) ps += p1[r];
;   { auto rr = __builtin_amdgcn_permlane32_swap(__float_as_uint(ps), __float_as_uint(ps), false, false);
;     ps = __uint_as_float(rr[0]) + __uint_as_float(rr[1]); }
;   l_reg = l_reg * alpha + ps;
;   PK4(p0, 0, pa0); PK4(p0, 8, pa1); PK4(p1, 0, pa2); PK4(p1, 8, pa3);
; }
;   p0 = f32x16{}; p1 = f32x16{};
; #pragma unroll
;   for (int d0 = DLO; d0 < DHI; ++d0) { int cb = (d0 * 16 + hi * 8) * 2;
;     bf16x8 b0 = *reinterpret_cast<const bf16x8*>((const char*)Ks + KSWZ(r32, cb));
;     bf16x8 b1 = *reinterpret_cast<const bf16x8*>((const char*)Ks + KSWZ(32 + r32, cb));
;     p0 = __builtin_amdgcn_mfma_f32_32x32x16_bf16(b0, qr[d0], p0, 0, 0, 0);
;     p1 = __builtin_amdgcn_mfma_f32_32x32x16_bf16(b1, qr[d0], p1, 0, 0, 0); }
; }
.LBB0_1043:
	ds_read_b128 v[66:69], v218 offset:49152
	ds_read_b128 v[70:73], v218 offset:57344
	ds_read_b128 v[186:189], v225 offset:49152
	ds_read_b128 v[230:233], v225 offset:57344
	ds_read_b128 v[234:237], v224 offset:49152
	ds_read_b128 v[238:241], v224 offset:57344
	ds_read_b128 v[242:245], v222 offset:49152
	ds_read_b128 v[246:249], v222 offset:57344
	v_add_f32_e32 v162, 0, v177
	v_add_f32_e32 v162, v195, v162
	s_waitcnt lgkmcnt(7)
	v_mfma_f32_32x32x16_bf16 v[82:97], v[66:69], v[118:121], 0
	v_add_f32_e32 v162, v163, v162
	v_add_f32_e32 v162, v194, v162
	v_add_f32_e32 v162, v164, v162
	v_add_f32_e32 v162, v176, v162
	v_add_f32_e32 v162, v165, v162
	v_add_f32_e32 v162, v175, v162
	v_add_f32_e32 v162, v166, v162
	s_waitcnt lgkmcnt(6)
	v_mfma_f32_32x32x16_bf16 v[66:81], v[70:73], v[118:121], 0
	v_add_f32_e32 v162, v174, v162
	v_add_f32_e32 v162, v167, v162
	v_add_f32_e32 v162, v173, v162
	v_exp_f32_e32 v158, v158
	v_add_f32_e32 v162, v168, v162
	v_exp_f32_e32 v159, v159
	v_add_f32_e32 v162, v172, v162
	s_waitcnt lgkmcnt(5)
	v_mfma_f32_32x32x16_bf16 v[82:97], v[186:189], v[110:113], v[82:97]
	v_exp_f32_e32 v156, v156
	v_add_f32_e32 v162, v169, v162
	v_exp_f32_e32 v157, v157
	v_add_f32_e32 v162, v171, v162
	v_exp_f32_e32 v150, v150
	v_add_f32_e32 v162, v158, v162
	v_exp_f32_e32 v151, v151
	s_waitcnt lgkmcnt(4)
	v_mfma_f32_32x32x16_bf16 v[66:81], v[230:233], v[110:113], v[66:81]
	ds_read_b128 v[186:189], v220 offset:49152
	ds_read_b128 v[230:233], v220 offset:57344
	v_add_f32_e32 v162, v159, v162
	v_exp_f32_e32 v148, v148
	v_add_f32_e32 v162, v156, v162
	v_exp_f32_e32 v149, v149
	v_add_f32_e32 v162, v157, v162
	v_exp_f32_e32 v146, v146
	s_waitcnt lgkmcnt(5)
	v_mfma_f32_32x32x16_bf16 v[82:97], v[234:237], v[126:129], v[82:97]
	v_add_f32_e32 v162, v150, v162
	v_exp_f32_e32 v147, v147
	v_add_f32_e32 v162, v151, v162
	v_exp_f32_e32 v160, v160
	v_add_f32_e32 v162, v148, v162
	v_exp_f32_e32 v161, v161
	v_add_f32_e32 v162, v149, v162
	s_waitcnt lgkmcnt(4)
	v_mfma_f32_32x32x16_bf16 v[66:81], v[238:241], v[126:129], v[66:81]
	ds_read_b128 v[234:237], v219 offset:49152
	ds_read_b128 v[238:241], v219 offset:57344
	v_exp_f32_e32 v154, v154
	v_add_f32_e32 v162, v146, v162
	v_exp_f32_e32 v155, v155
	v_add_f32_e32 v162, v147, v162
	v_exp_f32_e32 v152, v152
	v_add_f32_e32 v162, v160, v162
	s_waitcnt lgkmcnt(5)
	v_mfma_f32_32x32x16_bf16 v[82:97], v[242:245], v[122:125], v[82:97]
	v_exp_f32_e32 v153, v153
	v_add_f32_e32 v162, v161, v162
	v_add_f32_e32 v162, v154, v162
	v_add_f32_e32 v162, v155, v162
	v_add_f32_e32 v162, v152, v162
	v_add_f32_e32 v227, v153, v162
	s_waitcnt lgkmcnt(4)
	v_mfma_f32_32x32x16_bf16 v[66:81], v[246:249], v[122:125], v[66:81]
	ds_read_b128 v[242:245], v221 offset:49152
	ds_read_b128 v[246:249], v221 offset:57344
	s_waitcnt lgkmcnt(5)
	v_mfma_f32_32x32x16_bf16 v[82:97], v[186:189], v[114:117], v[82:97]
	s_waitcnt lgkmcnt(4)
	v_mfma_f32_32x32x16_bf16 v[66:81], v[230:233], v[114:117], v[66:81]
	ds_read_b128 v[186:189], v223 offset:49152
	ds_read_b128 v[230:233], v223 offset:57344
	s_waitcnt lgkmcnt(5)
	v_mfma_f32_32x32x16_bf16 v[82:97], v[234:237], v[106:109], v[82:97]
	s_waitcnt lgkmcnt(4)
	v_mfma_f32_32x32x16_bf16 v[66:81], v[238:241], v[106:109], v[66:81]
	s_waitcnt lgkmcnt(3)
	v_mfma_f32_32x32x16_bf16 v[82:97], v[242:245], v[102:105], v[82:97]
	s_waitcnt lgkmcnt(2)
	v_mfma_f32_32x32x16_bf16 v[66:81], v[246:249], v[102:105], v[66:81]
	v_cvt_pk_bf16_f32 v162, v177, v195
	v_cvt_pk_bf16_f32 v163, v163, v194
	v_cvt_pk_bf16_f32 v164, v164, v176
	v_cvt_pk_bf16_f32 v165, v165, v175
	v_cvt_pk_bf16_f32 v166, v166, v174
	v_cvt_pk_bf16_f32 v167, v167, v173
	s_waitcnt lgkmcnt(1)
	v_mfma_f32_32x32x16_bf16 v[82:97], v[186:189], v[98:101], v[82:97]
	v_mov_b32_e32 v228, v227
	s_nop 1
	v_permlane32_swap_b32_e32 v227, v228
	v_permlane32_swap_b32_e32 v162, v164
	v_cvt_pk_bf16_f32 v168, v168, v172
	v_cvt_pk_bf16_f32 v169, v169, v171
	s_waitcnt lgkmcnt(0)
	v_mfma_f32_32x32x16_bf16 v[66:81], v[230:233], v[98:101], v[66:81]
	v_cvt_pk_bf16_f32 v172, v158, v159
	v_cvt_pk_bf16_f32 v173, v156, v157
	v_cvt_pk_bf16_f32 v174, v150, v151
	v_cvt_pk_bf16_f32 v175, v148, v149
	v_cvt_pk_bf16_f32 v230, v146, v147
	v_cvt_pk_bf16_f32 v231, v160, v161
	v_cvt_pk_bf16_f32 v232, v154, v155
	v_cvt_pk_bf16_f32 v233, v152, v153
	v_permlane32_swap_b32_e32 v163, v165
	v_permlane32_swap_b32_e32 v166, v168
	v_permlane32_swap_b32_e32 v167, v169
	v_permlane32_swap_b32_e32 v172, v174
	v_permlane32_swap_b32_e32 v173, v175
	v_permlane32_swap_b32_e32 v230, v232
	v_permlane32_swap_b32_e32 v231, v233
	s_waitcnt vmcnt(0)
	ds_write_b128 v216, v[130:133]
	ds_write_b128 v217, v[134:137]
	ds_write_b128 v214, v[138:141] offset:32768
	ds_write_b128 v215, v[142:145] offset:32768
	v_lshl_add_u64 v[196:197], v[192:193], 0, v[0:1]
	s_mov_b32 s1, 0x18fb0000
	v_add_co_u32_e32 v146, vcc, s1, v196
	s_mov_b32 s1, 0x18ff8000
	s_nop 0
	v_addc_co_u32_e32 v147, vcc, 0, v197, vcc
	v_add_co_u32_e32 v150, vcc, s1, v196
	v_lshl_add_u64 v[194:195], v[190:191], 0, v[0:1]
	s_nop 0
	v_addc_co_u32_e32 v151, vcc, 0, v197, vcc
	s_mov_b32 s1, 0x1f648000
	v_add_co_u32_e32 v154, vcc, s1, v194
	s_mov_b32 s1, 0x1f654000
	s_nop 0
	v_addc_co_u32_e32 v155, vcc, 0, v195, vcc
	v_add_co_u32_e32 v158, vcc, s1, v194
	global_load_dwordx4 v[146:149], v[146:147], off
	s_nop 0
	global_load_dwordx4 v[150:153], v[150:151], off
	v_addc_co_u32_e32 v159, vcc, 0, v195, vcc
	global_load_dwordx4 v[154:157], v[154:155], off
	s_nop 0
	global_load_dwordx4 v[158:161], v[158:159], off
	ds_read_b64_tr_b16 v[234:235], v213 offset:0
	ds_read_b64_tr_b16 v[236:237], v213 offset:0x800
	ds_read_b64_tr_b16 v[238:239], v213 offset:0x1000
	ds_read_b64_tr_b16 v[240:241], v213 offset:0x1800
	ds_read_b64_tr_b16 v[242:243], v213 offset:0x2000
	ds_read_b64_tr_b16 v[244:245], v213 offset:0x2800
	ds_read_b64_tr_b16 v[246:247], v213 offset:0x3000
	ds_read_b64_tr_b16 v[248:249], v213 offset:0x3800
	s_waitcnt lgkmcnt(4)
; __device__ __forceinline__ void partialSM(f32x16& p0, f32x16& p1, float& m_reg, float& mn, float& alpha) {
;   constexpr float C = SCALE * 1.4426950408889634f;
;   float pmax = p0[0];
; #pragma unroll
;   for (int r = 1; r < 16; ++r) pmax = fmaxf(pmax, p0[r]);
; #pragma unroll
;   for (int r = 0; r < 16; ++r) pmax = fmaxf(pmax, p1[r]);
;   { auto rr = __builtin_amdgcn_permlane32_swap(__float_as_uint(pmax), __float_as_uint(pmax), false, false);
;     pmax = fmaxf(__uint_as_float(rr[0]), __uint_as_float(rr[1])); }
;   if (__builtin_expect(__all(pmax - m_reg <= THR / SCALE), 1)) { mn = m_reg; alpha = 1.f; }
;   else { mn = fmaxf(m_reg, pmax); alpha = __builtin_amdgcn_exp2f((m_reg - mn) * C); m_reg = mn; }
	s_nop 0
	v_mfma_f32_32x32x16_bf16 v[2:17], v[162:165], v[234:237], v[2:17]
	ds_read_b64_tr_b16 v[234:235], v213 offset:0x200
	ds_read_b64_tr_b16 v[236:237], v213 offset:0xa00
	v_mfma_f32_32x32x16_bf16 v[2:17], v[166:169], v[238:241], v[2:17]
	ds_read_b64_tr_b16 v[238:239], v213 offset:0x1200
	ds_read_b64_tr_b16 v[240:241], v213 offset:0x1a00
	s_waitcnt lgkmcnt(4)
	v_mfma_f32_32x32x16_bf16 v[2:17], v[172:175], v[242:245], v[2:17]
	ds_read_b64_tr_b16 v[242:243], v213 offset:0x2200
	ds_read_b64_tr_b16 v[244:245], v213 offset:0x2a00
	v_mfma_f32_32x32x16_bf16 v[2:17], v[230:233], v[246:249], v[2:17]
	ds_read_b64_tr_b16 v[246:247], v213 offset:0x3200
	ds_read_b64_tr_b16 v[248:249], v213 offset:0x3a00
	s_waitcnt lgkmcnt(4)
	v_mfma_f32_32x32x16_bf16 v[50:65], v[162:165], v[234:237], v[50:65]
	ds_read_b64_tr_b16 v[234:235], v213 offset:0x400
	ds_read_b64_tr_b16 v[236:237], v213 offset:0xc00
	v_mfma_f32_32x32x16_bf16 v[50:65], v[166:169], v[238:241], v[50:65]
	ds_read_b64_tr_b16 v[238:239], v213 offset:0x1400
	ds_read_b64_tr_b16 v[240:241], v213 offset:0x1c00
	s_waitcnt lgkmcnt(4)
	v_mfma_f32_32x32x16_bf16 v[50:65], v[172:175], v[242:245], v[50:65]
	ds_read_b64_tr_b16 v[242:243], v213 offset:0x2400
	ds_read_b64_tr_b16 v[244:245], v213 offset:0x2c00
	v_mfma_f32_32x32x16_bf16 v[50:65], v[230:233], v[246:249], v[50:65]
	ds_read_b64_tr_b16 v[246:247], v213 offset:0x3400
	ds_read_b64_tr_b16 v[248:249], v213 offset:0x3c00
	s_waitcnt lgkmcnt(4)
	v_mfma_f32_32x32x16_bf16 v[34:49], v[162:165], v[234:237], v[34:49]
	ds_read_b64_tr_b16 v[234:235], v213 offset:0x600
	ds_read_b64_tr_b16 v[236:237], v213 offset:0xe00
	v_mfma_f32_32x32x16_bf16 v[34:49], v[166:169], v[238:241], v[34:49]
	ds_read_b64_tr_b16 v[238:239], v213 offset:0x1600
	ds_read_b64_tr_b16 v[240:241], v213 offset:0x1e00
	s_waitcnt lgkmcnt(4)
	v_mfma_f32_32x32x16_bf16 v[34:49], v[172:175], v[242:245], v[34:49]
	ds_read_b64_tr_b16 v[242:243], v213 offset:0x2600
	ds_read_b64_tr_b16 v[244:245], v213 offset:0x2e00
	v_mfma_f32_32x32x16_bf16 v[34:49], v[230:233], v[246:249], v[34:49]
	ds_read_b64_tr_b16 v[246:247], v213 offset:0x3600
	ds_read_b64_tr_b16 v[248:249], v213 offset:0x3e00
	s_waitcnt lgkmcnt(4)
	v_mfma_f32_32x32x16_bf16 v[18:33], v[162:165], v[234:237], v[18:33]
	v_max_f32_e32 v162, v83, v83
	v_max_f32_e32 v163, v82, v82
	v_max_f32_e32 v162, v163, v162
	v_max3_f32 v162, v162, v84, v85
	v_max3_f32 v162, v162, v86, v87
	v_max3_f32 v162, v162, v88, v89
	v_max3_f32 v162, v162, v90, v91
	v_max3_f32 v162, v162, v92, v93
	v_max3_f32 v162, v162, v94, v95
	v_mfma_f32_32x32x16_bf16 v[18:33], v[166:169], v[238:241], v[18:33]
	v_max3_f32 v162, v162, v96, v97
	v_max3_f32 v162, v162, v66, v67
	v_max3_f32 v162, v162, v68, v69
	v_max3_f32 v162, v162, v70, v71
	v_max3_f32 v162, v162, v72, v73
	v_max3_f32 v162, v162, v74, v75
	v_max3_f32 v162, v162, v76, v77
	v_max3_f32 v162, v162, v78, v79
	s_waitcnt lgkmcnt(0)
	v_mfma_f32_32x32x16_bf16 v[18:33], v[172:175], v[242:245], v[18:33]
	v_max3_f32 v162, v162, v80, v81
	v_mov_b32_e32 v163, v162
	s_nop 1
	v_permlane32_swap_b32_e32 v162, v163
	v_max_f32_e32 v163, v163, v163
	v_max_f32_e32 v162, v162, v162
	v_max_f32_e32 v162, v162, v163
	v_sub_f32_e32 v163, v162, v170
	v_cmp_ge_f32_e32 vcc, s63, v163
	v_max_f32_e32 v163, v170, v170
	v_max_f32_e32 v162, v163, v162
	v_mfma_f32_32x32x16_bf16 v[18:33], v[230:233], v[246:249], v[18:33]
	v_sub_f32_e32 v163, v170, v162
	v_mul_f32_e32 v163, 0x3e0293ee, v163
	v_exp_f32_e32 v163, v163
	s_cmp_eq_u64 vcc, exec
	s_cselect_b64 s[8:9], -1, 0
	s_waitcnt vmcnt(4)
	v_cndmask_b32_e64 v229, v163, 1.0, s[8:9]
	v_cmp_gt_f32_e32 vcc, 1.0, v229
	s_cbranch_vccz .LBB0_1047
	s_and_saveexec_b64 s[2:3], s[6:7]
	ds_write_b32 v210, v229 offset:128
	s_or_b64 exec, exec, s[2:3]
	s_waitcnt lgkmcnt(0)
	v_add_u32_e32 v163, s15, v209
	ds_read_b128 v[164:167], v163 offset:224
	ds_read_b128 v[172:175], v163 offset:192
	ds_read_b128 v[230:233], v163 offset:160
	ds_read_b128 v[234:237], v163 offset:128
	s_waitcnt lgkmcnt(3)
	v_pk_mul_f32 v[14:15], v[14:15], v[164:165]
	s_waitcnt lgkmcnt(2)
	v_pk_mul_f32 v[10:11], v[10:11], v[172:173]
	s_waitcnt lgkmcnt(1)
	v_pk_mul_f32 v[6:7], v[6:7], v[230:231]
	v_pk_mul_f32 v[16:17], v[16:17], v[166:167]
	v_pk_mul_f32 v[12:13], v[12:13], v[174:175]
	v_pk_mul_f32 v[8:9], v[8:9], v[232:233]
	s_waitcnt lgkmcnt(0)
	v_pk_mul_f32 v[4:5], v[4:5], v[236:237]
	v_pk_mul_f32 v[2:3], v[2:3], v[234:235]
	v_pk_mul_f32 v[62:63], v[62:63], v[164:165]
	v_pk_mul_f32 v[58:59], v[58:59], v[172:173]
	v_pk_mul_f32 v[54:55], v[54:55], v[230:231]
	v_pk_mul_f32 v[64:65], v[64:65], v[166:167]
	v_pk_mul_f32 v[60:61], v[60:61], v[174:175]
	v_pk_mul_f32 v[56:57], v[56:57], v[232:233]
	v_pk_mul_f32 v[52:53], v[52:53], v[236:237]
	v_pk_mul_f32 v[50:51], v[50:51], v[234:235]
	v_pk_mul_f32 v[46:47], v[46:47], v[164:165]
	v_pk_mul_f32 v[42:43], v[42:43], v[172:173]
	v_pk_mul_f32 v[38:39], v[38:39], v[230:231]
	v_pk_mul_f32 v[48:49], v[48:49], v[166:167]
	v_pk_mul_f32 v[44:45], v[44:45], v[174:175]
	v_pk_mul_f32 v[40:41], v[40:41], v[232:233]
	v_pk_mul_f32 v[36:37], v[36:37], v[236:237]
	v_pk_mul_f32 v[34:35], v[34:35], v[234:235]
	v_pk_mul_f32 v[30:31], v[30:31], v[164:165]
	v_pk_mul_f32 v[26:27], v[26:27], v[172:173]
	v_pk_mul_f32 v[22:23], v[22:23], v[230:231]
	v_pk_mul_f32 v[32:33], v[32:33], v[166:167]
	v_pk_mul_f32 v[28:29], v[28:29], v[174:175]
	v_pk_mul_f32 v[24:25], v[24:25], v[232:233]
	v_pk_mul_f32 v[20:21], v[20:21], v[236:237]
	v_pk_mul_f32 v[18:19], v[18:19], v[234:235]
; __device__ __forceinline__ void partialSM(f32x16& p0, f32x16& p1, float& m_reg, float& mn, float& alpha) {
;     ...
;   float mnC = -mn * C;
; #pragma unroll
;   for (int r = 0; r < 16; ++r) p0[r] = fmaf(p0[r], C, mnC);
; #pragma unroll
;   for (int r = 0; r < 16; ++r) p1[r] = fmaf(p1[r], C, mnC);
; #pragma unroll
;   for (int r = 0; r < 16; ++r) p0[r] = __builtin_amdgcn_exp2f(p0[r]);
.LBB0_1047:
	v_cndmask_b32_e64 v230, v162, v170, s[8:9]
	v_mul_f32_e32 v231, 0xbe0293ee, v230
	v_fmamk_f32 v82, v82, 0x3e0293ee, v231
	v_fmamk_f32 v83, v83, 0x3e0293ee, v231
	v_fmamk_f32 v84, v84, 0x3e0293ee, v231
	v_fmamk_f32 v85, v85, 0x3e0293ee, v231
	v_fmamk_f32 v86, v86, 0x3e0293ee, v231
	v_fmamk_f32 v87, v87, 0x3e0293ee, v231
	v_fmamk_f32 v88, v88, 0x3e0293ee, v231
	v_fmamk_f32 v89, v89, 0x3e0293ee, v231
	v_fmamk_f32 v90, v90, 0x3e0293ee, v231
	v_fmamk_f32 v91, v91, 0x3e0293ee, v231
	v_fmamk_f32 v92, v92, 0x3e0293ee, v231
	v_fmamk_f32 v93, v93, 0x3e0293ee, v231
	v_fmamk_f32 v94, v94, 0x3e0293ee, v231
	v_fmamk_f32 v95, v95, 0x3e0293ee, v231
	v_fmamk_f32 v96, v96, 0x3e0293ee, v231
	v_fmamk_f32 v97, v97, 0x3e0293ee, v231
	v_exp_f32_e32 v162, v82
	v_exp_f32_e32 v177, v83
	v_exp_f32_e32 v163, v84
	v_exp_f32_e32 v176, v85
	v_exp_f32_e32 v164, v86
	v_exp_f32_e32 v175, v87
	v_exp_f32_e32 v165, v88
	v_exp_f32_e32 v174, v89
	v_exp_f32_e32 v166, v90
	v_exp_f32_e32 v173, v91
	v_exp_f32_e32 v167, v92
	v_exp_f32_e32 v172, v93
	v_exp_f32_e32 v168, v94
	v_exp_f32_e32 v171, v95
	v_exp_f32_e32 v169, v96
	v_exp_f32_e32 v170, v97
	v_fmamk_f32 v240, v66, 0x3e0293ee, v231
	v_fmamk_f32 v241, v67, 0x3e0293ee, v231
	v_fmamk_f32 v242, v68, 0x3e0293ee, v231
	v_fmamk_f32 v243, v69, 0x3e0293ee, v231
	v_fmamk_f32 v244, v70, 0x3e0293ee, v231
	v_fmamk_f32 v233, v71, 0x3e0293ee, v231
	v_fmamk_f32 v234, v72, 0x3e0293ee, v231
	v_fmamk_f32 v235, v73, 0x3e0293ee, v231
	v_fmamk_f32 v236, v74, 0x3e0293ee, v231
	v_fmamk_f32 v237, v75, 0x3e0293ee, v231
	v_fmamk_f32 v238, v76, 0x3e0293ee, v231
	v_fmamk_f32 v239, v77, 0x3e0293ee, v231
	v_fmamk_f32 v232, v78, 0x3e0293ee, v231
	v_fmamk_f32 v245, v79, 0x3e0293ee, v231
	v_fmamk_f32 v246, v80, 0x3e0293ee, v231
	v_fmac_f32_e32 v231, 0x3e0293ee, v81
	s_waitcnt lgkmcnt(0)
	s_barrier
; __device__ __forceinline__ void finishSM(f32x16& p0, f32x16& p1, float alpha, float& l_reg, bf16x8& pa0, bf16x8& pa1, bf16x8& pa2, bf16x8& pa3) {
; #pragma unroll
;   for (int r = 0; r < 16; ++r) p1[r] = __builtin_amdgcn_exp2f(p1[r]);
;   float ps = 0;
; #pragma unroll
;   for (int r = 0; r < 16; ++r) ps += p0[r];
; #pragma unroll
;   for (int r = 0; r < 16; ++r) ps += p1[r];
;   { auto rr = __builtin_amdgcn_permlane32_swap(__float_as_uint(ps), __float_as_uint(ps), false, false);
;     ps = __uint_as_float(rr[0]) + __uint_as_float(rr[1]); }
;   l_reg = l_reg * alpha + ps;
;   PK4(p0, 0, pa0); PK4(p0, 8, pa1); PK4(p1, 0, pa2); PK4(p1, 8, pa3);
; }
;   p0 = f32x16{}; p1 = f32x16{};
; #pragma unroll
;   for (int d0 = DLO; d0 < DHI; ++d0) { int cb = (d0 * 16 + hi * 8) * 2;
;     bf16x8 b0 = *reinterpret_cast<const bf16x8*>((const char*)Ks + KSWZ(r32, cb));
;     bf16x8 b1 = *reinterpret_cast<const bf16x8*>((const char*)Ks + KSWZ(32 + r32, cb));
;     p0 = __builtin_amdgcn_mfma_f32_32x32x16_bf16(b0, qr[d0], p0, 0, 0, 0);
;     p1 = __builtin_amdgcn_mfma_f32_32x32x16_bf16(b1, qr[d0], p1, 0, 0, 0); }
; }
	v_xor_b32_e32 v218, 0x10000, v218
	v_xor_b32_e32 v225, 0x10000, v225
	v_xor_b32_e32 v224, 0x10000, v224
	v_xor_b32_e32 v222, 0x10000, v222
	v_xor_b32_e32 v220, 0x10000, v220
	v_xor_b32_e32 v219, 0x10000, v219
	v_xor_b32_e32 v221, 0x10000, v221
	v_xor_b32_e32 v223, 0x10000, v223
	ds_read_b128 v[66:69], v218 offset:32768
	ds_read_b128 v[70:73], v218 offset:40960
	ds_read_b128 v[130:133], v225 offset:32768
	ds_read_b128 v[134:137], v225 offset:40960
	ds_read_b128 v[138:141], v224 offset:32768
	ds_read_b128 v[142:145], v224 offset:40960
	v_exp_f32_e32 v233, v233
	v_exp_f32_e32 v234, v234
	s_waitcnt lgkmcnt(5)
	v_mfma_f32_32x32x16_bf16 v[82:97], v[66:69], v[118:121], 0
	v_exp_f32_e32 v235, v235
	v_exp_f32_e32 v236, v236
	v_exp_f32_e32 v237, v237
	v_exp_f32_e32 v238, v238
	v_exp_f32_e32 v239, v239
	s_waitcnt lgkmcnt(4)
	v_mfma_f32_32x32x16_bf16 v[66:81], v[70:73], v[118:121], 0
	s_waitcnt lgkmcnt(3)
	v_mfma_f32_32x32x16_bf16 v[82:97], v[130:133], v[110:113], v[82:97]
	s_waitcnt lgkmcnt(2)
	v_mfma_f32_32x32x16_bf16 v[66:81], v[134:137], v[110:113], v[66:81]
	ds_read_b128 v[130:133], v222 offset:32768
	ds_read_b128 v[134:137], v222 offset:40960
	s_waitcnt lgkmcnt(3)
	v_mfma_f32_32x32x16_bf16 v[82:97], v[138:141], v[126:129], v[82:97]
	s_waitcnt lgkmcnt(2)
	v_mfma_f32_32x32x16_bf16 v[66:81], v[142:145], v[126:129], v[66:81]
	ds_read_b128 v[138:141], v220 offset:32768
	ds_read_b128 v[142:145], v220 offset:40960
	s_waitcnt lgkmcnt(3)
	v_mfma_f32_32x32x16_bf16 v[82:97], v[130:133], v[122:125], v[82:97]
	s_waitcnt lgkmcnt(2)
	v_mfma_f32_32x32x16_bf16 v[66:81], v[134:137], v[122:125], v[66:81]
	ds_read_b128 v[130:133], v219 offset:32768
	ds_read_b128 v[134:137], v219 offset:40960
	s_waitcnt lgkmcnt(3)
	v_mfma_f32_32x32x16_bf16 v[82:97], v[138:141], v[114:117], v[82:97]
	s_waitcnt lgkmcnt(2)
	v_mfma_f32_32x32x16_bf16 v[66:81], v[142:145], v[114:117], v[66:81]
	ds_read_b128 v[138:141], v221 offset:32768
	ds_read_b128 v[142:145], v221 offset:40960
	s_waitcnt lgkmcnt(3)
	v_mfma_f32_32x32x16_bf16 v[82:97], v[130:133], v[106:109], v[82:97]
	s_waitcnt lgkmcnt(2)
	v_mfma_f32_32x32x16_bf16 v[66:81], v[134:137], v[106:109], v[66:81]
	ds_read_b128 v[130:133], v223 offset:32768
	ds_read_b128 v[134:137], v223 offset:40960
	s_waitcnt lgkmcnt(3)
	v_mfma_f32_32x32x16_bf16 v[82:97], v[138:141], v[102:105], v[82:97]
	s_waitcnt lgkmcnt(2)
	v_mfma_f32_32x32x16_bf16 v[66:81], v[142:145], v[102:105], v[66:81]
	s_waitcnt lgkmcnt(1)
	v_mfma_f32_32x32x16_bf16 v[82:97], v[130:133], v[98:101], v[82:97]
	v_exp_f32_e32 v186, v240
	v_exp_f32_e32 v240, v244
	v_exp_f32_e32 v244, v231
	v_add_f32_e32 v231, 0, v162
	v_add_f32_e32 v231, v177, v231
	v_add_f32_e32 v231, v163, v231
	v_add_f32_e32 v231, v176, v231
	v_add_f32_e32 v231, v164, v231
	v_add_f32_e32 v231, v175, v231
	v_add_f32_e32 v231, v165, v231
	v_add_f32_e32 v231, v174, v231
	v_add_f32_e32 v231, v166, v231
	v_add_f32_e32 v231, v173, v231
	v_add_f32_e32 v231, v167, v231
	v_add_f32_e32 v231, v172, v231
	v_add_f32_e32 v231, v168, v231
	v_exp_f32_e32 v187, v241
	v_add_f32_e32 v231, v171, v231
	v_exp_f32_e32 v188, v242
	v_add_f32_e32 v231, v169, v231
	v_exp_f32_e32 v189, v243
	v_add_f32_e32 v231, v170, v231
	v_add_f32_e32 v231, v186, v231
	v_add_f32_e32 v231, v187, v231
	v_add_f32_e32 v231, v188, v231
	v_add_f32_e32 v231, v189, v231
	v_add_f32_e32 v231, v240, v231
	v_add_f32_e32 v231, v233, v231
	v_add_f32_e32 v231, v234, v231
	v_add_f32_e32 v231, v235, v231
	v_exp_f32_e32 v241, v232
	v_add_f32_e32 v231, v236, v231
	v_exp_f32_e32 v242, v245
	v_add_f32_e32 v231, v237, v231
	s_waitcnt lgkmcnt(0)
	v_mfma_f32_32x32x16_bf16 v[66:81], v[134:137], v[98:101], v[66:81]
	v_exp_f32_e32 v243, v246
	v_add_f32_e32 v231, v238, v231
	v_add_f32_e32 v231, v239, v231
	v_add_f32_e32 v231, v241, v231
	v_add_f32_e32 v231, v242, v231
	v_add_f32_e32 v231, v243, v231
	v_add_f32_e32 v231, v244, v231
	v_mov_b32_e32 v232, v231
	v_cvt_pk_bf16_f32 v162, v162, v177
	v_cvt_pk_bf16_f32 v163, v163, v176
	v_cvt_pk_bf16_f32 v164, v164, v175
	v_cvt_pk_bf16_f32 v165, v165, v174
	v_cvt_pk_bf16_f32 v166, v166, v173
	v_cvt_pk_bf16_f32 v167, v167, v172
	v_cvt_pk_bf16_f32 v168, v168, v171
	v_cvt_pk_bf16_f32 v169, v169, v170
	v_cvt_pk_bf16_f32 v170, v186, v187
	v_cvt_pk_bf16_f32 v171, v188, v189
	v_cvt_pk_bf16_f32 v172, v240, v233
	v_cvt_pk_bf16_f32 v173, v234, v235
	v_cvt_pk_bf16_f32 v174, v236, v237
	v_cvt_pk_bf16_f32 v175, v238, v239
	v_cvt_pk_bf16_f32 v176, v241, v242
	v_cvt_pk_bf16_f32 v177, v243, v244
	s_nop 1
	v_permlane32_swap_b32_e32 v231, v232
	v_permlane32_swap_b32_e32 v162, v164
	v_permlane32_swap_b32_e32 v163, v165
	v_permlane32_swap_b32_e32 v166, v168
	v_permlane32_swap_b32_e32 v167, v169
	v_permlane32_swap_b32_e32 v170, v172
	v_permlane32_swap_b32_e32 v171, v173
	v_permlane32_swap_b32_e32 v174, v176
	v_permlane32_swap_b32_e32 v175, v177
	s_waitcnt vmcnt(0)
	ds_write_b128 v216, v[146:149] offset:16384
	ds_write_b128 v217, v[150:153] offset:16384
	ds_write_b128 v214, v[154:157] offset:49152
	ds_write_b128 v215, v[158:161] offset:49152
	s_cmp_gt_u32 s34, 60
	s_cselect_b64 s[2:3], -1, 0
	s_and_b64 vcc, exec, s[2:3]
	s_cbranch_vccnz .LBB0_1049
	v_add_co_u32_e32 v130, vcc, 0x19040000, v196
	s_nop 1
	v_addc_co_u32_e32 v131, vcc, 0, v197, vcc
	v_add_co_u32_e32 v134, vcc, 0x19088000, v196
	s_nop 1
	v_addc_co_u32_e32 v135, vcc, 0, v197, vcc
	v_add_co_u32_e32 v138, vcc, 0x1f660000, v194
	global_load_dwordx4 v[130:133], v[130:131], off
	s_nop 0
	global_load_dwordx4 v[134:137], v[134:135], off
	v_addc_co_u32_e32 v139, vcc, 0, v195, vcc
	v_add_co_u32_e32 v142, vcc, 0x1f66c000, v194
	s_nop 1
	v_addc_co_u32_e32 v143, vcc, 0, v195, vcc
	global_load_dwordx4 v[138:141], v[138:139], off
	s_nop 0
	global_load_dwordx4 v[142:145], v[142:143], off

; __device__ __forceinline__ unsigned cvt_pk_bf16(float lo, float hi) { unsigned r; asm volatile("v_cvt_pk_bf16_f32 %0, %1, %2" : "=v"(r) : "v"(lo), "v"(hi)); return r; }
; __device__ __forceinline__ float silu_mul(float g, float u) { const float e = __builtin_amdgcn_exp2f(-1.4426950408889634f * g); return g * __builtin_amdgcn_rcpf(1.0f + e) * u; }
; __device__ __forceinline__ float rs_of(const rsq_t* rsq, int row) { return __builtin_amdgcn_rsqf((float)rsq[row] * (1.0f / (1048576.0f * 2048.0f)) + 1e-6f); }
;     __device__ __forceinline__ void operator()(const f32x4 (&acc)[2][2][4][2], const Unit& u, int wr, int wc, int fr, int fq) const {
;         const int row0 = u.pm * BM + wr * 64 + fr; const int col0 = u.pn * HALF + wc * 32 + 8 * fq;
; #pragma unroll
;         for (int ai = 0; ai < 2; ++ai)
; #pragma unroll
;             for (int m = 0; m < 4; ++m) { const int row = row0 + ai * HALF + m * 16; bf16_t* rowp = O + (size_t)row * ldc + col0;
;                 const float rs = rs_of(rsq, row);
;                 const f32x4 g0 = acc[ai][0][m][0] * rs, g1 = acc[ai][0][m][1] * rs, u0 = acc[ai][1][m][0] * rs, u1 = acc[ai][1][m][1] * rs;
;                 u32x4 w;
;                 w.x = cvt_pk_bf16(silu_mul(g0[0], u0[0]), silu_mul(g0[1], u0[1])); w.y = cvt_pk_bf16(silu_mul(g0[2], u0[2]), silu_mul(g0[3], u0[3]));
;                 w.z = cvt_pk_bf16(silu_mul(g1[0], u1[0]), silu_mul(g1[1], u1[1])); w.w = cvt_pk_bf16(silu_mul(g1[2], u1[2]), silu_mul(g1[3], u1[3]));
;                 *(u32x4*)rowp = w; }
.LBB0_1362:
	v_lshl_add_u32 v144, s1, 7, v152
	v_lshl_add_u32 v140, s2, 8, v150
	v_ashrrev_i32_e32 v145, 31, v144
	v_mov_b64_e32 v[142:143], s[10:11]
	s_movk_i32 s1, 0x2c00
	v_ashrrev_i32_e32 v141, 31, v140
	v_mad_i64_i32 v[146:147], s[2:3], v140, s1, v[142:143]
	v_lshlrev_b64 v[144:145], 1, v[144:145]
	v_lshl_add_u64 v[148:149], v[146:147], 0, v[144:145]
	v_lshl_add_u64 v[146:147], v[140:141], 3, s[12:13]
	global_load_dwordx2 v[154:155], v[146:147], off
	global_load_dwordx2 v[158:159], v[146:147], off offset:128
	global_load_dwordx2 v[160:161], v[146:147], off offset:256
	global_load_dwordx2 v[162:163], v[146:147], off offset:384
	global_load_dwordx2 v[164:165], v[146:147], off offset:1024
	global_load_dwordx2 v[166:167], v[146:147], off offset:1152
	global_load_dwordx2 v[168:169], v[146:147], off offset:1280
	global_load_dwordx2 v[170:171], v[146:147], off offset:1408
	s_andn2_b64 vcc, exec, s[6:7]
	s_waitcnt vmcnt(0)
	v_ffbh_u32_e32 v141, v155
	v_min_u32_e32 v141, 32, v141
	v_lshlrev_b64 v[154:155], v141, v[154:155]
	v_min_u32_e32 v154, 1, v154
	v_or_b32_e32 v154, v155, v154
	v_cvt_f32_u32_e32 v154, v154
	v_sub_u32_e32 v141, 32, v141
	v_ldexp_f32 v141, v154, v141
	v_fmamk_f32 v141, v141, 0x30000000, v198
	v_rsq_f32_e32 v154, v141
	s_nop 0
	v_pk_mul_f32 v[126:127], v[126:127], v[154:155] op_sel_hi:[1,0]
	v_pk_mul_f32 v[156:157], v[118:119], v[154:155] op_sel_hi:[1,0]
	v_pk_mul_f32 v[118:119], v[116:117], v[154:155] op_sel_hi:[1,0]
	v_pk_mul_f32 v[116:117], v[114:115], v[154:155] op_sel_hi:[1,0]
	v_mul_f32_e32 v114, 0xbfb8aa3b, v126
	v_mul_f32_e32 v115, 0xbfb8aa3b, v127
	v_exp_f32_e32 v114, v114
	v_exp_f32_e32 v115, v115
	v_pk_mul_f32 v[128:129], v[128:129], v[154:155] op_sel_hi:[1,0]
	v_pk_mul_f32 v[120:121], v[120:121], v[154:155] op_sel_hi:[1,0]
	v_add_f32_e32 v114, 1.0, v114
	v_add_f32_e32 v115, 1.0, v115
	v_rcp_f32_e32 v114, v114
	v_rcp_f32_e32 v115, v115
	v_pk_mul_f32 v[122:123], v[122:123], v[154:155] op_sel_hi:[1,0]
	v_pk_mul_f32 v[124:125], v[124:125], v[154:155] op_sel_hi:[1,0]
	v_mul_f32_e32 v114, v126, v114
	v_mul_f32_e32 v115, v127, v115
	v_mul_f32_e32 v114, v156, v114
	v_mul_f32_e32 v115, v157, v115
	v_cvt_pk_bf16_f32 v114, v114, v115
	v_mul_f32_e32 v115, 0xbfb8aa3b, v128
	v_exp_f32_e32 v115, v115
	s_nop 0
	v_add_f32_e32 v115, 1.0, v115
	v_rcp_f32_e32 v115, v115
	s_nop 0
	v_mul_f32_e32 v115, v128, v115
	v_mul_f32_e32 v115, v120, v115
	v_mul_f32_e32 v120, 0xbfb8aa3b, v129
	v_exp_f32_e32 v120, v120
	s_nop 0
	v_add_f32_e32 v120, 1.0, v120
	v_rcp_f32_e32 v120, v120
	s_nop 0
	v_mul_f32_e32 v120, v129, v120
	v_mul_f32_e32 v120, v121, v120
	v_cvt_pk_bf16_f32 v115, v115, v120
	v_mul_f32_e32 v120, 0xbfb8aa3b, v122
	v_exp_f32_e32 v120, v120
	s_nop 0
	v_add_f32_e32 v120, 1.0, v120
	v_rcp_f32_e32 v120, v120
	s_nop 0
	v_mul_f32_e32 v120, v122, v120
	v_mul_f32_e32 v116, v116, v120
	v_mul_f32_e32 v120, 0xbfb8aa3b, v123
	v_exp_f32_e32 v120, v120
	s_nop 0
	v_add_f32_e32 v120, 1.0, v120
	v_rcp_f32_e32 v120, v120
	s_nop 0
	v_mul_f32_e32 v120, v123, v120
	v_mul_f32_e32 v117, v117, v120
	v_cvt_pk_bf16_f32 v116, v116, v117
	v_mul_f32_e32 v117, 0xbfb8aa3b, v124
	v_exp_f32_e32 v117, v117
	s_nop 0
	v_add_f32_e32 v117, 1.0, v117
	v_rcp_f32_e32 v117, v117
	s_nop 0
	v_mul_f32_e32 v117, v124, v117
	v_mul_f32_e32 v117, v118, v117
	v_mul_f32_e32 v118, 0xbfb8aa3b, v125
	v_exp_f32_e32 v118, v118
	s_nop 0
	v_add_f32_e32 v118, 1.0, v118
	v_rcp_f32_e32 v118, v118
	s_nop 0
	v_mul_f32_e32 v118, v125, v118
	v_mul_f32_e32 v118, v119, v118
	v_cvt_pk_bf16_f32 v117, v117, v118
	global_store_dwordx4 v[148:149], v[114:117], off
	s_nop 1
	v_mov_b32_e32 v116, v158
	v_mov_b32_e32 v117, v159
	v_ffbh_u32_e32 v118, v117
	v_min_u32_e32 v118, 32, v118
	v_lshlrev_b64 v[116:117], v118, v[116:117]
	v_min_u32_e32 v116, 1, v116
	v_or_b32_e32 v116, v117, v116
	v_cvt_f32_u32_e32 v116, v116
	v_sub_u32_e32 v117, 32, v118
	v_or_b32_e32 v114, 16, v140
	v_mad_i64_i32 v[114:115], s[2:3], v114, s1, v[142:143]
	v_ldexp_f32 v116, v116, v117
	v_fmamk_f32 v116, v116, 0x30000000, v198
	v_rsq_f32_e32 v116, v116
	v_lshl_add_u64 v[114:115], v[114:115], 0, v[144:145]
	v_pk_mul_f32 v[110:111], v[110:111], v[116:117] op_sel_hi:[1,0]
	v_pk_mul_f32 v[118:119], v[102:103], v[116:117] op_sel_hi:[1,0]
	v_pk_mul_f32 v[102:103], v[100:101], v[116:117] op_sel_hi:[1,0]
	v_pk_mul_f32 v[100:101], v[98:99], v[116:117] op_sel_hi:[1,0]
	v_mul_f32_e32 v98, 0xbfb8aa3b, v110
	v_mul_f32_e32 v99, 0xbfb8aa3b, v111
	v_exp_f32_e32 v98, v98
	v_exp_f32_e32 v99, v99
	v_pk_mul_f32 v[112:113], v[112:113], v[116:117] op_sel_hi:[1,0]
	v_pk_mul_f32 v[104:105], v[104:105], v[116:117] op_sel_hi:[1,0]
	v_add_f32_e32 v98, 1.0, v98
	v_add_f32_e32 v99, 1.0, v99
	v_rcp_f32_e32 v98, v98
	v_rcp_f32_e32 v99, v99
	v_pk_mul_f32 v[106:107], v[106:107], v[116:117] op_sel_hi:[1,0]
	v_pk_mul_f32 v[108:109], v[108:109], v[116:117] op_sel_hi:[1,0]
	v_mul_f32_e32 v98, v110, v98
	v_mul_f32_e32 v99, v111, v99
	v_mul_f32_e32 v98, v118, v98
	v_mul_f32_e32 v99, v119, v99
	v_cvt_pk_bf16_f32 v98, v98, v99
	v_mul_f32_e32 v99, 0xbfb8aa3b, v112
	v_exp_f32_e32 v99, v99
	s_nop 0
	v_add_f32_e32 v99, 1.0, v99
	v_rcp_f32_e32 v99, v99
	s_nop 0
	v_mul_f32_e32 v99, v112, v99
	v_mul_f32_e32 v99, v104, v99
	v_mul_f32_e32 v104, 0xbfb8aa3b, v113
	v_exp_f32_e32 v104, v104
	s_nop 0
	v_add_f32_e32 v104, 1.0, v104
	v_rcp_f32_e32 v104, v104
	s_nop 0
	v_mul_f32_e32 v104, v113, v104
	v_mul_f32_e32 v104, v105, v104
	v_cvt_pk_bf16_f32 v99, v99, v104
	v_mul_f32_e32 v104, 0xbfb8aa3b, v106
	v_exp_f32_e32 v104, v104
	s_nop 0
	v_add_f32_e32 v104, 1.0, v104
	v_rcp_f32_e32 v104, v104
	s_nop 0
	v_mul_f32_e32 v104, v106, v104
	v_mul_f32_e32 v100, v100, v104
	v_mul_f32_e32 v104, 0xbfb8aa3b, v107
; __device__ __forceinline__ unsigned cvt_pk_bf16(float lo, float hi) { unsigned r; asm volatile("v_cvt_pk_bf16_f32 %0, %1, %2" : "=v"(r) : "v"(lo), "v"(hi)); return r; }
; __device__ __forceinline__ float silu_mul(float g, float u) { const float e = __builtin_amdgcn_exp2f(-1.4426950408889634f * g); return g * __builtin_amdgcn_rcpf(1.0f + e) * u; }
; __device__ __forceinline__ float rs_of(const rsq_t* rsq, int row) { return __builtin_amdgcn_rsqf((float)rsq[row] * (1.0f / (1048576.0f * 2048.0f)) + 1e-6f); }
;     __device__ __forceinline__ void operator()(const f32x4 (&acc)[2][2][4][2], const Unit& u, int wr, int wc, int fr, int fq) const {
;     ...
;             for (int m = 0; m < 4; ++m) { const int row = row0 + ai * HALF + m * 16; bf16_t* rowp = O + (size_t)row * ldc + col0;
;                 const float rs = rs_of(rsq, row);
;                 const f32x4 g0 = acc[ai][0][m][0] * rs, g1 = acc[ai][0][m][1] * rs, u0 = acc[ai][1][m][0] * rs, u1 = acc[ai][1][m][1] * rs;
;                 u32x4 w;
;                 w.x = cvt_pk_bf16(silu_mul(g0[0], u0[0]), silu_mul(g0[1], u0[1])); w.y = cvt_pk_bf16(silu_mul(g0[2], u0[2]), silu_mul(g0[3], u0[3]));
;                 w.z = cvt_pk_bf16(silu_mul(g1[0], u1[0]), silu_mul(g1[1], u1[1])); w.w = cvt_pk_bf16(silu_mul(g1[2], u1[2]), silu_mul(g1[3], u1[3]));
;                 *(u32x4*)rowp = w; }
	v_exp_f32_e32 v104, v104
	s_nop 0
	v_add_f32_e32 v104, 1.0, v104
	v_rcp_f32_e32 v104, v104
	s_nop 0
	v_mul_f32_e32 v104, v107, v104
	v_mul_f32_e32 v101, v101, v104
	v_cvt_pk_bf16_f32 v100, v100, v101
	v_mul_f32_e32 v101, 0xbfb8aa3b, v108
	v_exp_f32_e32 v101, v101
	s_nop 0
	v_add_f32_e32 v101, 1.0, v101
	v_rcp_f32_e32 v101, v101
	s_nop 0
	v_mul_f32_e32 v101, v108, v101
	v_mul_f32_e32 v101, v102, v101
	v_mul_f32_e32 v102, 0xbfb8aa3b, v109
	v_exp_f32_e32 v102, v102
	s_nop 0
	v_add_f32_e32 v102, 1.0, v102
	v_rcp_f32_e32 v102, v102
	s_nop 0
	v_mul_f32_e32 v102, v109, v102
	v_mul_f32_e32 v102, v103, v102
	v_cvt_pk_bf16_f32 v101, v101, v102
	global_store_dwordx4 v[114:115], v[98:101], off
	s_nop 1
	v_mov_b32_e32 v100, v160
	v_mov_b32_e32 v101, v161
	v_ffbh_u32_e32 v102, v101
	v_min_u32_e32 v102, 32, v102
	v_lshlrev_b64 v[100:101], v102, v[100:101]
	v_min_u32_e32 v100, 1, v100
	v_or_b32_e32 v100, v101, v100
	v_cvt_f32_u32_e32 v100, v100
	v_sub_u32_e32 v101, 32, v102
	v_or_b32_e32 v98, 32, v140
	v_mad_i64_i32 v[98:99], s[2:3], v98, s1, v[142:143]
	v_ldexp_f32 v100, v100, v101
	v_fmamk_f32 v100, v100, 0x30000000, v198
	v_rsq_f32_e32 v100, v100
	v_lshl_add_u64 v[98:99], v[98:99], 0, v[144:145]
	v_pk_mul_f32 v[94:95], v[94:95], v[100:101] op_sel_hi:[1,0]
	v_pk_mul_f32 v[102:103], v[86:87], v[100:101] op_sel_hi:[1,0]
	v_pk_mul_f32 v[86:87], v[84:85], v[100:101] op_sel_hi:[1,0]
	v_pk_mul_f32 v[84:85], v[82:83], v[100:101] op_sel_hi:[1,0]
	v_mul_f32_e32 v82, 0xbfb8aa3b, v94
	v_mul_f32_e32 v83, 0xbfb8aa3b, v95
	v_exp_f32_e32 v82, v82
	v_exp_f32_e32 v83, v83
	v_pk_mul_f32 v[96:97], v[96:97], v[100:101] op_sel_hi:[1,0]
	v_pk_mul_f32 v[88:89], v[88:89], v[100:101] op_sel_hi:[1,0]
	v_add_f32_e32 v82, 1.0, v82
	v_add_f32_e32 v83, 1.0, v83
	v_rcp_f32_e32 v82, v82
	v_rcp_f32_e32 v83, v83
	v_pk_mul_f32 v[90:91], v[90:91], v[100:101] op_sel_hi:[1,0]
	v_pk_mul_f32 v[92:93], v[92:93], v[100:101] op_sel_hi:[1,0]
	v_mul_f32_e32 v82, v94, v82
	v_mul_f32_e32 v83, v95, v83
	v_mul_f32_e32 v82, v102, v82
	v_mul_f32_e32 v83, v103, v83
	v_cvt_pk_bf16_f32 v82, v82, v83
	v_mul_f32_e32 v83, 0xbfb8aa3b, v96
	v_exp_f32_e32 v83, v83
	s_nop 0
	v_add_f32_e32 v83, 1.0, v83
	v_rcp_f32_e32 v83, v83
	s_nop 0
	v_mul_f32_e32 v83, v96, v83
	v_mul_f32_e32 v83, v88, v83
	v_mul_f32_e32 v88, 0xbfb8aa3b, v97
	v_exp_f32_e32 v88, v88
	s_nop 0
	v_add_f32_e32 v88, 1.0, v88
	v_rcp_f32_e32 v88, v88
	s_nop 0
	v_mul_f32_e32 v88, v97, v88
	v_mul_f32_e32 v88, v89, v88
	v_cvt_pk_bf16_f32 v83, v83, v88
	v_mul_f32_e32 v88, 0xbfb8aa3b, v90
	v_exp_f32_e32 v88, v88
	s_nop 0
	v_add_f32_e32 v88, 1.0, v88
	v_rcp_f32_e32 v88, v88
	s_nop 0
	v_mul_f32_e32 v88, v90, v88
	v_mul_f32_e32 v84, v84, v88
	v_mul_f32_e32 v88, 0xbfb8aa3b, v91
	v_exp_f32_e32 v88, v88
	s_nop 0
	v_add_f32_e32 v88, 1.0, v88
	v_rcp_f32_e32 v88, v88
	s_nop 0
	v_mul_f32_e32 v88, v91, v88
	v_mul_f32_e32 v85, v85, v88
	v_cvt_pk_bf16_f32 v84, v84, v85
	v_mul_f32_e32 v85, 0xbfb8aa3b, v92
	v_exp_f32_e32 v85, v85
	s_nop 0
	v_add_f32_e32 v85, 1.0, v85
	v_rcp_f32_e32 v85, v85
	s_nop 0
	v_mul_f32_e32 v85, v92, v85
	v_mul_f32_e32 v85, v86, v85
	v_mul_f32_e32 v86, 0xbfb8aa3b, v93
	v_exp_f32_e32 v86, v86
	s_nop 0
	v_add_f32_e32 v86, 1.0, v86
	v_rcp_f32_e32 v86, v86
	s_nop 0
	v_mul_f32_e32 v86, v93, v86
	v_mul_f32_e32 v86, v87, v86
	v_cvt_pk_bf16_f32 v85, v85, v86
	global_store_dwordx4 v[98:99], v[82:85], off
	s_nop 1
	v_mov_b32_e32 v84, v162
	v_mov_b32_e32 v85, v163
	v_ffbh_u32_e32 v86, v85
	v_min_u32_e32 v86, 32, v86
	v_lshlrev_b64 v[84:85], v86, v[84:85]
	v_min_u32_e32 v84, 1, v84
	v_or_b32_e32 v84, v85, v84
	v_cvt_f32_u32_e32 v84, v84
	v_sub_u32_e32 v85, 32, v86
	v_or_b32_e32 v82, 48, v140
	v_mad_i64_i32 v[82:83], s[2:3], v82, s1, v[142:143]
	v_ldexp_f32 v84, v84, v85
	v_fmamk_f32 v84, v84, 0x30000000, v198
	v_rsq_f32_e32 v84, v84
	v_lshl_add_u64 v[82:83], v[82:83], 0, v[144:145]
	v_pk_mul_f32 v[78:79], v[78:79], v[84:85] op_sel_hi:[1,0]
	v_pk_mul_f32 v[86:87], v[70:71], v[84:85] op_sel_hi:[1,0]
	v_pk_mul_f32 v[70:71], v[68:69], v[84:85] op_sel_hi:[1,0]
	v_pk_mul_f32 v[68:69], v[66:67], v[84:85] op_sel_hi:[1,0]
	v_mul_f32_e32 v66, 0xbfb8aa3b, v78
	v_mul_f32_e32 v67, 0xbfb8aa3b, v79
	v_exp_f32_e32 v66, v66
	v_exp_f32_e32 v67, v67
	v_pk_mul_f32 v[80:81], v[80:81], v[84:85] op_sel_hi:[1,0]
	v_pk_mul_f32 v[72:73], v[72:73], v[84:85] op_sel_hi:[1,0]
	v_add_f32_e32 v66, 1.0, v66
	v_add_f32_e32 v67, 1.0, v67
	v_rcp_f32_e32 v66, v66
	v_rcp_f32_e32 v67, v67
	v_pk_mul_f32 v[74:75], v[74:75], v[84:85] op_sel_hi:[1,0]
	v_pk_mul_f32 v[76:77], v[76:77], v[84:85] op_sel_hi:[1,0]
	v_mul_f32_e32 v66, v78, v66
	v_mul_f32_e32 v67, v79, v67
	v_mul_f32_e32 v66, v86, v66
	v_mul_f32_e32 v67, v87, v67
	v_cvt_pk_bf16_f32 v66, v66, v67
	v_mul_f32_e32 v67, 0xbfb8aa3b, v80
	v_exp_f32_e32 v67, v67
	s_nop 0
	v_add_f32_e32 v67, 1.0, v67
	v_rcp_f32_e32 v67, v67
	s_nop 0
	v_mul_f32_e32 v67, v80, v67
	v_mul_f32_e32 v67, v72, v67
	v_mul_f32_e32 v72, 0xbfb8aa3b, v81
	v_exp_f32_e32 v72, v72
	s_nop 0
	v_add_f32_e32 v72, 1.0, v72
	v_rcp_f32_e32 v72, v72
	s_nop 0
	v_mul_f32_e32 v72, v81, v72
	v_mul_f32_e32 v72, v73, v72
	v_cvt_pk_bf16_f32 v67, v67, v72
	v_mul_f32_e32 v72, 0xbfb8aa3b, v74
	v_exp_f32_e32 v72, v72
	s_nop 0
	v_add_f32_e32 v72, 1.0, v72
	v_rcp_f32_e32 v72, v72
	s_nop 0
	v_mul_f32_e32 v72, v74, v72
	v_mul_f32_e32 v68, v68, v72
	v_mul_f32_e32 v72, 0xbfb8aa3b, v75
	v_exp_f32_e32 v72, v72
	s_nop 0
	v_add_f32_e32 v72, 1.0, v72
	v_rcp_f32_e32 v72, v72
	s_nop 0
	v_mul_f32_e32 v72, v75, v72
	v_mul_f32_e32 v69, v69, v72
	v_cvt_pk_bf16_f32 v68, v68, v69
	v_mul_f32_e32 v69, 0xbfb8aa3b, v76
	v_exp_f32_e32 v69, v69
	s_nop 0
	v_add_f32_e32 v69, 1.0, v69
	v_rcp_f32_e32 v69, v69
	s_nop 0
; __device__ __forceinline__ unsigned cvt_pk_bf16(float lo, float hi) { unsigned r; asm volatile("v_cvt_pk_bf16_f32 %0, %1, %2" : "=v"(r) : "v"(lo), "v"(hi)); return r; }
; __device__ __forceinline__ float silu_mul(float g, float u) { const float e = __builtin_amdgcn_exp2f(-1.4426950408889634f * g); return g * __builtin_amdgcn_rcpf(1.0f + e) * u; }
; __device__ __forceinline__ float rs_of(const rsq_t* rsq, int row) { return __builtin_amdgcn_rsqf((float)rsq[row] * (1.0f / (1048576.0f * 2048.0f)) + 1e-6f); }
;     __device__ __forceinline__ void operator()(const f32x4 (&acc)[2][2][4][2], const Unit& u, int wr, int wc, int fr, int fq) const {
;     ...
;             for (int m = 0; m < 4; ++m) { const int row = row0 + ai * HALF + m * 16; bf16_t* rowp = O + (size_t)row * ldc + col0;
;                 const float rs = rs_of(rsq, row);
;                 const f32x4 g0 = acc[ai][0][m][0] * rs, g1 = acc[ai][0][m][1] * rs, u0 = acc[ai][1][m][0] * rs, u1 = acc[ai][1][m][1] * rs;
;                 u32x4 w;
;                 w.x = cvt_pk_bf16(silu_mul(g0[0], u0[0]), silu_mul(g0[1], u0[1])); w.y = cvt_pk_bf16(silu_mul(g0[2], u0[2]), silu_mul(g0[3], u0[3]));
;                 w.z = cvt_pk_bf16(silu_mul(g1[0], u1[0]), silu_mul(g1[1], u1[1])); w.w = cvt_pk_bf16(silu_mul(g1[2], u1[2]), silu_mul(g1[3], u1[3]));
;                 *(u32x4*)rowp = w; }
	v_mul_f32_e32 v69, v76, v69
	v_mul_f32_e32 v69, v70, v69
	v_mul_f32_e32 v70, 0xbfb8aa3b, v77
	v_exp_f32_e32 v70, v70
	s_nop 0
	v_add_f32_e32 v70, 1.0, v70
	v_rcp_f32_e32 v70, v70
	s_nop 0
	v_mul_f32_e32 v70, v77, v70
	v_mul_f32_e32 v70, v71, v70
	v_cvt_pk_bf16_f32 v69, v69, v70
	global_store_dwordx4 v[82:83], v[66:69], off
	s_nop 1
	v_mov_b32_e32 v68, v164
	v_mov_b32_e32 v69, v165
	v_ffbh_u32_e32 v70, v69
	v_min_u32_e32 v70, 32, v70
	v_lshlrev_b64 v[68:69], v70, v[68:69]
	v_min_u32_e32 v68, 1, v68
	v_or_b32_e32 v68, v69, v68
	v_cvt_f32_u32_e32 v68, v68
	v_sub_u32_e32 v69, 32, v70
	v_add_u32_e32 v66, 0x80, v140
	v_mad_i64_i32 v[66:67], s[2:3], v66, s1, v[142:143]
	v_ldexp_f32 v68, v68, v69
	v_fmamk_f32 v68, v68, 0x30000000, v198
	v_rsq_f32_e32 v68, v68
	v_lshl_add_u64 v[66:67], v[66:67], 0, v[144:145]
	v_pk_mul_f32 v[62:63], v[62:63], v[68:69] op_sel_hi:[1,0]
	v_pk_mul_f32 v[70:71], v[54:55], v[68:69] op_sel_hi:[1,0]
	v_pk_mul_f32 v[54:55], v[52:53], v[68:69] op_sel_hi:[1,0]
	v_pk_mul_f32 v[52:53], v[50:51], v[68:69] op_sel_hi:[1,0]
	v_mul_f32_e32 v50, 0xbfb8aa3b, v62
	v_mul_f32_e32 v51, 0xbfb8aa3b, v63
	v_exp_f32_e32 v50, v50
	v_exp_f32_e32 v51, v51
	v_pk_mul_f32 v[64:65], v[64:65], v[68:69] op_sel_hi:[1,0]
	v_pk_mul_f32 v[56:57], v[56:57], v[68:69] op_sel_hi:[1,0]
	v_add_f32_e32 v50, 1.0, v50
	v_add_f32_e32 v51, 1.0, v51
	v_rcp_f32_e32 v50, v50
	v_rcp_f32_e32 v51, v51
	v_pk_mul_f32 v[58:59], v[58:59], v[68:69] op_sel_hi:[1,0]
	v_pk_mul_f32 v[60:61], v[60:61], v[68:69] op_sel_hi:[1,0]
	v_mul_f32_e32 v50, v62, v50
	v_mul_f32_e32 v51, v63, v51
	v_mul_f32_e32 v50, v70, v50
	v_mul_f32_e32 v51, v71, v51
	v_cvt_pk_bf16_f32 v50, v50, v51
	v_mul_f32_e32 v51, 0xbfb8aa3b, v64
	v_exp_f32_e32 v51, v51
	s_nop 0
	v_add_f32_e32 v51, 1.0, v51
	v_rcp_f32_e32 v51, v51
	s_nop 0
	v_mul_f32_e32 v51, v64, v51
	v_mul_f32_e32 v51, v56, v51
	v_mul_f32_e32 v56, 0xbfb8aa3b, v65
	v_exp_f32_e32 v56, v56
	s_nop 0
	v_add_f32_e32 v56, 1.0, v56
	v_rcp_f32_e32 v56, v56
	s_nop 0
	v_mul_f32_e32 v56, v65, v56
	v_mul_f32_e32 v56, v57, v56
	v_cvt_pk_bf16_f32 v51, v51, v56
	v_mul_f32_e32 v56, 0xbfb8aa3b, v58
	v_exp_f32_e32 v56, v56
	s_nop 0
	v_add_f32_e32 v56, 1.0, v56
	v_rcp_f32_e32 v56, v56
	s_nop 0
	v_mul_f32_e32 v56, v58, v56
	v_mul_f32_e32 v52, v52, v56
	v_mul_f32_e32 v56, 0xbfb8aa3b, v59
	v_exp_f32_e32 v56, v56
	s_nop 0
	v_add_f32_e32 v56, 1.0, v56
	v_rcp_f32_e32 v56, v56
	s_nop 0
	v_mul_f32_e32 v56, v59, v56
	v_mul_f32_e32 v53, v53, v56
	v_cvt_pk_bf16_f32 v52, v52, v53
	v_mul_f32_e32 v53, 0xbfb8aa3b, v60
	v_exp_f32_e32 v53, v53
	s_nop 0
	v_add_f32_e32 v53, 1.0, v53
	v_rcp_f32_e32 v53, v53
	s_nop 0
	v_mul_f32_e32 v53, v60, v53
	v_mul_f32_e32 v53, v54, v53
	v_mul_f32_e32 v54, 0xbfb8aa3b, v61
	v_exp_f32_e32 v54, v54
	s_nop 0
	v_add_f32_e32 v54, 1.0, v54
	v_rcp_f32_e32 v54, v54
	s_nop 0
	v_mul_f32_e32 v54, v61, v54
	v_mul_f32_e32 v54, v55, v54
	v_cvt_pk_bf16_f32 v53, v53, v54
	global_store_dwordx4 v[66:67], v[50:53], off
	s_nop 1
	v_mov_b32_e32 v52, v166
	v_mov_b32_e32 v53, v167
	v_ffbh_u32_e32 v54, v53
	v_min_u32_e32 v54, 32, v54
	v_lshlrev_b64 v[52:53], v54, v[52:53]
	v_min_u32_e32 v52, 1, v52
	v_or_b32_e32 v52, v53, v52
	v_cvt_f32_u32_e32 v52, v52
	v_sub_u32_e32 v53, 32, v54
	v_add_u32_e32 v50, 0x90, v140
	v_mad_i64_i32 v[50:51], s[2:3], v50, s1, v[142:143]
	v_ldexp_f32 v52, v52, v53
	v_fmamk_f32 v52, v52, 0x30000000, v198
	v_rsq_f32_e32 v52, v52
	v_lshl_add_u64 v[50:51], v[50:51], 0, v[144:145]
	v_pk_mul_f32 v[46:47], v[46:47], v[52:53] op_sel_hi:[1,0]
	v_pk_mul_f32 v[54:55], v[38:39], v[52:53] op_sel_hi:[1,0]
	v_pk_mul_f32 v[38:39], v[36:37], v[52:53] op_sel_hi:[1,0]
	v_pk_mul_f32 v[36:37], v[34:35], v[52:53] op_sel_hi:[1,0]
	v_mul_f32_e32 v34, 0xbfb8aa3b, v46
	v_mul_f32_e32 v35, 0xbfb8aa3b, v47
	v_exp_f32_e32 v34, v34
	v_exp_f32_e32 v35, v35
	v_pk_mul_f32 v[48:49], v[48:49], v[52:53] op_sel_hi:[1,0]
	v_pk_mul_f32 v[40:41], v[40:41], v[52:53] op_sel_hi:[1,0]
	v_add_f32_e32 v34, 1.0, v34
	v_add_f32_e32 v35, 1.0, v35
	v_rcp_f32_e32 v34, v34
	v_rcp_f32_e32 v35, v35
	v_pk_mul_f32 v[42:43], v[42:43], v[52:53] op_sel_hi:[1,0]
	v_pk_mul_f32 v[44:45], v[44:45], v[52:53] op_sel_hi:[1,0]
	v_mul_f32_e32 v34, v46, v34
	v_mul_f32_e32 v35, v47, v35
	v_mul_f32_e32 v34, v54, v34
	v_mul_f32_e32 v35, v55, v35
	v_cvt_pk_bf16_f32 v34, v34, v35
	v_mul_f32_e32 v35, 0xbfb8aa3b, v48
	v_exp_f32_e32 v35, v35
	s_nop 0
	v_add_f32_e32 v35, 1.0, v35
	v_rcp_f32_e32 v35, v35
	s_nop 0
	v_mul_f32_e32 v35, v48, v35
	v_mul_f32_e32 v35, v40, v35
	v_mul_f32_e32 v40, 0xbfb8aa3b, v49
	v_exp_f32_e32 v40, v40
	s_nop 0
	v_add_f32_e32 v40, 1.0, v40
	v_rcp_f32_e32 v40, v40
	s_nop 0
	v_mul_f32_e32 v40, v49, v40
	v_mul_f32_e32 v40, v41, v40
	v_cvt_pk_bf16_f32 v35, v35, v40
	v_mul_f32_e32 v40, 0xbfb8aa3b, v42
	v_exp_f32_e32 v40, v40
	s_nop 0
	v_add_f32_e32 v40, 1.0, v40
	v_rcp_f32_e32 v40, v40
	s_nop 0
	v_mul_f32_e32 v40, v42, v40
	v_mul_f32_e32 v36, v36, v40
	v_mul_f32_e32 v40, 0xbfb8aa3b, v43
	v_exp_f32_e32 v40, v40
	s_nop 0
	v_add_f32_e32 v40, 1.0, v40
	v_rcp_f32_e32 v40, v40
	s_nop 0
	v_mul_f32_e32 v40, v43, v40
	v_mul_f32_e32 v37, v37, v40
	v_cvt_pk_bf16_f32 v36, v36, v37
	v_mul_f32_e32 v37, 0xbfb8aa3b, v44
	v_exp_f32_e32 v37, v37
	s_nop 0
	v_add_f32_e32 v37, 1.0, v37
	v_rcp_f32_e32 v37, v37
	s_nop 0
	v_mul_f32_e32 v37, v44, v37
	v_mul_f32_e32 v37, v38, v37
	v_mul_f32_e32 v38, 0xbfb8aa3b, v45
	v_exp_f32_e32 v38, v38
	s_nop 0
; __device__ __forceinline__ unsigned cvt_pk_bf16(float lo, float hi) { unsigned r; asm volatile("v_cvt_pk_bf16_f32 %0, %1, %2" : "=v"(r) : "v"(lo), "v"(hi)); return r; }
; __device__ __forceinline__ float rs_of(const rsq_t* rsq, int row) { return __builtin_amdgcn_rsqf((float)rsq[row] * (1.0f / (1048576.0f * 2048.0f)) + 1e-6f); }
; __device__ __forceinline__ float silu_mul(float g, float u) { const float e = __builtin_amdgcn_exp2f(-1.4426950408889634f * g); return g * __builtin_amdgcn_rcpf(1.0f + e) * u; }
; #define PG8_BAR __builtin_amdgcn_s_barrier()
;     __device__ __forceinline__ void operator()(const f32x4 (&acc)[2][2][4][2], const Unit& u, int wr, int wc, int fr, int fq) const {
;     ...
;             for (int m = 0; m < 4; ++m) { const int row = row0 + ai * HALF + m * 16; bf16_t* rowp = O + (size_t)row * ldc + col0;
;                 const float rs = rs_of(rsq, row);
;                 const f32x4 g0 = acc[ai][0][m][0] * rs, g1 = acc[ai][0][m][1] * rs, u0 = acc[ai][1][m][0] * rs, u1 = acc[ai][1][m][1] * rs;
;                 u32x4 w;
;                 w.x = cvt_pk_bf16(silu_mul(g0[0], u0[0]), silu_mul(g0[1], u0[1])); w.y = cvt_pk_bf16(silu_mul(g0[2], u0[2]), silu_mul(g0[3], u0[3]));
;                 w.z = cvt_pk_bf16(silu_mul(g1[0], u1[0]), silu_mul(g1[1], u1[1])); w.w = cvt_pk_bf16(silu_mul(g1[2], u1[2]), silu_mul(g1[3], u1[3]));
;                 *(u32x4*)rowp = w; }
; template <class Epi, class Sched, bool ALIGN_EPI = false, bool SP2 = false>
; __device__ __forceinline__ void gemm_phase(const int g_wave, PG8_LAS unsigned char* lds, const Gemm g, const Sched& S, const Epi& E) {
;     ...
;         if constexpr (ALIGN_EPI) { if (wr == 0) PG8_BAR; }
;         if constexpr (!Epi::AFTER_DRAIN) { E(acc, cur, wr, wc, fr, fq); S.done(cur); }
;         if (!has_next) break;
; #pragma unroll
;         for (int a = 0; a < 2; ++a)
; #pragma unroll
;             for (int b = 0; b < 2; ++b)
; #pragma unroll
;                 for (int m = 0; m < 4; ++m)
; #pragma unroll
;                     for (int n = 0; n < 2; ++n) acc[a][b][m][n] = (f32x4){0.f, 0.f, 0.f, 0.f};
;         cur = nxt; cA = nA; cB = nB; ++ui;
;         if constexpr (ALIGN_EPI) { if (wr == 1) PG8_BAR; }
	v_add_f32_e32 v38, 1.0, v38
	v_rcp_f32_e32 v38, v38
	s_nop 0
	v_mul_f32_e32 v38, v45, v38
	v_mul_f32_e32 v38, v39, v38
	v_cvt_pk_bf16_f32 v37, v37, v38
	global_store_dwordx4 v[50:51], v[34:37], off
	s_nop 1
	v_mov_b32_e32 v36, v168
	v_mov_b32_e32 v37, v169
	v_ffbh_u32_e32 v38, v37
	v_min_u32_e32 v38, 32, v38
	v_lshlrev_b64 v[36:37], v38, v[36:37]
	v_min_u32_e32 v36, 1, v36
	v_or_b32_e32 v36, v37, v36
	v_cvt_f32_u32_e32 v36, v36
	v_sub_u32_e32 v37, 32, v38
	v_add_u32_e32 v34, 0xa0, v140
	v_mad_i64_i32 v[34:35], s[2:3], v34, s1, v[142:143]
	v_ldexp_f32 v36, v36, v37
	v_fmamk_f32 v36, v36, 0x30000000, v198
	v_rsq_f32_e32 v36, v36
	v_lshl_add_u64 v[34:35], v[34:35], 0, v[144:145]
	v_pk_mul_f32 v[30:31], v[30:31], v[36:37] op_sel_hi:[1,0]
	v_pk_mul_f32 v[38:39], v[22:23], v[36:37] op_sel_hi:[1,0]
	v_pk_mul_f32 v[22:23], v[20:21], v[36:37] op_sel_hi:[1,0]
	v_pk_mul_f32 v[20:21], v[18:19], v[36:37] op_sel_hi:[1,0]
	v_mul_f32_e32 v18, 0xbfb8aa3b, v30
	v_mul_f32_e32 v19, 0xbfb8aa3b, v31
	v_exp_f32_e32 v18, v18
	v_exp_f32_e32 v19, v19
	v_pk_mul_f32 v[32:33], v[32:33], v[36:37] op_sel_hi:[1,0]
	v_pk_mul_f32 v[24:25], v[24:25], v[36:37] op_sel_hi:[1,0]
	v_add_f32_e32 v18, 1.0, v18
	v_add_f32_e32 v19, 1.0, v19
	v_rcp_f32_e32 v18, v18
	v_rcp_f32_e32 v19, v19
	v_pk_mul_f32 v[26:27], v[26:27], v[36:37] op_sel_hi:[1,0]
	v_pk_mul_f32 v[28:29], v[28:29], v[36:37] op_sel_hi:[1,0]
	v_mul_f32_e32 v18, v30, v18
	v_mul_f32_e32 v19, v31, v19
	v_mul_f32_e32 v18, v38, v18
	v_mul_f32_e32 v19, v39, v19
	v_cvt_pk_bf16_f32 v18, v18, v19
	v_mul_f32_e32 v19, 0xbfb8aa3b, v32
	v_exp_f32_e32 v19, v19
	s_nop 0
	v_add_f32_e32 v19, 1.0, v19
	v_rcp_f32_e32 v19, v19
	s_nop 0
	v_mul_f32_e32 v19, v32, v19
	v_mul_f32_e32 v19, v24, v19
	v_mul_f32_e32 v24, 0xbfb8aa3b, v33
	v_exp_f32_e32 v24, v24
	s_nop 0
	v_add_f32_e32 v24, 1.0, v24
	v_rcp_f32_e32 v24, v24
	s_nop 0
	v_mul_f32_e32 v24, v33, v24
	v_mul_f32_e32 v24, v25, v24
	v_cvt_pk_bf16_f32 v19, v19, v24
	v_mul_f32_e32 v24, 0xbfb8aa3b, v26
	v_exp_f32_e32 v24, v24
	s_nop 0
	v_add_f32_e32 v24, 1.0, v24
	v_rcp_f32_e32 v24, v24
	s_nop 0
	v_mul_f32_e32 v24, v26, v24
	v_mul_f32_e32 v20, v20, v24
	v_mul_f32_e32 v24, 0xbfb8aa3b, v27
	v_exp_f32_e32 v24, v24
	s_nop 0
	v_add_f32_e32 v24, 1.0, v24
	v_rcp_f32_e32 v24, v24
	s_nop 0
	v_mul_f32_e32 v24, v27, v24
	v_mul_f32_e32 v21, v21, v24
	v_cvt_pk_bf16_f32 v20, v20, v21
	v_mul_f32_e32 v21, 0xbfb8aa3b, v28
	v_exp_f32_e32 v21, v21
	s_nop 0
	v_add_f32_e32 v21, 1.0, v21
	v_rcp_f32_e32 v21, v21
	s_nop 0
	v_mul_f32_e32 v21, v28, v21
	v_mul_f32_e32 v21, v22, v21
	v_mul_f32_e32 v22, 0xbfb8aa3b, v29
	v_exp_f32_e32 v22, v22
	s_nop 0
	v_add_f32_e32 v22, 1.0, v22
	v_rcp_f32_e32 v22, v22
	s_nop 0
	v_mul_f32_e32 v22, v29, v22
	v_mul_f32_e32 v22, v23, v22
	v_cvt_pk_bf16_f32 v21, v21, v22
	global_store_dwordx4 v[34:35], v[18:21], off
	s_nop 1
	v_mov_b32_e32 v20, v170
	v_mov_b32_e32 v21, v171
	v_ffbh_u32_e32 v22, v21
	v_min_u32_e32 v22, 32, v22
	v_lshlrev_b64 v[20:21], v22, v[20:21]
	v_min_u32_e32 v20, 1, v20
	v_or_b32_e32 v20, v21, v20
	v_cvt_f32_u32_e32 v20, v20
	v_sub_u32_e32 v21, 32, v22
	v_add_u32_e32 v18, 0xb0, v140
	v_mad_i64_i32 v[18:19], s[2:3], v18, s1, v[142:143]
	v_ldexp_f32 v20, v20, v21
	v_fmamk_f32 v20, v20, 0x30000000, v198
	v_rsq_f32_e32 v20, v20
	v_lshl_add_u64 v[18:19], v[18:19], 0, v[144:145]
	s_mov_b64 s[2:3], -1
	v_pk_mul_f32 v[14:15], v[14:15], v[20:21] op_sel_hi:[1,0]
	v_pk_mul_f32 v[22:23], v[4:5], v[20:21] op_sel_hi:[1,0]
	v_pk_mul_f32 v[4:5], v[2:3], v[20:21] op_sel_hi:[1,0]
	v_mul_f32_e32 v2, 0xbfb8aa3b, v14
	v_mul_f32_e32 v3, 0xbfb8aa3b, v15
	v_exp_f32_e32 v2, v2
	v_exp_f32_e32 v3, v3
	v_pk_mul_f32 v[6:7], v[6:7], v[20:21] op_sel_hi:[1,0]
	v_pk_mul_f32 v[16:17], v[16:17], v[20:21] op_sel_hi:[1,0]
	v_add_f32_e32 v2, 1.0, v2
	v_add_f32_e32 v3, 1.0, v3
	v_rcp_f32_e32 v2, v2
	v_rcp_f32_e32 v3, v3
	v_pk_mul_f32 v[8:9], v[8:9], v[20:21] op_sel_hi:[1,0]
	v_pk_mul_f32 v[10:11], v[10:11], v[20:21] op_sel_hi:[1,0]
	v_mul_f32_e32 v2, v14, v2
	v_mul_f32_e32 v3, v15, v3
	v_mul_f32_e32 v2, v6, v2
	v_mul_f32_e32 v3, v7, v3
	v_cvt_pk_bf16_f32 v2, v2, v3
	v_mul_f32_e32 v3, 0xbfb8aa3b, v16
	v_mul_f32_e32 v6, 0xbfb8aa3b, v17
	v_exp_f32_e32 v3, v3
	v_exp_f32_e32 v6, v6
	v_pk_mul_f32 v[12:13], v[12:13], v[20:21] op_sel_hi:[1,0]
	v_add_f32_e32 v3, 1.0, v3
	v_add_f32_e32 v6, 1.0, v6
	v_rcp_f32_e32 v3, v3
	v_rcp_f32_e32 v6, v6
	v_mul_f32_e32 v3, v16, v3
	v_mul_f32_e32 v6, v17, v6
	v_mul_f32_e32 v3, v8, v3
	v_mul_f32_e32 v6, v9, v6
	v_cvt_pk_bf16_f32 v3, v3, v6
	v_mul_f32_e32 v6, 0xbfb8aa3b, v10
	v_exp_f32_e32 v6, v6
	s_nop 0
	v_add_f32_e32 v6, 1.0, v6
	v_rcp_f32_e32 v6, v6
	s_nop 0
	v_mul_f32_e32 v6, v10, v6
	v_mul_f32_e32 v4, v4, v6
	v_mul_f32_e32 v6, 0xbfb8aa3b, v11
	v_exp_f32_e32 v6, v6
	s_nop 0
	v_add_f32_e32 v6, 1.0, v6
	v_rcp_f32_e32 v6, v6
	s_nop 0
	v_mul_f32_e32 v6, v11, v6
	v_mul_f32_e32 v5, v5, v6
	v_cvt_pk_bf16_f32 v4, v4, v5
	v_mul_f32_e32 v5, 0xbfb8aa3b, v12
	v_exp_f32_e32 v5, v5
	v_mul_f32_e32 v6, 0xbfb8aa3b, v13
	v_exp_f32_e32 v6, v6
	v_add_f32_e32 v5, 1.0, v5
	v_rcp_f32_e32 v5, v5
	v_add_f32_e32 v6, 1.0, v6
	v_rcp_f32_e32 v6, v6
	v_mul_f32_e32 v5, v12, v5
	v_mul_f32_e32 v5, v22, v5
	v_mul_f32_e32 v6, v13, v6
	v_mul_f32_e32 v6, v23, v6
	v_cvt_pk_bf16_f32 v5, v5, v6
	global_store_dwordx4 v[18:19], v[2:5], off
	s_cbranch_vccnz .LBB0_1355
	s_andn2_b64 vcc, exec, s[8:9]
	s_cbranch_vccnz .LBB0_1354
	s_barrier
	s_branch .LBB0_1354
